# 4-phase GEMM loops: deferred counted vmcnt waits + ph4 staging between M3 and M4
# baseline (speedup 1.0000x reference)
; #define PG8_STAGE(bufoff, gbase, voff) do { _Pragma("unroll") for (int _i = 0; _i < 2; ++_i) \
;         __builtin_amdgcn_global_load_lds((const unsigned*)((const char*)(gbase) + (voff)[_i]), (LAS unsigned*)(lds + (bufoff) + ldsw + _i * 8192), 16, 0, 0); } while (0)
; #define PG8_LDA(dst, b, h) do { _Pragma("unroll") for (int m = 0; m < 4; ++m) _Pragma("unroll") for (int k = 0; k < 2; ++k) dst[m][k] = *(const LAS bf16x8*)(lds + PG8_SA(b, h) + aoff + m * 2048 + k * 1024); } while (0)
; #define PG8_LDB(dst, b, h) do { _Pragma("unroll") for (int n = 0; n < 2; ++n) _Pragma("unroll") for (int k = 0; k < 2; ++k) dst[n][k] = *(const LAS bf16x8*)(lds + PG8_SB(b, h) + boff + n * 2048 + k * 1024); } while (0)
; #define PG8_MMA(ai, bj, At, Bt) do { __builtin_amdgcn_s_setprio(1); _Pragma("unroll") for (int m = 0; m < 4; ++m) _Pragma("unroll") for (int n = 0; n < 2; ++n) _Pragma("unroll") for (int k = 0; k < 2; ++k) \
;         acc[ai][bj][m][n] = __builtin_amdgcn_mfma_f32_16x16x32_bf16(Bt[n][k], At[m][k], acc[ai][bj][m][n], 0, 0, 0); __builtin_amdgcn_s_setprio(0); } while (0)
; #define PG8_WAIT_V(n) asm volatile("s_waitcnt vmcnt(" #n ")" ::: "memory")
; #define PG8_WAIT_L(n) asm volatile("s_waitcnt lgkmcnt(" #n ")" ::: "memory")
; #define PG8_BAR __builtin_amdgcn_s_barrier()
; template <class Epi, class Sched>
; __device__ __forceinline__ void gemm_phase(LAS unsigned char* lds, const Gemm g, const Sched& S, const Epi& E) {
;     ...
;             const bool last = (t == nt - 2);
;             const char* a1 = cA + (size_t)(t + 1) * kstep;
;             const char* a2 = last ? nA : cA + (size_t)(t + 2) * kstep; const char* b2 = last ? nB : cB + (size_t)(t + 2) * kstep;
;             const char* a3 = a2 + kstep; const char* b3 = b2 + kstep;
;             PG8_LDB(B0, 0, 0); PG8_SCHED; PG8_LDA(At, 0, 0); PG8_STAGE(PG8_SA(1, 1), a1 + hstep, voffA);
;             PG8_WAIT_L(8); PG8_BAR; PG8_WAIT_L(0); PG8_MMA(0, 0, At, B0); PG8_BAR; PG8_SCHED;
;             PG8_LDB(B1, 0, 1); PG8_STAGE(PG8_SB(0, 0), b2, voffB);
;             PG8_BAR; PG8_WAIT_L(0); PG8_MMA(0, 1, At, B1); PG8_BAR;
;             PG8_LDA(At, 0, 1); PG8_STAGE(PG8_SA(0, 0), a2, voffA);
;             PG8_BAR; PG8_WAIT_L(0); PG8_MMA(1, 0, At, B0); PG8_BAR; PG8_SCHED;
;             PG8_STAGE(PG8_SB(0, 1), b2 + hstep, voffB);
;             PG8_WAIT_V(6); PG8_BAR; PG8_MMA(1, 1, At, B1); PG8_BAR;
.LBB0_44:
	s_add_u32 s50, s28, 0x100
	s_addc_u32 s51, s29, 0
	s_cmpk_eq_i32 s75, 0x7c
	s_cselect_b32 s55, s27, s51
	s_cselect_b32 s54, s71, s50
	s_cselect_b32 s53, s25, s74
	s_cselect_b32 s52, s72, s73
	v_lshl_add_u64 v[156:157], s[28:29], 0, v[150:151]
	s_add_i32 m0, s9, 0xc000
	s_nop 0
	global_load_lds_dwordx4 v[156:157], off
	v_lshl_add_u64 v[156:157], s[28:29], 0, v[148:149]
	s_add_i32 m0, s9, 0xe000
	s_nop 0
	global_load_lds_dwordx4 v[156:157], off
	s_add_i32 s38, 0, 0x10000
	v_add_u32_e32 v78, s38, v163
	ds_read_b128 v[66:69], v78
	ds_read_b128 v[70:73], v78 offset:1024
	ds_read_b128 v[74:77], v78 offset:2048
	ds_read_b128 v[78:81], v78 offset:3072
	ds_read_b128 v[152:155], v165
	ds_read_b128 v[166:169], v165 offset:1024
	ds_read_b128 v[170:173], v165 offset:2048
	ds_read_b128 v[174:177], v165 offset:3072
	ds_read_b128 v[178:181], v165 offset:4096
	ds_read_b128 v[182:185], v165 offset:5120
	ds_read_b128 v[186:189], v165 offset:6144
	ds_read_b128 v[190:193], v165 offset:7168
	s_add_i32 s39, 0, 0x14000
	v_add_u32_e32 v156, s39, v163
	ds_read_b128 v[194:197], v156
	ds_read_b128 v[198:201], v156 offset:1024
	ds_read_b128 v[202:205], v156 offset:2048
	ds_read_b128 v[210:213], v156 offset:3072
	s_waitcnt vmcnt(8)
	s_waitcnt lgkmcnt(4)
	s_barrier
	s_waitcnt lgkmcnt(0)
	s_setprio 1
	v_mfma_f32_16x16x32_bf16 v[142:145], v[66:69], v[152:155], v[142:145]
	v_mfma_f32_16x16x32_bf16 v[138:141], v[74:77], v[152:155], v[138:141]
	v_mfma_f32_16x16x32_bf16 v[126:129], v[66:69], v[170:173], v[126:129]
	v_mfma_f32_16x16x32_bf16 v[122:125], v[74:77], v[170:173], v[122:125]
	v_mfma_f32_16x16x32_bf16 v[110:113], v[66:69], v[178:181], v[110:113]
	v_mfma_f32_16x16x32_bf16 v[106:109], v[74:77], v[178:181], v[106:109]
	v_mfma_f32_16x16x32_bf16 v[102:105], v[66:69], v[186:189], v[102:105]
	v_mfma_f32_16x16x32_bf16 v[98:101], v[74:77], v[186:189], v[98:101]
	v_mfma_f32_16x16x32_bf16 v[142:145], v[70:73], v[166:169], v[142:145]
	v_mfma_f32_16x16x32_bf16 v[138:141], v[78:81], v[166:169], v[138:141]
	v_mfma_f32_16x16x32_bf16 v[126:129], v[70:73], v[174:177], v[126:129]
	v_mfma_f32_16x16x32_bf16 v[122:125], v[78:81], v[174:177], v[122:125]
	v_mfma_f32_16x16x32_bf16 v[110:113], v[70:73], v[182:185], v[110:113]
	v_mfma_f32_16x16x32_bf16 v[106:109], v[78:81], v[182:185], v[106:109]
	v_mfma_f32_16x16x32_bf16 v[102:105], v[70:73], v[190:193], v[102:105]
	v_mfma_f32_16x16x32_bf16 v[98:101], v[78:81], v[190:193], v[98:101]
	v_mfma_f32_16x16x32_bf16 v[134:137], v[194:197], v[152:155], v[134:137]
	v_mfma_f32_16x16x32_bf16 v[130:133], v[202:205], v[152:155], v[130:133]
	v_mfma_f32_16x16x32_bf16 v[118:121], v[194:197], v[170:173], v[118:121]
	v_mfma_f32_16x16x32_bf16 v[114:117], v[202:205], v[170:173], v[114:117]
	v_mfma_f32_16x16x32_bf16 v[94:97], v[194:197], v[178:181], v[94:97]
	v_mfma_f32_16x16x32_bf16 v[90:93], v[202:205], v[178:181], v[90:93]
	v_mfma_f32_16x16x32_bf16 v[86:89], v[194:197], v[186:189], v[86:89]
	v_mfma_f32_16x16x32_bf16 v[82:85], v[202:205], v[186:189], v[82:85]
	v_mfma_f32_16x16x32_bf16 v[134:137], v[198:201], v[166:169], v[134:137]
	v_mfma_f32_16x16x32_bf16 v[130:133], v[210:213], v[166:169], v[130:133]
	v_mfma_f32_16x16x32_bf16 v[118:121], v[198:201], v[174:177], v[118:121]
	v_mfma_f32_16x16x32_bf16 v[114:117], v[210:213], v[174:177], v[114:117]
	v_mfma_f32_16x16x32_bf16 v[94:97], v[198:201], v[182:185], v[94:97]
	v_mfma_f32_16x16x32_bf16 v[90:93], v[210:213], v[182:185], v[90:93]
	v_mfma_f32_16x16x32_bf16 v[86:89], v[198:201], v[190:193], v[86:89]
	v_mfma_f32_16x16x32_bf16 v[82:85], v[210:213], v[190:193], v[82:85]
	s_setprio 0
	s_barrier
	s_add_i32 s28, s38, s60
	v_lshl_add_u64 v[156:157], s[52:53], 0, v[0:1]
	s_mov_b32 m0, s28
	v_lshl_add_u64 v[160:161], s[52:53], 0, v[146:147]
	global_load_lds_dwordx4 v[156:157], off
	s_add_i32 m0, s28, 0x2000
	s_nop 0
	global_load_lds_dwordx4 v[160:161], off
	s_mov_b32 m0, s9
	v_lshl_add_u64 v[206:207], s[54:55], 0, v[0:1]
	global_load_lds_dwordx4 v[206:207], off
	v_lshl_add_u64 v[214:215], s[54:55], 0, v[146:147]
	s_mov_b32 m0, s61
	s_nop 0
	global_load_lds_dwordx4 v[214:215], off
	ds_read_b128 v[152:155], v165 offset:16384
	ds_read_b128 v[166:169], v165 offset:17408
	ds_read_b128 v[170:173], v165 offset:18432
	ds_read_b128 v[174:177], v165 offset:19456
	ds_read_b128 v[178:181], v165 offset:20480
	ds_read_b128 v[182:185], v165 offset:21504
	ds_read_b128 v[186:189], v165 offset:22528
	ds_read_b128 v[190:193], v165 offset:23552
	s_waitcnt vmcnt(6)
	s_waitcnt lgkmcnt(0)
	s_barrier
; #define PG8_STAGE(bufoff, gbase, voff) do { _Pragma("unroll") for (int _i = 0; _i < 2; ++_i) \
;         __builtin_amdgcn_global_load_lds((const unsigned*)((const char*)(gbase) + (voff)[_i]), (LAS unsigned*)(lds + (bufoff) + ldsw + _i * 8192), 16, 0, 0); } while (0)
; #define PG8_LDA(dst, b, h) do { _Pragma("unroll") for (int m = 0; m < 4; ++m) _Pragma("unroll") for (int k = 0; k < 2; ++k) dst[m][k] = *(const LAS bf16x8*)(lds + PG8_SA(b, h) + aoff + m * 2048 + k * 1024); } while (0)
; #define PG8_LDB(dst, b, h) do { _Pragma("unroll") for (int n = 0; n < 2; ++n) _Pragma("unroll") for (int k = 0; k < 2; ++k) dst[n][k] = *(const LAS bf16x8*)(lds + PG8_SB(b, h) + boff + n * 2048 + k * 1024); } while (0)
; #define PG8_MMA(ai, bj, At, Bt) do { __builtin_amdgcn_s_setprio(1); _Pragma("unroll") for (int m = 0; m < 4; ++m) _Pragma("unroll") for (int n = 0; n < 2; ++n) _Pragma("unroll") for (int k = 0; k < 2; ++k) \
;         acc[ai][bj][m][n] = __builtin_amdgcn_mfma_f32_16x16x32_bf16(Bt[n][k], At[m][k], acc[ai][bj][m][n], 0, 0, 0); __builtin_amdgcn_s_setprio(0); } while (0)
; #define PG8_WAIT_V(n) asm volatile("s_waitcnt vmcnt(" #n ")" ::: "memory")
; #define PG8_WAIT_L(n) asm volatile("s_waitcnt lgkmcnt(" #n ")" ::: "memory")
; #define PG8_BAR __builtin_amdgcn_s_barrier()
; #define PG8_SCHED __builtin_amdgcn_sched_barrier(0)
; template <class Epi, class Sched>
; __device__ __forceinline__ void gemm_phase(LAS unsigned char* lds, const Gemm g, const Sched& S, const Epi& E) {
;     ...
;             PG8_BAR; PG8_WAIT_L(0); PG8_MMA(1, 0, At, B0); PG8_BAR; PG8_SCHED;
;             PG8_STAGE(PG8_SB(0, 1), b2 + hstep, voffB);
;             PG8_WAIT_V(6); PG8_BAR; PG8_MMA(1, 1, At, B1); PG8_BAR;
;             PG8_LDB(B0, 1, 0); PG8_SCHED; PG8_LDA(At, 1, 0); PG8_STAGE(PG8_SA(0, 1), a2 + hstep, voffA);
;             PG8_WAIT_L(8); PG8_BAR; PG8_WAIT_L(0); PG8_MMA(0, 0, At, B0); PG8_BAR; PG8_SCHED;
;             PG8_LDB(B1, 1, 1); PG8_STAGE(PG8_SB(1, 0), b3, voffB);
;             PG8_BAR; PG8_WAIT_L(0); PG8_MMA(0, 1, At, B1); PG8_BAR;
	s_setprio 1
	v_mfma_f32_16x16x32_bf16 v[62:65], v[66:69], v[152:155], v[62:65]
	v_mfma_f32_16x16x32_bf16 v[58:61], v[74:77], v[152:155], v[58:61]
	v_mfma_f32_16x16x32_bf16 v[46:49], v[66:69], v[170:173], v[46:49]
	v_mfma_f32_16x16x32_bf16 v[42:45], v[74:77], v[170:173], v[42:45]
	v_mfma_f32_16x16x32_bf16 v[30:33], v[66:69], v[178:181], v[30:33]
	v_mfma_f32_16x16x32_bf16 v[26:29], v[74:77], v[178:181], v[26:29]
	v_mfma_f32_16x16x32_bf16 v[22:25], v[66:69], v[186:189], v[22:25]
	v_mfma_f32_16x16x32_bf16 v[14:17], v[74:77], v[186:189], v[14:17]
	v_mfma_f32_16x16x32_bf16 v[62:65], v[70:73], v[166:169], v[62:65]
	v_mfma_f32_16x16x32_bf16 v[58:61], v[78:81], v[166:169], v[58:61]
	v_mfma_f32_16x16x32_bf16 v[46:49], v[70:73], v[174:177], v[46:49]
	v_mfma_f32_16x16x32_bf16 v[42:45], v[78:81], v[174:177], v[42:45]
	v_mfma_f32_16x16x32_bf16 v[30:33], v[70:73], v[182:185], v[30:33]
	v_mfma_f32_16x16x32_bf16 v[26:29], v[78:81], v[182:185], v[26:29]
	v_mfma_f32_16x16x32_bf16 v[22:25], v[70:73], v[190:193], v[22:25]
	v_mfma_f32_16x16x32_bf16 v[14:17], v[78:81], v[190:193], v[14:17]
	s_add_u32 s28, s52, 0x200000
	s_addc_u32 s29, s53, 0
	s_add_i32 s38, s39, s60
	v_lshl_add_u64 v[66:67], s[28:29], 0, v[0:1]
	s_mov_b32 m0, s38
	s_nop 0
	global_load_lds_dwordx4 v[66:67], off
	v_lshl_add_u64 v[66:67], s[28:29], 0, v[146:147]
	s_add_i32 m0, s38, 0x2000
	s_nop 0
	global_load_lds_dwordx4 v[66:67], off
	v_mfma_f32_16x16x32_bf16 v[54:57], v[194:197], v[152:155], v[54:57]
	v_mfma_f32_16x16x32_bf16 v[50:53], v[202:205], v[152:155], v[50:53]
	v_mfma_f32_16x16x32_bf16 v[38:41], v[194:197], v[170:173], v[38:41]
	v_mfma_f32_16x16x32_bf16 v[34:37], v[202:205], v[170:173], v[34:37]
	v_mfma_f32_16x16x32_bf16 v[18:21], v[194:197], v[178:181], v[18:21]
	v_mfma_f32_16x16x32_bf16 v[10:13], v[202:205], v[178:181], v[10:13]
	v_mfma_f32_16x16x32_bf16 v[6:9], v[194:197], v[186:189], v[6:9]
	v_mfma_f32_16x16x32_bf16 v[2:5], v[202:205], v[186:189], v[2:5]
	v_mfma_f32_16x16x32_bf16 v[54:57], v[198:201], v[166:169], v[54:57]
	v_mfma_f32_16x16x32_bf16 v[50:53], v[210:213], v[166:169], v[50:53]
	v_mfma_f32_16x16x32_bf16 v[38:41], v[198:201], v[174:177], v[38:41]
	v_mfma_f32_16x16x32_bf16 v[34:37], v[210:213], v[174:177], v[34:37]
	v_mfma_f32_16x16x32_bf16 v[18:21], v[198:201], v[182:185], v[18:21]
	v_mfma_f32_16x16x32_bf16 v[10:13], v[210:213], v[182:185], v[10:13]
	v_mfma_f32_16x16x32_bf16 v[6:9], v[198:201], v[190:193], v[6:9]
	v_mfma_f32_16x16x32_bf16 v[2:5], v[210:213], v[190:193], v[2:5]
	s_setprio 0
	s_barrier
	s_add_u32 s28, s54, 0x200000
	s_addc_u32 s29, s55, 0
	s_mov_b32 m0, s62
	v_lshl_add_u64 v[194:195], s[28:29], 0, v[0:1]
	global_load_lds_dwordx4 v[194:195], off
	v_lshl_add_u64 v[194:195], s[28:29], 0, v[146:147]
	s_mov_b32 m0, s63
	s_nop 0
	global_load_lds_dwordx4 v[194:195], off
	s_add_i32 s38, 0, 0x18000
	v_add_u32_e32 v78, s38, v163
	ds_read_b128 v[66:69], v78
	ds_read_b128 v[70:73], v78 offset:1024
	ds_read_b128 v[74:77], v78 offset:2048
	ds_read_b128 v[78:81], v78 offset:3072
	ds_read_b128 v[152:155], v165 offset:32768
	ds_read_b128 v[166:169], v165 offset:33792
	ds_read_b128 v[170:173], v165 offset:34816
	ds_read_b128 v[174:177], v165 offset:35840
	ds_read_b128 v[178:181], v165 offset:36864
	ds_read_b128 v[182:185], v165 offset:37888
	ds_read_b128 v[186:189], v165 offset:38912
	ds_read_b128 v[190:193], v165 offset:39936
	s_add_i32 s39, 0, 0x1c000
	v_add_u32_e32 v210, s39, v163
	ds_read_b128 v[194:197], v210
	ds_read_b128 v[198:201], v210 offset:1024
	ds_read_b128 v[202:205], v210 offset:2048
	ds_read_b128 v[210:213], v210 offset:3072
	s_waitcnt vmcnt(8)
	s_waitcnt lgkmcnt(4)
	s_barrier
	s_waitcnt lgkmcnt(0)
	s_setprio 1
	v_mfma_f32_16x16x32_bf16 v[142:145], v[66:69], v[152:155], v[142:145]
	v_mfma_f32_16x16x32_bf16 v[138:141], v[74:77], v[152:155], v[138:141]
	v_mfma_f32_16x16x32_bf16 v[126:129], v[66:69], v[170:173], v[126:129]
	v_mfma_f32_16x16x32_bf16 v[122:125], v[74:77], v[170:173], v[122:125]
	v_mfma_f32_16x16x32_bf16 v[110:113], v[66:69], v[178:181], v[110:113]
	v_mfma_f32_16x16x32_bf16 v[106:109], v[74:77], v[178:181], v[106:109]
	v_mfma_f32_16x16x32_bf16 v[102:105], v[66:69], v[186:189], v[102:105]
	v_mfma_f32_16x16x32_bf16 v[98:101], v[74:77], v[186:189], v[98:101]
	v_mfma_f32_16x16x32_bf16 v[142:145], v[70:73], v[166:169], v[142:145]
	v_mfma_f32_16x16x32_bf16 v[138:141], v[78:81], v[166:169], v[138:141]
	v_mfma_f32_16x16x32_bf16 v[126:129], v[70:73], v[174:177], v[126:129]
	v_mfma_f32_16x16x32_bf16 v[122:125], v[78:81], v[174:177], v[122:125]
	v_mfma_f32_16x16x32_bf16 v[110:113], v[70:73], v[182:185], v[110:113]
	v_mfma_f32_16x16x32_bf16 v[106:109], v[78:81], v[182:185], v[106:109]
	v_mfma_f32_16x16x32_bf16 v[102:105], v[70:73], v[190:193], v[102:105]
	v_mfma_f32_16x16x32_bf16 v[98:101], v[78:81], v[190:193], v[98:101]
	v_mfma_f32_16x16x32_bf16 v[134:137], v[194:197], v[152:155], v[134:137]
	v_mfma_f32_16x16x32_bf16 v[130:133], v[202:205], v[152:155], v[130:133]
	v_mfma_f32_16x16x32_bf16 v[118:121], v[194:197], v[170:173], v[118:121]
	v_mfma_f32_16x16x32_bf16 v[114:117], v[202:205], v[170:173], v[114:117]
	v_mfma_f32_16x16x32_bf16 v[94:97], v[194:197], v[178:181], v[94:97]
	v_mfma_f32_16x16x32_bf16 v[90:93], v[202:205], v[178:181], v[90:93]
	v_mfma_f32_16x16x32_bf16 v[86:89], v[194:197], v[186:189], v[86:89]
	v_mfma_f32_16x16x32_bf16 v[82:85], v[202:205], v[186:189], v[82:85]
	v_mfma_f32_16x16x32_bf16 v[134:137], v[198:201], v[166:169], v[134:137]
	v_mfma_f32_16x16x32_bf16 v[130:133], v[210:213], v[166:169], v[130:133]
	v_mfma_f32_16x16x32_bf16 v[118:121], v[198:201], v[174:177], v[118:121]
	v_mfma_f32_16x16x32_bf16 v[114:117], v[210:213], v[174:177], v[114:117]
	v_mfma_f32_16x16x32_bf16 v[94:97], v[198:201], v[182:185], v[94:97]
	v_mfma_f32_16x16x32_bf16 v[90:93], v[210:213], v[182:185], v[90:93]
	v_mfma_f32_16x16x32_bf16 v[86:89], v[198:201], v[190:193], v[86:89]
	v_mfma_f32_16x16x32_bf16 v[82:85], v[210:213], v[190:193], v[82:85]
	s_setprio 0
	s_barrier
; #define PG8_STAGE(bufoff, gbase, voff) do { _Pragma("unroll") for (int _i = 0; _i < 2; ++_i) \
;         __builtin_amdgcn_global_load_lds((const unsigned*)((const char*)(gbase) + (voff)[_i]), (LAS unsigned*)(lds + (bufoff) + ldsw + _i * 8192), 16, 0, 0); } while (0)
; #define PG8_LDA(dst, b, h) do { _Pragma("unroll") for (int m = 0; m < 4; ++m) _Pragma("unroll") for (int k = 0; k < 2; ++k) dst[m][k] = *(const LAS bf16x8*)(lds + PG8_SA(b, h) + aoff + m * 2048 + k * 1024); } while (0)
; #define PG8_MMA(ai, bj, At, Bt) do { __builtin_amdgcn_s_setprio(1); _Pragma("unroll") for (int m = 0; m < 4; ++m) _Pragma("unroll") for (int n = 0; n < 2; ++n) _Pragma("unroll") for (int k = 0; k < 2; ++k) \
;         acc[ai][bj][m][n] = __builtin_amdgcn_mfma_f32_16x16x32_bf16(Bt[n][k], At[m][k], acc[ai][bj][m][n], 0, 0, 0); __builtin_amdgcn_s_setprio(0); } while (0)
; #define PG8_WAIT_V(n) asm volatile("s_waitcnt vmcnt(" #n ")" ::: "memory")
; #define PG8_WAIT_L(n) asm volatile("s_waitcnt lgkmcnt(" #n ")" ::: "memory")
; #define PG8_BAR __builtin_amdgcn_s_barrier()
; #define PG8_SCHED __builtin_amdgcn_sched_barrier(0)
; template <class Epi, class Sched>
; __device__ __forceinline__ void gemm_phase(LAS unsigned char* lds, const Gemm g, const Sched& S, const Epi& E) {
;     ...
;             PG8_LDA(At, 1, 1); PG8_STAGE(PG8_SA(1, 0), a3, voffA);
;             PG8_BAR; PG8_WAIT_L(0); PG8_MMA(1, 0, At, B0); PG8_BAR; PG8_SCHED;
;             PG8_STAGE(PG8_SB(1, 1), b3 + hstep, voffB);
;             PG8_WAIT_V(6); PG8_BAR; PG8_MMA(1, 1, At, B1); PG8_BAR;
;         }
;         E(acc, cur, wr, wc, fr, fq);
;         if (!has_next) break;
	s_add_i32 s28, s38, s60
	v_lshl_add_u64 v[156:157], v[156:157], 0, s[36:37]
	s_mov_b32 m0, s28
	s_nop 0
	global_load_lds_dwordx4 v[156:157], off
	v_lshl_add_u64 v[156:157], v[160:161], 0, s[36:37]
	s_add_i32 m0, s28, 0x2000
	s_nop 0
	global_load_lds_dwordx4 v[156:157], off
	s_mov_b32 m0, s66
	v_lshl_add_u64 v[156:157], v[206:207], 0, s[36:37]
	global_load_lds_dwordx4 v[156:157], off
	v_lshl_add_u64 v[156:157], v[214:215], 0, s[36:37]
	s_mov_b32 m0, s67
	s_nop 0
	global_load_lds_dwordx4 v[156:157], off
	ds_read_b128 v[152:155], v165 offset:49152
	ds_read_b128 v[166:169], v165 offset:50176
	ds_read_b128 v[170:173], v165 offset:51200
	ds_read_b128 v[174:177], v165 offset:52224
	ds_read_b128 v[178:181], v165 offset:53248
	ds_read_b128 v[182:185], v165 offset:54272
	ds_read_b128 v[186:189], v165 offset:55296
	ds_read_b128 v[190:193], v165 offset:56320
	s_waitcnt vmcnt(6)
	s_waitcnt lgkmcnt(0)
	s_barrier
	s_setprio 1
	v_mfma_f32_16x16x32_bf16 v[62:65], v[66:69], v[152:155], v[62:65]
	v_mfma_f32_16x16x32_bf16 v[58:61], v[74:77], v[152:155], v[58:61]
	v_mfma_f32_16x16x32_bf16 v[46:49], v[66:69], v[170:173], v[46:49]
	v_mfma_f32_16x16x32_bf16 v[42:45], v[74:77], v[170:173], v[42:45]
	v_mfma_f32_16x16x32_bf16 v[30:33], v[66:69], v[178:181], v[30:33]
	v_mfma_f32_16x16x32_bf16 v[26:29], v[74:77], v[178:181], v[26:29]
	v_mfma_f32_16x16x32_bf16 v[22:25], v[66:69], v[186:189], v[22:25]
	v_mfma_f32_16x16x32_bf16 v[14:17], v[74:77], v[186:189], v[14:17]
	v_mfma_f32_16x16x32_bf16 v[62:65], v[70:73], v[166:169], v[62:65]
	v_mfma_f32_16x16x32_bf16 v[58:61], v[78:81], v[166:169], v[58:61]
	v_mfma_f32_16x16x32_bf16 v[46:49], v[70:73], v[174:177], v[46:49]
	v_mfma_f32_16x16x32_bf16 v[42:45], v[78:81], v[174:177], v[42:45]
	v_mfma_f32_16x16x32_bf16 v[30:33], v[70:73], v[182:185], v[30:33]
	v_mfma_f32_16x16x32_bf16 v[26:29], v[78:81], v[182:185], v[26:29]
	v_mfma_f32_16x16x32_bf16 v[22:25], v[70:73], v[190:193], v[22:25]
	v_mfma_f32_16x16x32_bf16 v[14:17], v[78:81], v[190:193], v[14:17]
	s_add_u32 s28, s52, 0x200080
	s_addc_u32 s29, s53, 0
	s_add_i32 s38, s39, s60
	v_lshl_add_u64 v[66:67], s[28:29], 0, v[0:1]
	s_mov_b32 m0, s38
	s_nop 0
	global_load_lds_dwordx4 v[66:67], off
	v_lshl_add_u64 v[66:67], s[28:29], 0, v[146:147]
	s_add_i32 m0, s38, 0x2000
	s_nop 0
	global_load_lds_dwordx4 v[66:67], off
	v_mfma_f32_16x16x32_bf16 v[54:57], v[194:197], v[152:155], v[54:57]
	v_mfma_f32_16x16x32_bf16 v[50:53], v[202:205], v[152:155], v[50:53]
	v_mfma_f32_16x16x32_bf16 v[38:41], v[194:197], v[170:173], v[38:41]
	v_mfma_f32_16x16x32_bf16 v[34:37], v[202:205], v[170:173], v[34:37]
	v_mfma_f32_16x16x32_bf16 v[18:21], v[194:197], v[178:181], v[18:21]
	v_mfma_f32_16x16x32_bf16 v[10:13], v[202:205], v[178:181], v[10:13]
	v_mfma_f32_16x16x32_bf16 v[6:9], v[194:197], v[186:189], v[6:9]
	v_mfma_f32_16x16x32_bf16 v[2:5], v[202:205], v[186:189], v[2:5]
	v_mfma_f32_16x16x32_bf16 v[54:57], v[198:201], v[166:169], v[54:57]
	v_mfma_f32_16x16x32_bf16 v[50:53], v[210:213], v[166:169], v[50:53]
	v_mfma_f32_16x16x32_bf16 v[38:41], v[198:201], v[174:177], v[38:41]
	v_mfma_f32_16x16x32_bf16 v[34:37], v[210:213], v[174:177], v[34:37]
	v_mfma_f32_16x16x32_bf16 v[18:21], v[198:201], v[182:185], v[18:21]
	v_mfma_f32_16x16x32_bf16 v[10:13], v[210:213], v[182:185], v[10:13]
	v_mfma_f32_16x16x32_bf16 v[6:9], v[198:201], v[190:193], v[6:9]
	v_mfma_f32_16x16x32_bf16 v[2:5], v[210:213], v[190:193], v[2:5]
	s_setprio 0
	s_add_i32 s75, s75, 2
	s_add_u32 s73, s73, 0x100
	s_addc_u32 s74, s74, 0
	s_cmpk_gt_u32 s75, 0x7d
	s_mov_b64 s[28:29], s[50:51]
	s_barrier
	s_cbranch_scc0 .LBB0_44
	s_cmp_lt_i32 s8, 64
	s_cselect_b64 s[50:51], -1, 0
	s_cmp_gt_i32 s8, 63
	s_cbranch_scc0 .LBB0_35
	s_mov_b64 s[52:53], 0x18000
	s_mov_b64 s[28:29], s[46:47]
	s_branch .LBB0_36

; #define PG8_STAGE(bufoff, gbase, voff) do { _Pragma("unroll") for (int _i = 0; _i < 2; ++_i) \
;         __builtin_amdgcn_global_load_lds((const unsigned*)((const char*)(gbase) + (voff)[_i]), (LAS unsigned*)(lds + (bufoff) + ldsw + _i * 8192), 16, 0, 0); } while (0)
; #define PG8_LDA(dst, b, h) do { _Pragma("unroll") for (int m = 0; m < 4; ++m) _Pragma("unroll") for (int k = 0; k < 2; ++k) dst[m][k] = *(const LAS bf16x8*)(lds + PG8_SA(b, h) + aoff + m * 2048 + k * 1024); } while (0)
; #define PG8_LDB(dst, b, h) do { _Pragma("unroll") for (int n = 0; n < 2; ++n) _Pragma("unroll") for (int k = 0; k < 2; ++k) dst[n][k] = *(const LAS bf16x8*)(lds + PG8_SB(b, h) + boff + n * 2048 + k * 1024); } while (0)
; #define PG8_MMA(ai, bj, At, Bt) do { __builtin_amdgcn_s_setprio(1); _Pragma("unroll") for (int m = 0; m < 4; ++m) _Pragma("unroll") for (int n = 0; n < 2; ++n) _Pragma("unroll") for (int k = 0; k < 2; ++k) \
;         acc[ai][bj][m][n] = __builtin_amdgcn_mfma_f32_16x16x32_bf16(Bt[n][k], At[m][k], acc[ai][bj][m][n], 0, 0, 0); __builtin_amdgcn_s_setprio(0); } while (0)
; #define PG8_WAIT_V(n) asm volatile("s_waitcnt vmcnt(" #n ")" ::: "memory")
; #define PG8_WAIT_L(n) asm volatile("s_waitcnt lgkmcnt(" #n ")" ::: "memory")
; #define PG8_BAR __builtin_amdgcn_s_barrier()
; template <class Epi, class Sched>
; __device__ __forceinline__ void gemm_phase(LAS unsigned char* lds, const Gemm g, const Sched& S, const Epi& E) {
;     ...
;             const bool last = (t == nt - 2);
;             const char* a1 = cA + (size_t)(t + 1) * kstep;
;             const char* a2 = last ? nA : cA + (size_t)(t + 2) * kstep; const char* b2 = last ? nB : cB + (size_t)(t + 2) * kstep;
;             const char* a3 = a2 + kstep; const char* b3 = b2 + kstep;
;             PG8_LDB(B0, 0, 0); PG8_SCHED; PG8_LDA(At, 0, 0); PG8_STAGE(PG8_SA(1, 1), a1 + hstep, voffA);
;             PG8_WAIT_L(8); PG8_BAR; PG8_WAIT_L(0); PG8_MMA(0, 0, At, B0); PG8_BAR; PG8_SCHED;
;             PG8_LDB(B1, 0, 1); PG8_STAGE(PG8_SB(0, 0), b2, voffB);
;             PG8_BAR; PG8_WAIT_L(0); PG8_MMA(0, 1, At, B1); PG8_BAR;
;             PG8_LDA(At, 0, 1); PG8_STAGE(PG8_SA(0, 0), a2, voffA);
;             PG8_BAR; PG8_WAIT_L(0); PG8_MMA(1, 0, At, B0); PG8_BAR; PG8_SCHED;
;             PG8_STAGE(PG8_SB(0, 1), b2 + hstep, voffB);
;             PG8_WAIT_V(6); PG8_BAR; PG8_MMA(1, 1, At, B1); PG8_BAR;
.LBB0_58:
	s_add_u32 s52, s50, 0x100
	s_addc_u32 s53, s51, 0
	s_cmp_eq_u32 s71, 28
	s_cselect_b32 s57, s11, s53
	s_cselect_b32 s56, s29, s52
	s_cselect_b32 s55, s41, s70
	s_cselect_b32 s54, s43, s69
	v_lshl_add_u64 v[156:157], s[50:51], 0, v[134:135]
	s_add_i32 m0, s25, 0xc000
	s_nop 0
	global_load_lds_dwordx4 v[156:157], off
	v_lshl_add_u64 v[156:157], s[50:51], 0, v[132:133]
	s_add_i32 m0, s25, 0xe000
	s_nop 0
	global_load_lds_dwordx4 v[156:157], off
	s_add_i32 s38, 0, 0x10000
	v_add_u32_e32 v152, s38, v137
	ds_read_b128 v[140:143], v152
	ds_read_b128 v[144:147], v152 offset:1024
	ds_read_b128 v[148:151], v152 offset:2048
	ds_read_b128 v[152:155], v152 offset:3072
	ds_read_b128 v[160:163], v139
	ds_read_b128 v[164:167], v139 offset:1024
	ds_read_b128 v[168:171], v139 offset:2048
	ds_read_b128 v[172:175], v139 offset:3072
	ds_read_b128 v[176:179], v139 offset:4096
	ds_read_b128 v[180:183], v139 offset:5120
	ds_read_b128 v[184:187], v139 offset:6144
	ds_read_b128 v[188:191], v139 offset:7168
	s_add_i32 s50, 0, 0x14000
	v_add_u32_e32 v156, s50, v137
	ds_read_b128 v[192:195], v156
	ds_read_b128 v[196:199], v156 offset:1024
	ds_read_b128 v[200:203], v156 offset:2048
	ds_read_b128 v[204:207], v156 offset:3072
	s_waitcnt vmcnt(8)
	s_waitcnt lgkmcnt(4)
	s_barrier
	s_waitcnt lgkmcnt(0)
	s_setprio 1
	v_mfma_f32_16x16x32_bf16 v[126:129], v[140:143], v[160:163], v[126:129]
	v_mfma_f32_16x16x32_bf16 v[122:125], v[148:151], v[160:163], v[122:125]
	v_mfma_f32_16x16x32_bf16 v[118:121], v[140:143], v[168:171], v[118:121]
	v_mfma_f32_16x16x32_bf16 v[114:117], v[148:151], v[168:171], v[114:117]
	v_mfma_f32_16x16x32_bf16 v[106:109], v[140:143], v[176:179], v[106:109]
	v_mfma_f32_16x16x32_bf16 v[98:101], v[148:151], v[176:179], v[98:101]
	v_mfma_f32_16x16x32_bf16 v[90:93], v[140:143], v[184:187], v[90:93]
	v_mfma_f32_16x16x32_bf16 v[82:85], v[148:151], v[184:187], v[82:85]
	v_mfma_f32_16x16x32_bf16 v[126:129], v[144:147], v[164:167], v[126:129]
	v_mfma_f32_16x16x32_bf16 v[122:125], v[152:155], v[164:167], v[122:125]
	v_mfma_f32_16x16x32_bf16 v[118:121], v[144:147], v[172:175], v[118:121]
	v_mfma_f32_16x16x32_bf16 v[114:117], v[152:155], v[172:175], v[114:117]
	v_mfma_f32_16x16x32_bf16 v[106:109], v[144:147], v[180:183], v[106:109]
	v_mfma_f32_16x16x32_bf16 v[98:101], v[152:155], v[180:183], v[98:101]
	v_mfma_f32_16x16x32_bf16 v[90:93], v[144:147], v[188:191], v[90:93]
	v_mfma_f32_16x16x32_bf16 v[82:85], v[152:155], v[188:191], v[82:85]
	v_mfma_f32_16x16x32_bf16 v[110:113], v[192:195], v[160:163], v[110:113]
	v_mfma_f32_16x16x32_bf16 v[102:105], v[200:203], v[160:163], v[102:105]
	v_mfma_f32_16x16x32_bf16 v[94:97], v[192:195], v[168:171], v[94:97]
	v_mfma_f32_16x16x32_bf16 v[86:89], v[200:203], v[168:171], v[86:89]
	v_mfma_f32_16x16x32_bf16 v[78:81], v[192:195], v[176:179], v[78:81]
	v_mfma_f32_16x16x32_bf16 v[74:77], v[200:203], v[176:179], v[74:77]
	v_mfma_f32_16x16x32_bf16 v[70:73], v[192:195], v[184:187], v[70:73]
	v_mfma_f32_16x16x32_bf16 v[66:69], v[200:203], v[184:187], v[66:69]
	v_mfma_f32_16x16x32_bf16 v[110:113], v[196:199], v[164:167], v[110:113]
	v_mfma_f32_16x16x32_bf16 v[102:105], v[204:207], v[164:167], v[102:105]
	v_mfma_f32_16x16x32_bf16 v[94:97], v[196:199], v[172:175], v[94:97]
	v_mfma_f32_16x16x32_bf16 v[86:89], v[204:207], v[172:175], v[86:89]
	v_mfma_f32_16x16x32_bf16 v[78:81], v[196:199], v[180:183], v[78:81]
	v_mfma_f32_16x16x32_bf16 v[74:77], v[204:207], v[180:183], v[74:77]
	v_mfma_f32_16x16x32_bf16 v[70:73], v[196:199], v[188:191], v[70:73]
	v_mfma_f32_16x16x32_bf16 v[66:69], v[204:207], v[188:191], v[66:69]
	s_setprio 0
	s_barrier
	s_add_i32 s38, s38, s63
	v_lshl_add_u64 v[156:157], s[54:55], 0, v[0:1]
	s_mov_b32 m0, s38
	v_lshl_add_u64 v[210:211], s[54:55], 0, v[130:131]
	global_load_lds_dwordx4 v[156:157], off
	s_add_i32 m0, s38, 0x2000
	s_nop 0
	global_load_lds_dwordx4 v[210:211], off
	s_mov_b32 m0, s25
	v_lshl_add_u64 v[212:213], s[56:57], 0, v[0:1]
	global_load_lds_dwordx4 v[212:213], off
	v_lshl_add_u64 v[214:215], s[56:57], 0, v[130:131]
	s_mov_b32 m0, s27
	s_nop 0
	global_load_lds_dwordx4 v[214:215], off
	ds_read_b128 v[160:163], v139 offset:16384
	ds_read_b128 v[164:167], v139 offset:17408
	ds_read_b128 v[168:171], v139 offset:18432
	ds_read_b128 v[172:175], v139 offset:19456
	ds_read_b128 v[176:179], v139 offset:20480
	ds_read_b128 v[180:183], v139 offset:21504
	ds_read_b128 v[184:187], v139 offset:22528
	ds_read_b128 v[188:191], v139 offset:23552
	s_waitcnt vmcnt(6)
	s_waitcnt lgkmcnt(0)
	s_barrier
; #define PG8_STAGE(bufoff, gbase, voff) do { _Pragma("unroll") for (int _i = 0; _i < 2; ++_i) \
;         __builtin_amdgcn_global_load_lds((const unsigned*)((const char*)(gbase) + (voff)[_i]), (LAS unsigned*)(lds + (bufoff) + ldsw + _i * 8192), 16, 0, 0); } while (0)
; #define PG8_LDA(dst, b, h) do { _Pragma("unroll") for (int m = 0; m < 4; ++m) _Pragma("unroll") for (int k = 0; k < 2; ++k) dst[m][k] = *(const LAS bf16x8*)(lds + PG8_SA(b, h) + aoff + m * 2048 + k * 1024); } while (0)
; #define PG8_LDB(dst, b, h) do { _Pragma("unroll") for (int n = 0; n < 2; ++n) _Pragma("unroll") for (int k = 0; k < 2; ++k) dst[n][k] = *(const LAS bf16x8*)(lds + PG8_SB(b, h) + boff + n * 2048 + k * 1024); } while (0)
; #define PG8_MMA(ai, bj, At, Bt) do { __builtin_amdgcn_s_setprio(1); _Pragma("unroll") for (int m = 0; m < 4; ++m) _Pragma("unroll") for (int n = 0; n < 2; ++n) _Pragma("unroll") for (int k = 0; k < 2; ++k) \
;         acc[ai][bj][m][n] = __builtin_amdgcn_mfma_f32_16x16x32_bf16(Bt[n][k], At[m][k], acc[ai][bj][m][n], 0, 0, 0); __builtin_amdgcn_s_setprio(0); } while (0)
; #define PG8_WAIT_V(n) asm volatile("s_waitcnt vmcnt(" #n ")" ::: "memory")
; #define PG8_WAIT_L(n) asm volatile("s_waitcnt lgkmcnt(" #n ")" ::: "memory")
; #define PG8_BAR __builtin_amdgcn_s_barrier()
; #define PG8_SCHED __builtin_amdgcn_sched_barrier(0)
; template <class Epi, class Sched>
; __device__ __forceinline__ void gemm_phase(LAS unsigned char* lds, const Gemm g, const Sched& S, const Epi& E) {
;     ...
;             PG8_BAR; PG8_WAIT_L(0); PG8_MMA(1, 0, At, B0); PG8_BAR; PG8_SCHED;
;             PG8_STAGE(PG8_SB(0, 1), b2 + hstep, voffB);
;             PG8_WAIT_V(6); PG8_BAR; PG8_MMA(1, 1, At, B1); PG8_BAR;
;             PG8_LDB(B0, 1, 0); PG8_SCHED; PG8_LDA(At, 1, 0); PG8_STAGE(PG8_SA(0, 1), a2 + hstep, voffA);
;             PG8_WAIT_L(8); PG8_BAR; PG8_WAIT_L(0); PG8_MMA(0, 0, At, B0); PG8_BAR; PG8_SCHED;
;             PG8_LDB(B1, 1, 1); PG8_STAGE(PG8_SB(1, 0), b3, voffB);
;             PG8_BAR; PG8_WAIT_L(0); PG8_MMA(0, 1, At, B1); PG8_BAR;
	s_setprio 1
	v_mfma_f32_16x16x32_bf16 v[62:65], v[140:143], v[160:163], v[62:65]
	v_mfma_f32_16x16x32_bf16 v[58:61], v[148:151], v[160:163], v[58:61]
	v_mfma_f32_16x16x32_bf16 v[54:57], v[140:143], v[168:171], v[54:57]
	v_mfma_f32_16x16x32_bf16 v[50:53], v[148:151], v[168:171], v[50:53]
	v_mfma_f32_16x16x32_bf16 v[38:41], v[140:143], v[176:179], v[38:41]
	v_mfma_f32_16x16x32_bf16 v[34:37], v[148:151], v[176:179], v[34:37]
	v_mfma_f32_16x16x32_bf16 v[22:25], v[140:143], v[184:187], v[22:25]
	v_mfma_f32_16x16x32_bf16 v[18:21], v[148:151], v[184:187], v[18:21]
	v_mfma_f32_16x16x32_bf16 v[62:65], v[144:147], v[164:167], v[62:65]
	v_mfma_f32_16x16x32_bf16 v[58:61], v[152:155], v[164:167], v[58:61]
	v_mfma_f32_16x16x32_bf16 v[54:57], v[144:147], v[172:175], v[54:57]
	v_mfma_f32_16x16x32_bf16 v[50:53], v[152:155], v[172:175], v[50:53]
	v_mfma_f32_16x16x32_bf16 v[38:41], v[144:147], v[180:183], v[38:41]
	v_mfma_f32_16x16x32_bf16 v[34:37], v[152:155], v[180:183], v[34:37]
	v_mfma_f32_16x16x32_bf16 v[22:25], v[144:147], v[188:191], v[22:25]
	v_mfma_f32_16x16x32_bf16 v[18:21], v[152:155], v[188:191], v[18:21]
	s_add_u32 s38, s54, 0x200000
	s_addc_u32 s39, s55, 0
	s_add_i32 s50, s50, s63
	v_lshl_add_u64 v[140:141], s[38:39], 0, v[0:1]
	s_mov_b32 m0, s50
	s_nop 0
	global_load_lds_dwordx4 v[140:141], off
	v_lshl_add_u64 v[140:141], s[38:39], 0, v[130:131]
	s_add_i32 m0, s50, 0x2000
	s_nop 0
	global_load_lds_dwordx4 v[140:141], off
	v_mfma_f32_16x16x32_bf16 v[46:49], v[192:195], v[160:163], v[46:49]
	v_mfma_f32_16x16x32_bf16 v[42:45], v[200:203], v[160:163], v[42:45]
	v_mfma_f32_16x16x32_bf16 v[30:33], v[192:195], v[168:171], v[30:33]
	v_mfma_f32_16x16x32_bf16 v[26:29], v[200:203], v[168:171], v[26:29]
	v_mfma_f32_16x16x32_bf16 v[14:17], v[192:195], v[176:179], v[14:17]
	v_mfma_f32_16x16x32_bf16 v[10:13], v[200:203], v[176:179], v[10:13]
	v_mfma_f32_16x16x32_bf16 v[6:9], v[192:195], v[184:187], v[6:9]
	v_mfma_f32_16x16x32_bf16 v[2:5], v[200:203], v[184:187], v[2:5]
	v_mfma_f32_16x16x32_bf16 v[46:49], v[196:199], v[164:167], v[46:49]
	v_mfma_f32_16x16x32_bf16 v[42:45], v[204:207], v[164:167], v[42:45]
	v_mfma_f32_16x16x32_bf16 v[30:33], v[196:199], v[172:175], v[30:33]
	v_mfma_f32_16x16x32_bf16 v[26:29], v[204:207], v[172:175], v[26:29]
	v_mfma_f32_16x16x32_bf16 v[14:17], v[196:199], v[180:183], v[14:17]
	v_mfma_f32_16x16x32_bf16 v[10:13], v[204:207], v[180:183], v[10:13]
	v_mfma_f32_16x16x32_bf16 v[6:9], v[196:199], v[188:191], v[6:9]
	v_mfma_f32_16x16x32_bf16 v[2:5], v[204:207], v[188:191], v[2:5]
	s_setprio 0
	s_barrier
	s_add_u32 s38, s56, 0x200000
	s_addc_u32 s39, s57, 0
	s_mov_b32 m0, s64
	v_lshl_add_u64 v[192:193], s[38:39], 0, v[0:1]
	global_load_lds_dwordx4 v[192:193], off
	v_lshl_add_u64 v[192:193], s[38:39], 0, v[130:131]
	s_mov_b32 m0, s65
	s_nop 0
	global_load_lds_dwordx4 v[192:193], off
	s_add_i32 s50, 0, 0x18000
	v_add_u32_e32 v152, s50, v137
	ds_read_b128 v[140:143], v152
	ds_read_b128 v[144:147], v152 offset:1024
	ds_read_b128 v[148:151], v152 offset:2048
	ds_read_b128 v[152:155], v152 offset:3072
	ds_read_b128 v[160:163], v139 offset:32768
	ds_read_b128 v[164:167], v139 offset:33792
	ds_read_b128 v[168:171], v139 offset:34816
	ds_read_b128 v[172:175], v139 offset:35840
	ds_read_b128 v[176:179], v139 offset:36864
	ds_read_b128 v[180:183], v139 offset:37888
	ds_read_b128 v[184:187], v139 offset:38912
	ds_read_b128 v[188:191], v139 offset:39936
	s_add_i32 s51, 0, 0x1c000
	v_add_u32_e32 v204, s51, v137
	ds_read_b128 v[192:195], v204
	ds_read_b128 v[196:199], v204 offset:1024
	ds_read_b128 v[200:203], v204 offset:2048
	ds_read_b128 v[204:207], v204 offset:3072
	s_waitcnt vmcnt(8)
	s_waitcnt lgkmcnt(4)
	s_barrier
	s_waitcnt lgkmcnt(0)
	s_setprio 1
	v_mfma_f32_16x16x32_bf16 v[126:129], v[140:143], v[160:163], v[126:129]
	v_mfma_f32_16x16x32_bf16 v[122:125], v[148:151], v[160:163], v[122:125]
	v_mfma_f32_16x16x32_bf16 v[118:121], v[140:143], v[168:171], v[118:121]
	v_mfma_f32_16x16x32_bf16 v[114:117], v[148:151], v[168:171], v[114:117]
	v_mfma_f32_16x16x32_bf16 v[106:109], v[140:143], v[176:179], v[106:109]
	v_mfma_f32_16x16x32_bf16 v[98:101], v[148:151], v[176:179], v[98:101]
	v_mfma_f32_16x16x32_bf16 v[90:93], v[140:143], v[184:187], v[90:93]
	v_mfma_f32_16x16x32_bf16 v[82:85], v[148:151], v[184:187], v[82:85]
	v_mfma_f32_16x16x32_bf16 v[126:129], v[144:147], v[164:167], v[126:129]
	v_mfma_f32_16x16x32_bf16 v[122:125], v[152:155], v[164:167], v[122:125]
	v_mfma_f32_16x16x32_bf16 v[118:121], v[144:147], v[172:175], v[118:121]
	v_mfma_f32_16x16x32_bf16 v[114:117], v[152:155], v[172:175], v[114:117]
	v_mfma_f32_16x16x32_bf16 v[106:109], v[144:147], v[180:183], v[106:109]
	v_mfma_f32_16x16x32_bf16 v[98:101], v[152:155], v[180:183], v[98:101]
	v_mfma_f32_16x16x32_bf16 v[90:93], v[144:147], v[188:191], v[90:93]
	v_mfma_f32_16x16x32_bf16 v[82:85], v[152:155], v[188:191], v[82:85]
	v_mfma_f32_16x16x32_bf16 v[110:113], v[192:195], v[160:163], v[110:113]
	v_mfma_f32_16x16x32_bf16 v[102:105], v[200:203], v[160:163], v[102:105]
	v_mfma_f32_16x16x32_bf16 v[94:97], v[192:195], v[168:171], v[94:97]
	v_mfma_f32_16x16x32_bf16 v[86:89], v[200:203], v[168:171], v[86:89]
	v_mfma_f32_16x16x32_bf16 v[78:81], v[192:195], v[176:179], v[78:81]
	v_mfma_f32_16x16x32_bf16 v[74:77], v[200:203], v[176:179], v[74:77]
	v_mfma_f32_16x16x32_bf16 v[70:73], v[192:195], v[184:187], v[70:73]
	v_mfma_f32_16x16x32_bf16 v[66:69], v[200:203], v[184:187], v[66:69]
	v_mfma_f32_16x16x32_bf16 v[110:113], v[196:199], v[164:167], v[110:113]
	v_mfma_f32_16x16x32_bf16 v[102:105], v[204:207], v[164:167], v[102:105]
	v_mfma_f32_16x16x32_bf16 v[94:97], v[196:199], v[172:175], v[94:97]
	v_mfma_f32_16x16x32_bf16 v[86:89], v[204:207], v[172:175], v[86:89]
	v_mfma_f32_16x16x32_bf16 v[78:81], v[196:199], v[180:183], v[78:81]
	v_mfma_f32_16x16x32_bf16 v[74:77], v[204:207], v[180:183], v[74:77]
	v_mfma_f32_16x16x32_bf16 v[70:73], v[196:199], v[188:191], v[70:73]
	v_mfma_f32_16x16x32_bf16 v[66:69], v[204:207], v[188:191], v[66:69]
	s_setprio 0
	s_barrier
; #define PG8_STAGE(bufoff, gbase, voff) do { _Pragma("unroll") for (int _i = 0; _i < 2; ++_i) \
;         __builtin_amdgcn_global_load_lds((const unsigned*)((const char*)(gbase) + (voff)[_i]), (LAS unsigned*)(lds + (bufoff) + ldsw + _i * 8192), 16, 0, 0); } while (0)
; #define PG8_LDA(dst, b, h) do { _Pragma("unroll") for (int m = 0; m < 4; ++m) _Pragma("unroll") for (int k = 0; k < 2; ++k) dst[m][k] = *(const LAS bf16x8*)(lds + PG8_SA(b, h) + aoff + m * 2048 + k * 1024); } while (0)
; #define PG8_MMA(ai, bj, At, Bt) do { __builtin_amdgcn_s_setprio(1); _Pragma("unroll") for (int m = 0; m < 4; ++m) _Pragma("unroll") for (int n = 0; n < 2; ++n) _Pragma("unroll") for (int k = 0; k < 2; ++k) \
;         acc[ai][bj][m][n] = __builtin_amdgcn_mfma_f32_16x16x32_bf16(Bt[n][k], At[m][k], acc[ai][bj][m][n], 0, 0, 0); __builtin_amdgcn_s_setprio(0); } while (0)
; #define PG8_WAIT_V(n) asm volatile("s_waitcnt vmcnt(" #n ")" ::: "memory")
; #define PG8_WAIT_L(n) asm volatile("s_waitcnt lgkmcnt(" #n ")" ::: "memory")
; #define PG8_BAR __builtin_amdgcn_s_barrier()
; #define PG8_SCHED __builtin_amdgcn_sched_barrier(0)
; template <class Epi, class Sched>
; __device__ __forceinline__ void gemm_phase(LAS unsigned char* lds, const Gemm g, const Sched& S, const Epi& E) {
;     ...
;             PG8_LDA(At, 1, 1); PG8_STAGE(PG8_SA(1, 0), a3, voffA);
;             PG8_BAR; PG8_WAIT_L(0); PG8_MMA(1, 0, At, B0); PG8_BAR; PG8_SCHED;
;             PG8_STAGE(PG8_SB(1, 1), b3 + hstep, voffB);
;             PG8_WAIT_V(6); PG8_BAR; PG8_MMA(1, 1, At, B1); PG8_BAR;
;         }
	s_add_i32 s38, s50, s63
	v_lshl_add_u64 v[156:157], v[156:157], 0, s[36:37]
	s_mov_b32 m0, s38
	s_nop 0
	global_load_lds_dwordx4 v[156:157], off
	v_lshl_add_u64 v[156:157], v[210:211], 0, s[36:37]
	s_add_i32 m0, s38, 0x2000
	s_nop 0
	global_load_lds_dwordx4 v[156:157], off
	s_mov_b32 m0, s66
	v_lshl_add_u64 v[156:157], v[212:213], 0, s[36:37]
	global_load_lds_dwordx4 v[156:157], off
	v_lshl_add_u64 v[156:157], v[214:215], 0, s[36:37]
	s_mov_b32 m0, s67
	s_nop 0
	global_load_lds_dwordx4 v[156:157], off
	ds_read_b128 v[160:163], v139 offset:49152
	ds_read_b128 v[164:167], v139 offset:50176
	ds_read_b128 v[168:171], v139 offset:51200
	ds_read_b128 v[172:175], v139 offset:52224
	ds_read_b128 v[176:179], v139 offset:53248
	ds_read_b128 v[180:183], v139 offset:54272
	ds_read_b128 v[184:187], v139 offset:55296
	ds_read_b128 v[188:191], v139 offset:56320
	s_waitcnt vmcnt(6)
	s_waitcnt lgkmcnt(0)
	s_barrier
	s_setprio 1
	v_mfma_f32_16x16x32_bf16 v[62:65], v[140:143], v[160:163], v[62:65]
	v_mfma_f32_16x16x32_bf16 v[58:61], v[148:151], v[160:163], v[58:61]
	v_mfma_f32_16x16x32_bf16 v[54:57], v[140:143], v[168:171], v[54:57]
	v_mfma_f32_16x16x32_bf16 v[50:53], v[148:151], v[168:171], v[50:53]
	v_mfma_f32_16x16x32_bf16 v[38:41], v[140:143], v[176:179], v[38:41]
	v_mfma_f32_16x16x32_bf16 v[34:37], v[148:151], v[176:179], v[34:37]
	v_mfma_f32_16x16x32_bf16 v[22:25], v[140:143], v[184:187], v[22:25]
	v_mfma_f32_16x16x32_bf16 v[18:21], v[148:151], v[184:187], v[18:21]
	v_mfma_f32_16x16x32_bf16 v[62:65], v[144:147], v[164:167], v[62:65]
	v_mfma_f32_16x16x32_bf16 v[58:61], v[152:155], v[164:167], v[58:61]
	v_mfma_f32_16x16x32_bf16 v[54:57], v[144:147], v[172:175], v[54:57]
	v_mfma_f32_16x16x32_bf16 v[50:53], v[152:155], v[172:175], v[50:53]
	v_mfma_f32_16x16x32_bf16 v[38:41], v[144:147], v[180:183], v[38:41]
	v_mfma_f32_16x16x32_bf16 v[34:37], v[152:155], v[180:183], v[34:37]
	v_mfma_f32_16x16x32_bf16 v[22:25], v[144:147], v[188:191], v[22:25]
	v_mfma_f32_16x16x32_bf16 v[18:21], v[152:155], v[188:191], v[18:21]
	s_add_u32 s38, s54, 0x200080
	s_addc_u32 s39, s55, 0
	s_add_i32 s50, s51, s63
	v_lshl_add_u64 v[140:141], s[38:39], 0, v[0:1]
	s_mov_b32 m0, s50
	s_nop 0
	global_load_lds_dwordx4 v[140:141], off
	v_lshl_add_u64 v[140:141], s[38:39], 0, v[130:131]
	s_add_i32 m0, s50, 0x2000
	s_nop 0
	global_load_lds_dwordx4 v[140:141], off
	v_mfma_f32_16x16x32_bf16 v[46:49], v[192:195], v[160:163], v[46:49]
	v_mfma_f32_16x16x32_bf16 v[42:45], v[200:203], v[160:163], v[42:45]
	v_mfma_f32_16x16x32_bf16 v[30:33], v[192:195], v[168:171], v[30:33]
	v_mfma_f32_16x16x32_bf16 v[26:29], v[200:203], v[168:171], v[26:29]
	v_mfma_f32_16x16x32_bf16 v[14:17], v[192:195], v[176:179], v[14:17]
	v_mfma_f32_16x16x32_bf16 v[10:13], v[200:203], v[176:179], v[10:13]
	v_mfma_f32_16x16x32_bf16 v[6:9], v[192:195], v[184:187], v[6:9]
	v_mfma_f32_16x16x32_bf16 v[2:5], v[200:203], v[184:187], v[2:5]
	v_mfma_f32_16x16x32_bf16 v[46:49], v[196:199], v[164:167], v[46:49]
	v_mfma_f32_16x16x32_bf16 v[42:45], v[204:207], v[164:167], v[42:45]
	v_mfma_f32_16x16x32_bf16 v[30:33], v[196:199], v[172:175], v[30:33]
	v_mfma_f32_16x16x32_bf16 v[26:29], v[204:207], v[172:175], v[26:29]
	v_mfma_f32_16x16x32_bf16 v[14:17], v[196:199], v[180:183], v[14:17]
	v_mfma_f32_16x16x32_bf16 v[10:13], v[204:207], v[180:183], v[10:13]
	v_mfma_f32_16x16x32_bf16 v[6:9], v[196:199], v[188:191], v[6:9]
	v_mfma_f32_16x16x32_bf16 v[2:5], v[204:207], v[188:191], v[2:5]
	s_setprio 0
	s_add_i32 s71, s71, 2
	s_add_u32 s69, s69, 0x100
	s_addc_u32 s70, s70, 0
	s_cmp_gt_u32 s71, 29
	s_mov_b64 s[50:51], s[52:53]
	s_barrier
	s_cbranch_scc0 .LBB0_58
;     __device__ __forceinline__ void operator()(const f32x4 (&acc)[2][2][4][2], const Unit& u, int wr, int wc, int fr, int fq) const {
;         const int row0 = u.pm * BM + wr * 64 + fr, col0 = u.pn * BM + wc * 32 + 4 * fq;
;         float* base = part + (size_t)u.ks * Mp * ldc;
; #pragma unroll
;         for (int ai = 0; ai < 2; ++ai)
; #pragma unroll
;             for (int m = 0; m < 4; ++m) { float* rowp = base + (size_t)(row0 + ai * HALF + m * 16) * ldc + col0;
; #pragma unroll
;                 for (int bj = 0; bj < 2; ++bj)
; #pragma unroll
;                     for (int n = 0; n < 2; ++n) *(f32x4*)(rowp + bj * HALF + n * 16) = acc[ai][bj][m][n]; }
;     }
	s_ashr_i32 s11, s10, 31
	s_lshl_b64 s[10:11], s[10:11], 24
	v_lshl_or_b32 v140, s26, 8, v138
	s_add_u32 s10, s8, s10
	v_lshl_add_u32 v142, s24, 8, v136
	s_addc_u32 s11, s9, s11
	v_ashrrev_i32_e32 v141, 31, v140
	v_ashrrev_i32_e32 v143, 31, v142
	v_lshl_add_u64 v[140:141], v[140:141], 2, s[10:11]
	v_lshlrev_b64 v[144:145], 13, v[142:143]
	v_lshl_add_u64 v[144:145], v[140:141], 0, v[144:145]
	global_store_dwordx4 v[144:145], v[126:129], off
	global_store_dwordx4 v[144:145], v[122:125], off offset:64
	global_store_dwordx4 v[144:145], v[110:113], off offset:512
	global_store_dwordx4 v[144:145], v[102:105], off offset:576
	s_mov_b64 s[10:11], 0x100000
	s_mov_b32 s26, s40
	v_or_b32_e32 v102, 16, v142
	v_ashrrev_i32_e32 v103, 31, v102
	v_lshlrev_b64 v[102:103], 13, v[102:103]
	v_lshl_add_u64 v[102:103], v[140:141], 0, v[102:103]
	global_store_dwordx4 v[102:103], v[118:121], off
	global_store_dwordx4 v[102:103], v[114:117], off offset:64
	global_store_dwordx4 v[102:103], v[94:97], off offset:512
	global_store_dwordx4 v[102:103], v[86:89], off offset:576
	s_mov_b32 s24, s42
	s_mov_b64 s[52:53], s[48:49]
	v_or_b32_e32 v86, 32, v142
	v_ashrrev_i32_e32 v87, 31, v86
	v_lshlrev_b64 v[86:87], 13, v[86:87]
	v_lshl_add_u64 v[86:87], v[140:141], 0, v[86:87]
	global_store_dwordx4 v[86:87], v[106:109], off
	global_store_dwordx4 v[86:87], v[98:101], off offset:64
	global_store_dwordx4 v[86:87], v[78:81], off offset:512
	global_store_dwordx4 v[86:87], v[74:77], off offset:576
	s_mov_b64 s[50:51], s[46:47]
	s_nop 0
	v_or_b32_e32 v74, 48, v142
	v_ashrrev_i32_e32 v75, 31, v74
	v_lshlrev_b64 v[74:75], 13, v[74:75]
	v_lshl_add_u64 v[74:75], v[140:141], 0, v[74:75]
	global_store_dwordx4 v[74:75], v[90:93], off
	global_store_dwordx4 v[74:75], v[82:85], off offset:64
	global_store_dwordx4 v[74:75], v[70:73], off offset:512
	global_store_dwordx4 v[74:75], v[66:69], off offset:576
	s_nop 1
	v_add_co_u32_e32 v68, vcc, s93, v144
	v_lshl_add_u64 v[66:67], v[144:145], 0, s[10:11]
	s_nop 0
	v_addc_co_u32_e32 v69, vcc, 0, v145, vcc
	s_mov_b64 s[10:11], 0x120000
	global_store_dwordx4 v[68:69], v[62:65], off
	global_store_dwordx4 v[66:67], v[58:61], off offset:64
	global_store_dwordx4 v[66:67], v[46:49], off offset:512
	global_store_dwordx4 v[66:67], v[42:45], off offset:576
	s_nop 1
	v_lshl_add_u64 v[42:43], v[144:145], 0, s[10:11]
	s_mov_b32 s10, 0x120000
	v_add_co_u32_e32 v44, vcc, s10, v144
	s_mov_b64 s[10:11], 0x140000
	s_nop 0
	v_addc_co_u32_e32 v45, vcc, 0, v145, vcc
	global_store_dwordx4 v[44:45], v[54:57], off
	global_store_dwordx4 v[42:43], v[50:53], off offset:64
	global_store_dwordx4 v[42:43], v[30:33], off offset:512
	global_store_dwordx4 v[42:43], v[26:29], off offset:576
	s_nop 1
	v_lshl_add_u64 v[26:27], v[144:145], 0, s[10:11]
	s_mov_b32 s10, 0x140000
	v_add_co_u32_e32 v28, vcc, s10, v144
	s_mov_b64 s[10:11], 0x160000
	s_nop 0
	v_addc_co_u32_e32 v29, vcc, 0, v145, vcc
	global_store_dwordx4 v[28:29], v[38:41], off
	global_store_dwordx4 v[26:27], v[34:37], off offset:64
	global_store_dwordx4 v[26:27], v[14:17], off offset:512
	global_store_dwordx4 v[26:27], v[10:13], off offset:576
	s_nop 1
	v_add_co_u32_e32 v12, vcc, 0x160000, v144
	v_lshl_add_u64 v[10:11], v[144:145], 0, s[10:11]
	s_nop 0
	v_addc_co_u32_e32 v13, vcc, 0, v145, vcc
	s_and_b64 vcc, exec, s[44:45]
	s_mov_b32 s10, s28
	global_store_dwordx4 v[12:13], v[22:25], off
	global_store_dwordx4 v[10:11], v[18:21], off offset:64
	global_store_dwordx4 v[10:11], v[6:9], off offset:512
	global_store_dwordx4 v[10:11], v[2:5], off offset:576
	s_cbranch_vccz .LBB0_55
	s_waitcnt vmcnt(0)
	s_cmpk_gt_u32 s60, 0xff
	s_cbranch_scc1 .LBB0_62
	s_barrier

; #define PG8_STAGE(bufoff, gbase, voff) do { _Pragma("unroll") for (int _i = 0; _i < 2; ++_i) \
;         __builtin_amdgcn_global_load_lds((const unsigned*)((const char*)(gbase) + (voff)[_i]), (LAS unsigned*)(lds + (bufoff) + ldsw + _i * 8192), 16, 0, 0); } while (0)
; #define PG8_LDA(dst, b, h) do { _Pragma("unroll") for (int m = 0; m < 4; ++m) _Pragma("unroll") for (int k = 0; k < 2; ++k) dst[m][k] = *(const LAS bf16x8*)(lds + PG8_SA(b, h) + aoff + m * 2048 + k * 1024); } while (0)
; #define PG8_LDB(dst, b, h) do { _Pragma("unroll") for (int n = 0; n < 2; ++n) _Pragma("unroll") for (int k = 0; k < 2; ++k) dst[n][k] = *(const LAS bf16x8*)(lds + PG8_SB(b, h) + boff + n * 2048 + k * 1024); } while (0)
; #define PG8_MMA(ai, bj, At, Bt) do { __builtin_amdgcn_s_setprio(1); _Pragma("unroll") for (int m = 0; m < 4; ++m) _Pragma("unroll") for (int n = 0; n < 2; ++n) _Pragma("unroll") for (int k = 0; k < 2; ++k) \
;         acc[ai][bj][m][n] = __builtin_amdgcn_mfma_f32_16x16x32_bf16(Bt[n][k], At[m][k], acc[ai][bj][m][n], 0, 0, 0); __builtin_amdgcn_s_setprio(0); } while (0)
; #define PG8_WAIT_V(n) asm volatile("s_waitcnt vmcnt(" #n ")" ::: "memory")
; #define PG8_WAIT_L(n) asm volatile("s_waitcnt lgkmcnt(" #n ")" ::: "memory")
; #define PG8_BAR __builtin_amdgcn_s_barrier()
; template <class Epi, class Sched>
; __device__ __forceinline__ void gemm_phase(LAS unsigned char* lds, const Gemm g, const Sched& S, const Epi& E) {
;     ...
;             const bool last = (t == nt - 2);
;             const char* a1 = cA + (size_t)(t + 1) * kstep;
;             const char* a2 = last ? nA : cA + (size_t)(t + 2) * kstep; const char* b2 = last ? nB : cB + (size_t)(t + 2) * kstep;
;             const char* a3 = a2 + kstep; const char* b3 = b2 + kstep;
;             PG8_LDB(B0, 0, 0); PG8_SCHED; PG8_LDA(At, 0, 0); PG8_STAGE(PG8_SA(1, 1), a1 + hstep, voffA);
;             PG8_WAIT_L(8); PG8_BAR; PG8_WAIT_L(0); PG8_MMA(0, 0, At, B0); PG8_BAR; PG8_SCHED;
;             PG8_LDB(B1, 0, 1); PG8_STAGE(PG8_SB(0, 0), b2, voffB);
;             PG8_BAR; PG8_WAIT_L(0); PG8_MMA(0, 1, At, B1); PG8_BAR;
;             PG8_LDA(At, 0, 1); PG8_STAGE(PG8_SA(0, 0), a2, voffA);
;             PG8_BAR; PG8_WAIT_L(0); PG8_MMA(1, 0, At, B0); PG8_BAR; PG8_SCHED;
;             PG8_STAGE(PG8_SB(0, 1), b2 + hstep, voffB);
;             PG8_WAIT_V(6); PG8_BAR; PG8_MMA(1, 1, At, B1); PG8_BAR;
.LBB0_73:
	s_add_u32 s38, s46, 0xfff80080
	s_addc_u32 s39, s47, -1
	s_cmp_eq_u32 s73, 28
	s_cselect_b32 s51, s29, s39
	s_cselect_b32 s50, s69, s38
	s_cselect_b32 s49, s27, s72
	s_cselect_b32 s48, s70, s71
	v_lshl_add_u64 v[140:141], s[46:47], 0, v[138:139]
	s_add_i32 m0, s9, 0xc000
	s_nop 0
	global_load_lds_dwordx4 v[140:141], off
	v_lshl_add_u64 v[140:141], s[46:47], 0, v[136:137]
	s_add_i32 m0, s9, 0xe000
	s_nop 0
	global_load_lds_dwordx4 v[140:141], off
	s_add_i32 s74, 0, 0x10000
	v_add_u32_e32 v140, s74, v143
	ds_read_b128 v[146:149], v140
	ds_read_b128 v[150:153], v140 offset:1024
	ds_read_b128 v[154:157], v140 offset:2048
	ds_read_b128 v[160:163], v140 offset:3072
	ds_read_b128 v[164:167], v145
	ds_read_b128 v[168:171], v145 offset:1024
	ds_read_b128 v[172:175], v145 offset:2048
	ds_read_b128 v[176:179], v145 offset:3072
	ds_read_b128 v[180:183], v145 offset:4096
	ds_read_b128 v[184:187], v145 offset:5120
	ds_read_b128 v[188:191], v145 offset:6144
	ds_read_b128 v[192:195], v145 offset:7168
	s_add_i32 s75, 0, 0x14000
	v_add_u32_e32 v140, s75, v143
	ds_read_b128 v[196:199], v140
	ds_read_b128 v[200:203], v140 offset:1024
	ds_read_b128 v[204:207], v140 offset:2048
	ds_read_b128 v[210:213], v140 offset:3072
	s_waitcnt vmcnt(8)
	s_waitcnt lgkmcnt(4)
	s_barrier
	s_waitcnt lgkmcnt(0)
	s_setprio 1
	v_mfma_f32_16x16x32_bf16 v[126:129], v[146:149], v[164:167], v[126:129]
	v_mfma_f32_16x16x32_bf16 v[122:125], v[154:157], v[164:167], v[122:125]
	v_mfma_f32_16x16x32_bf16 v[110:113], v[146:149], v[172:175], v[110:113]
	v_mfma_f32_16x16x32_bf16 v[106:109], v[154:157], v[172:175], v[106:109]
	v_mfma_f32_16x16x32_bf16 v[94:97], v[146:149], v[180:183], v[94:97]
	v_mfma_f32_16x16x32_bf16 v[90:93], v[154:157], v[180:183], v[90:93]
	v_mfma_f32_16x16x32_bf16 v[78:81], v[146:149], v[188:191], v[78:81]
	v_mfma_f32_16x16x32_bf16 v[74:77], v[154:157], v[188:191], v[74:77]
	v_mfma_f32_16x16x32_bf16 v[126:129], v[150:153], v[168:171], v[126:129]
	v_mfma_f32_16x16x32_bf16 v[122:125], v[160:163], v[168:171], v[122:125]
	v_mfma_f32_16x16x32_bf16 v[110:113], v[150:153], v[176:179], v[110:113]
	v_mfma_f32_16x16x32_bf16 v[106:109], v[160:163], v[176:179], v[106:109]
	v_mfma_f32_16x16x32_bf16 v[94:97], v[150:153], v[184:187], v[94:97]
	v_mfma_f32_16x16x32_bf16 v[90:93], v[160:163], v[184:187], v[90:93]
	v_mfma_f32_16x16x32_bf16 v[78:81], v[150:153], v[192:195], v[78:81]
	v_mfma_f32_16x16x32_bf16 v[74:77], v[160:163], v[192:195], v[74:77]
	v_mfma_f32_16x16x32_bf16 v[118:121], v[196:199], v[164:167], v[118:121]
	v_mfma_f32_16x16x32_bf16 v[114:117], v[204:207], v[164:167], v[114:117]
	v_mfma_f32_16x16x32_bf16 v[102:105], v[196:199], v[172:175], v[102:105]
	v_mfma_f32_16x16x32_bf16 v[98:101], v[204:207], v[172:175], v[98:101]
	v_mfma_f32_16x16x32_bf16 v[86:89], v[196:199], v[180:183], v[86:89]
	v_mfma_f32_16x16x32_bf16 v[82:85], v[204:207], v[180:183], v[82:85]
	v_mfma_f32_16x16x32_bf16 v[70:73], v[196:199], v[188:191], v[70:73]
	v_mfma_f32_16x16x32_bf16 v[66:69], v[204:207], v[188:191], v[66:69]
	v_mfma_f32_16x16x32_bf16 v[118:121], v[200:203], v[168:171], v[118:121]
	v_mfma_f32_16x16x32_bf16 v[114:117], v[210:213], v[168:171], v[114:117]
	v_mfma_f32_16x16x32_bf16 v[102:105], v[200:203], v[176:179], v[102:105]
	v_mfma_f32_16x16x32_bf16 v[98:101], v[210:213], v[176:179], v[98:101]
	v_mfma_f32_16x16x32_bf16 v[86:89], v[200:203], v[184:187], v[86:89]
	v_mfma_f32_16x16x32_bf16 v[82:85], v[210:213], v[184:187], v[82:85]
	v_mfma_f32_16x16x32_bf16 v[70:73], v[200:203], v[192:195], v[70:73]
	v_mfma_f32_16x16x32_bf16 v[66:69], v[210:213], v[192:195], v[66:69]
	s_setprio 0
	s_barrier
	s_add_i32 s38, s74, s56
	v_lshl_add_u64 v[140:141], s[48:49], 0, v[0:1]
	s_mov_b32 m0, s38
	v_lshl_add_u64 v[214:215], s[48:49], 0, v[130:131]
	global_load_lds_dwordx4 v[140:141], off
	s_add_i32 m0, s38, 0x2000
	s_nop 0
	global_load_lds_dwordx4 v[214:215], off
	s_mov_b32 m0, s9
	v_lshl_add_u64 v[216:217], s[50:51], 0, v[134:135]
	global_load_lds_dwordx4 v[216:217], off
	v_lshl_add_u64 v[224:225], s[50:51], 0, v[132:133]
	s_mov_b32 m0, s60
	s_nop 0
	global_load_lds_dwordx4 v[224:225], off
	ds_read_b128 v[164:167], v145 offset:16384
	ds_read_b128 v[168:171], v145 offset:17408
	ds_read_b128 v[172:175], v145 offset:18432
	ds_read_b128 v[176:179], v145 offset:19456
	ds_read_b128 v[180:183], v145 offset:20480
	ds_read_b128 v[184:187], v145 offset:21504
	ds_read_b128 v[188:191], v145 offset:22528
	ds_read_b128 v[192:195], v145 offset:23552
	s_waitcnt vmcnt(6)
	s_waitcnt lgkmcnt(0)
	s_barrier
; #define PG8_STAGE(bufoff, gbase, voff) do { _Pragma("unroll") for (int _i = 0; _i < 2; ++_i) \
;         __builtin_amdgcn_global_load_lds((const unsigned*)((const char*)(gbase) + (voff)[_i]), (LAS unsigned*)(lds + (bufoff) + ldsw + _i * 8192), 16, 0, 0); } while (0)
; #define PG8_LDA(dst, b, h) do { _Pragma("unroll") for (int m = 0; m < 4; ++m) _Pragma("unroll") for (int k = 0; k < 2; ++k) dst[m][k] = *(const LAS bf16x8*)(lds + PG8_SA(b, h) + aoff + m * 2048 + k * 1024); } while (0)
; #define PG8_LDB(dst, b, h) do { _Pragma("unroll") for (int n = 0; n < 2; ++n) _Pragma("unroll") for (int k = 0; k < 2; ++k) dst[n][k] = *(const LAS bf16x8*)(lds + PG8_SB(b, h) + boff + n * 2048 + k * 1024); } while (0)
; #define PG8_MMA(ai, bj, At, Bt) do { __builtin_amdgcn_s_setprio(1); _Pragma("unroll") for (int m = 0; m < 4; ++m) _Pragma("unroll") for (int n = 0; n < 2; ++n) _Pragma("unroll") for (int k = 0; k < 2; ++k) \
;         acc[ai][bj][m][n] = __builtin_amdgcn_mfma_f32_16x16x32_bf16(Bt[n][k], At[m][k], acc[ai][bj][m][n], 0, 0, 0); __builtin_amdgcn_s_setprio(0); } while (0)
; #define PG8_WAIT_V(n) asm volatile("s_waitcnt vmcnt(" #n ")" ::: "memory")
; #define PG8_WAIT_L(n) asm volatile("s_waitcnt lgkmcnt(" #n ")" ::: "memory")
; #define PG8_BAR __builtin_amdgcn_s_barrier()
; #define PG8_SCHED __builtin_amdgcn_sched_barrier(0)
; template <class Epi, class Sched>
; __device__ __forceinline__ void gemm_phase(LAS unsigned char* lds, const Gemm g, const Sched& S, const Epi& E) {
;     ...
;             PG8_BAR; PG8_WAIT_L(0); PG8_MMA(1, 0, At, B0); PG8_BAR; PG8_SCHED;
;             PG8_STAGE(PG8_SB(0, 1), b2 + hstep, voffB);
;             PG8_WAIT_V(6); PG8_BAR; PG8_MMA(1, 1, At, B1); PG8_BAR;
;             PG8_LDB(B0, 1, 0); PG8_SCHED; PG8_LDA(At, 1, 0); PG8_STAGE(PG8_SA(0, 1), a2 + hstep, voffA);
;             PG8_WAIT_L(8); PG8_BAR; PG8_WAIT_L(0); PG8_MMA(0, 0, At, B0); PG8_BAR; PG8_SCHED;
;             PG8_LDB(B1, 1, 1); PG8_STAGE(PG8_SB(1, 0), b3, voffB);
;             PG8_BAR; PG8_WAIT_L(0); PG8_MMA(0, 1, At, B1); PG8_BAR;
	s_setprio 1
	v_mfma_f32_16x16x32_bf16 v[62:65], v[146:149], v[164:167], v[62:65]
	v_mfma_f32_16x16x32_bf16 v[58:61], v[154:157], v[164:167], v[58:61]
	v_mfma_f32_16x16x32_bf16 v[46:49], v[146:149], v[172:175], v[46:49]
	v_mfma_f32_16x16x32_bf16 v[42:45], v[154:157], v[172:175], v[42:45]
	v_mfma_f32_16x16x32_bf16 v[30:33], v[146:149], v[180:183], v[30:33]
	v_mfma_f32_16x16x32_bf16 v[26:29], v[154:157], v[180:183], v[26:29]
	v_mfma_f32_16x16x32_bf16 v[14:17], v[146:149], v[188:191], v[14:17]
	v_mfma_f32_16x16x32_bf16 v[10:13], v[154:157], v[188:191], v[10:13]
	v_mfma_f32_16x16x32_bf16 v[62:65], v[150:153], v[168:171], v[62:65]
	v_mfma_f32_16x16x32_bf16 v[58:61], v[160:163], v[168:171], v[58:61]
	v_mfma_f32_16x16x32_bf16 v[46:49], v[150:153], v[176:179], v[46:49]
	v_mfma_f32_16x16x32_bf16 v[42:45], v[160:163], v[176:179], v[42:45]
	v_mfma_f32_16x16x32_bf16 v[30:33], v[150:153], v[184:187], v[30:33]
	v_mfma_f32_16x16x32_bf16 v[26:29], v[160:163], v[184:187], v[26:29]
	v_mfma_f32_16x16x32_bf16 v[14:17], v[150:153], v[192:195], v[14:17]
	v_mfma_f32_16x16x32_bf16 v[10:13], v[160:163], v[192:195], v[10:13]
	s_add_u32 s38, s48, 0x80000
	s_addc_u32 s39, s49, 0
	s_add_i32 s74, s75, s56
	v_lshl_add_u64 v[146:147], s[38:39], 0, v[0:1]
	s_mov_b32 m0, s74
	s_nop 0
	global_load_lds_dwordx4 v[146:147], off
	v_lshl_add_u64 v[146:147], s[38:39], 0, v[130:131]
	s_add_i32 m0, s74, 0x2000
	s_nop 0
	global_load_lds_dwordx4 v[146:147], off
	v_mfma_f32_16x16x32_bf16 v[54:57], v[196:199], v[164:167], v[54:57]
	v_mfma_f32_16x16x32_bf16 v[50:53], v[204:207], v[164:167], v[50:53]
	v_mfma_f32_16x16x32_bf16 v[38:41], v[196:199], v[172:175], v[38:41]
	v_mfma_f32_16x16x32_bf16 v[34:37], v[204:207], v[172:175], v[34:37]
	v_mfma_f32_16x16x32_bf16 v[22:25], v[196:199], v[180:183], v[22:25]
	v_mfma_f32_16x16x32_bf16 v[18:21], v[204:207], v[180:183], v[18:21]
	v_mfma_f32_16x16x32_bf16 v[6:9], v[196:199], v[188:191], v[6:9]
	v_mfma_f32_16x16x32_bf16 v[2:5], v[204:207], v[188:191], v[2:5]
	v_mfma_f32_16x16x32_bf16 v[54:57], v[200:203], v[168:171], v[54:57]
	v_mfma_f32_16x16x32_bf16 v[50:53], v[210:213], v[168:171], v[50:53]
	v_mfma_f32_16x16x32_bf16 v[38:41], v[200:203], v[176:179], v[38:41]
	v_mfma_f32_16x16x32_bf16 v[34:37], v[210:213], v[176:179], v[34:37]
	v_mfma_f32_16x16x32_bf16 v[22:25], v[200:203], v[184:187], v[22:25]
	v_mfma_f32_16x16x32_bf16 v[18:21], v[210:213], v[184:187], v[18:21]
	v_mfma_f32_16x16x32_bf16 v[6:9], v[200:203], v[192:195], v[6:9]
	v_mfma_f32_16x16x32_bf16 v[2:5], v[210:213], v[192:195], v[2:5]
	s_setprio 0
	s_barrier
	s_add_u32 s38, s50, 0x80000
	s_addc_u32 s39, s51, 0
	s_mov_b32 m0, s61
	v_lshl_add_u64 v[196:197], s[38:39], 0, v[134:135]
	global_load_lds_dwordx4 v[196:197], off
	v_lshl_add_u64 v[196:197], s[38:39], 0, v[132:133]
	s_mov_b32 m0, s62
	s_nop 0
	global_load_lds_dwordx4 v[196:197], off
	s_add_i32 s74, 0, 0x18000
	v_add_u32_e32 v160, s74, v143
	ds_read_b128 v[146:149], v160
	ds_read_b128 v[150:153], v160 offset:1024
	ds_read_b128 v[154:157], v160 offset:2048
	ds_read_b128 v[160:163], v160 offset:3072
	ds_read_b128 v[164:167], v145 offset:32768
	ds_read_b128 v[168:171], v145 offset:33792
	ds_read_b128 v[172:175], v145 offset:34816
	ds_read_b128 v[176:179], v145 offset:35840
	ds_read_b128 v[180:183], v145 offset:36864
	ds_read_b128 v[184:187], v145 offset:37888
	ds_read_b128 v[188:191], v145 offset:38912
	ds_read_b128 v[192:195], v145 offset:39936
	s_add_i32 s50, 0, 0x1c000
	v_add_u32_e32 v210, s50, v143
	ds_read_b128 v[196:199], v210
	ds_read_b128 v[200:203], v210 offset:1024
	ds_read_b128 v[204:207], v210 offset:2048
	ds_read_b128 v[210:213], v210 offset:3072
	s_waitcnt vmcnt(8)
	s_waitcnt lgkmcnt(4)
	s_barrier
	s_waitcnt lgkmcnt(0)
	s_setprio 1
	v_mfma_f32_16x16x32_bf16 v[126:129], v[146:149], v[164:167], v[126:129]
	v_mfma_f32_16x16x32_bf16 v[122:125], v[154:157], v[164:167], v[122:125]
	v_mfma_f32_16x16x32_bf16 v[110:113], v[146:149], v[172:175], v[110:113]
	v_mfma_f32_16x16x32_bf16 v[106:109], v[154:157], v[172:175], v[106:109]
	v_mfma_f32_16x16x32_bf16 v[94:97], v[146:149], v[180:183], v[94:97]
	v_mfma_f32_16x16x32_bf16 v[90:93], v[154:157], v[180:183], v[90:93]
	v_mfma_f32_16x16x32_bf16 v[78:81], v[146:149], v[188:191], v[78:81]
	v_mfma_f32_16x16x32_bf16 v[74:77], v[154:157], v[188:191], v[74:77]
	v_mfma_f32_16x16x32_bf16 v[126:129], v[150:153], v[168:171], v[126:129]
	v_mfma_f32_16x16x32_bf16 v[122:125], v[160:163], v[168:171], v[122:125]
	v_mfma_f32_16x16x32_bf16 v[110:113], v[150:153], v[176:179], v[110:113]
	v_mfma_f32_16x16x32_bf16 v[106:109], v[160:163], v[176:179], v[106:109]
	v_mfma_f32_16x16x32_bf16 v[94:97], v[150:153], v[184:187], v[94:97]
	v_mfma_f32_16x16x32_bf16 v[90:93], v[160:163], v[184:187], v[90:93]
	v_mfma_f32_16x16x32_bf16 v[78:81], v[150:153], v[192:195], v[78:81]
	v_mfma_f32_16x16x32_bf16 v[74:77], v[160:163], v[192:195], v[74:77]
	v_mfma_f32_16x16x32_bf16 v[118:121], v[196:199], v[164:167], v[118:121]
	v_mfma_f32_16x16x32_bf16 v[114:117], v[204:207], v[164:167], v[114:117]
	v_mfma_f32_16x16x32_bf16 v[102:105], v[196:199], v[172:175], v[102:105]
	v_mfma_f32_16x16x32_bf16 v[98:101], v[204:207], v[172:175], v[98:101]
	v_mfma_f32_16x16x32_bf16 v[86:89], v[196:199], v[180:183], v[86:89]
	v_mfma_f32_16x16x32_bf16 v[82:85], v[204:207], v[180:183], v[82:85]
	v_mfma_f32_16x16x32_bf16 v[70:73], v[196:199], v[188:191], v[70:73]
	v_mfma_f32_16x16x32_bf16 v[66:69], v[204:207], v[188:191], v[66:69]
	v_mfma_f32_16x16x32_bf16 v[118:121], v[200:203], v[168:171], v[118:121]
	v_mfma_f32_16x16x32_bf16 v[114:117], v[210:213], v[168:171], v[114:117]
	v_mfma_f32_16x16x32_bf16 v[102:105], v[200:203], v[176:179], v[102:105]
	v_mfma_f32_16x16x32_bf16 v[98:101], v[210:213], v[176:179], v[98:101]
	v_mfma_f32_16x16x32_bf16 v[86:89], v[200:203], v[184:187], v[86:89]
	v_mfma_f32_16x16x32_bf16 v[82:85], v[210:213], v[184:187], v[82:85]
	v_mfma_f32_16x16x32_bf16 v[70:73], v[200:203], v[192:195], v[70:73]
	v_mfma_f32_16x16x32_bf16 v[66:69], v[210:213], v[192:195], v[66:69]
	s_setprio 0
	s_barrier
; __device__ __forceinline__ unsigned cvt_pk_bf16(float lo, float hi) { unsigned r; asm("v_cvt_pk_bf16_f32 %0, %1, %2" : "=v"(r) : "v"(lo), "v"(hi)); return r; }
; #define PG8_STAGE(bufoff, gbase, voff) do { _Pragma("unroll") for (int _i = 0; _i < 2; ++_i) \
;         __builtin_amdgcn_global_load_lds((const unsigned*)((const char*)(gbase) + (voff)[_i]), (LAS unsigned*)(lds + (bufoff) + ldsw + _i * 8192), 16, 0, 0); } while (0)
; #define PG8_LDA(dst, b, h) do { _Pragma("unroll") for (int m = 0; m < 4; ++m) _Pragma("unroll") for (int k = 0; k < 2; ++k) dst[m][k] = *(const LAS bf16x8*)(lds + PG8_SA(b, h) + aoff + m * 2048 + k * 1024); } while (0)
; #define PG8_MMA(ai, bj, At, Bt) do { __builtin_amdgcn_s_setprio(1); _Pragma("unroll") for (int m = 0; m < 4; ++m) _Pragma("unroll") for (int n = 0; n < 2; ++n) _Pragma("unroll") for (int k = 0; k < 2; ++k) \
;         acc[ai][bj][m][n] = __builtin_amdgcn_mfma_f32_16x16x32_bf16(Bt[n][k], At[m][k], acc[ai][bj][m][n], 0, 0, 0); __builtin_amdgcn_s_setprio(0); } while (0)
; #define PG8_WAIT_V(n) asm volatile("s_waitcnt vmcnt(" #n ")" ::: "memory")
; #define PG8_WAIT_L(n) asm volatile("s_waitcnt lgkmcnt(" #n ")" ::: "memory")
; #define PG8_BAR __builtin_amdgcn_s_barrier()
;     __device__ __forceinline__ void operator()(const f32x4 (&acc)[2][2][4][2], const Unit& u, int wr, int wc, int fr, int fq) const {
;     ...
;                 for (int bj = 0; bj < 2; ++bj) { f32x4 v0 = acc[ai][bj][m][0], v1 = acc[ai][bj][m][1];
;                     if (ACT == 1) {
; #pragma unroll
;                         for (int j = 0; j < 4; ++j) { float a = fmaxf(v0[j], 0.f), b = fmaxf(v1[j], 0.f); v0[j] = a * a; v1[j] = b * b; } }
;                     u32x4 w; w.x = cvt_pk_bf16(v0[0], v0[1]); w.y = cvt_pk_bf16(v0[2], v0[3]); w.z = cvt_pk_bf16(v1[0], v1[1]); w.w = cvt_pk_bf16(v1[2], v1[3]);
;                     if (ACT == 1) __builtin_nontemporal_store(w, (u32x4*)(rowp + bj * HALF));
; template <class Epi, class Sched>
; __device__ __forceinline__ void gemm_phase(LAS unsigned char* lds, const Gemm g, const Sched& S, const Epi& E) {
;     ...
;             PG8_LDA(At, 1, 1); PG8_STAGE(PG8_SA(1, 0), a3, voffA);
;             PG8_BAR; PG8_WAIT_L(0); PG8_MMA(1, 0, At, B0); PG8_BAR; PG8_SCHED;
;             PG8_STAGE(PG8_SB(1, 1), b3 + hstep, voffB);
;             PG8_WAIT_V(6); PG8_BAR; PG8_MMA(1, 1, At, B1); PG8_BAR;
;         }
	s_add_i32 s38, s74, s56
	v_lshl_add_u64 v[140:141], v[140:141], 0, s[36:37]
	s_mov_b32 m0, s38
	s_nop 0
	global_load_lds_dwordx4 v[140:141], off
	v_lshl_add_u64 v[140:141], v[214:215], 0, s[36:37]
	s_add_i32 m0, s38, 0x2000
	s_nop 0
	global_load_lds_dwordx4 v[140:141], off
	s_mov_b32 m0, s64
	v_lshl_add_u64 v[140:141], v[216:217], 0, s[36:37]
	global_load_lds_dwordx4 v[140:141], off
	v_lshl_add_u64 v[140:141], v[224:225], 0, s[36:37]
	s_mov_b32 m0, s65
	s_nop 0
	global_load_lds_dwordx4 v[140:141], off
	ds_read_b128 v[164:167], v145 offset:49152
	ds_read_b128 v[168:171], v145 offset:50176
	ds_read_b128 v[172:175], v145 offset:51200
	ds_read_b128 v[176:179], v145 offset:52224
	ds_read_b128 v[180:183], v145 offset:53248
	ds_read_b128 v[184:187], v145 offset:54272
	ds_read_b128 v[188:191], v145 offset:55296
	ds_read_b128 v[192:195], v145 offset:56320
	s_waitcnt vmcnt(6)
	s_waitcnt lgkmcnt(0)
	s_barrier
	s_setprio 1
	v_mfma_f32_16x16x32_bf16 v[62:65], v[146:149], v[164:167], v[62:65]
	v_mfma_f32_16x16x32_bf16 v[58:61], v[154:157], v[164:167], v[58:61]
	v_mfma_f32_16x16x32_bf16 v[46:49], v[146:149], v[172:175], v[46:49]
	v_mfma_f32_16x16x32_bf16 v[42:45], v[154:157], v[172:175], v[42:45]
	v_mfma_f32_16x16x32_bf16 v[30:33], v[146:149], v[180:183], v[30:33]
	v_mfma_f32_16x16x32_bf16 v[26:29], v[154:157], v[180:183], v[26:29]
	v_mfma_f32_16x16x32_bf16 v[14:17], v[146:149], v[188:191], v[14:17]
	v_mfma_f32_16x16x32_bf16 v[10:13], v[154:157], v[188:191], v[10:13]
	v_mfma_f32_16x16x32_bf16 v[62:65], v[150:153], v[168:171], v[62:65]
	v_mfma_f32_16x16x32_bf16 v[58:61], v[160:163], v[168:171], v[58:61]
	v_mfma_f32_16x16x32_bf16 v[46:49], v[150:153], v[176:179], v[46:49]
	v_mfma_f32_16x16x32_bf16 v[42:45], v[160:163], v[176:179], v[42:45]
	v_mfma_f32_16x16x32_bf16 v[30:33], v[150:153], v[184:187], v[30:33]
	v_mfma_f32_16x16x32_bf16 v[26:29], v[160:163], v[184:187], v[26:29]
	v_mfma_f32_16x16x32_bf16 v[14:17], v[150:153], v[192:195], v[14:17]
	v_mfma_f32_16x16x32_bf16 v[10:13], v[160:163], v[192:195], v[10:13]
	s_add_u32 s38, s48, 0x80080
	s_addc_u32 s39, s49, 0
	s_add_i32 s48, s50, s56
	v_lshl_add_u64 v[140:141], s[38:39], 0, v[0:1]
	s_mov_b32 m0, s48
	s_nop 0
	global_load_lds_dwordx4 v[140:141], off
	v_lshl_add_u64 v[140:141], s[38:39], 0, v[130:131]
	s_add_i32 m0, s48, 0x2000
	s_nop 0
	global_load_lds_dwordx4 v[140:141], off
	v_mfma_f32_16x16x32_bf16 v[54:57], v[196:199], v[164:167], v[54:57]
	v_mfma_f32_16x16x32_bf16 v[50:53], v[204:207], v[164:167], v[50:53]
	v_mfma_f32_16x16x32_bf16 v[38:41], v[196:199], v[172:175], v[38:41]
	v_mfma_f32_16x16x32_bf16 v[34:37], v[204:207], v[172:175], v[34:37]
	v_mfma_f32_16x16x32_bf16 v[22:25], v[196:199], v[180:183], v[22:25]
	v_mfma_f32_16x16x32_bf16 v[18:21], v[204:207], v[180:183], v[18:21]
	v_mfma_f32_16x16x32_bf16 v[6:9], v[196:199], v[188:191], v[6:9]
	v_mfma_f32_16x16x32_bf16 v[2:5], v[204:207], v[188:191], v[2:5]
	v_mfma_f32_16x16x32_bf16 v[54:57], v[200:203], v[168:171], v[54:57]
	v_mfma_f32_16x16x32_bf16 v[50:53], v[210:213], v[168:171], v[50:53]
	v_mfma_f32_16x16x32_bf16 v[38:41], v[200:203], v[176:179], v[38:41]
	v_mfma_f32_16x16x32_bf16 v[34:37], v[210:213], v[176:179], v[34:37]
	v_mfma_f32_16x16x32_bf16 v[22:25], v[200:203], v[184:187], v[22:25]
	v_mfma_f32_16x16x32_bf16 v[18:21], v[210:213], v[184:187], v[18:21]
	v_mfma_f32_16x16x32_bf16 v[6:9], v[200:203], v[192:195], v[6:9]
	v_mfma_f32_16x16x32_bf16 v[2:5], v[210:213], v[192:195], v[2:5]
	s_setprio 0
	s_add_i32 s73, s73, 2
	s_add_u32 s71, s71, 0x100
	s_addc_u32 s72, s72, 0
	s_add_u32 s46, s46, 0x100
	s_addc_u32 s47, s47, 0
	s_cmp_gt_u32 s73, 29
	s_barrier
	s_cbranch_scc0 .LBB0_73
	v_lshl_add_u32 v146, s8, 8, v142
	v_max_f32_e32 v122, v122, v122
	v_ashrrev_i32_e32 v147, 31, v146
	v_max_f32_e32 v122, 0, v122
	v_max_f32_e32 v123, v123, v123
	v_max_f32_e32 v124, v124, v124
	v_lshl_or_b32 v140, s68, 8, v144
	v_lshlrev_b64 v[148:149], 14, v[146:147]
	v_mul_f32_e32 v147, v122, v122
	v_max_f32_e32 v122, v127, v127
	v_max_f32_e32 v123, 0, v123
	v_max_f32_e32 v124, 0, v124
	v_ashrrev_i32_e32 v141, 31, v140
	v_max_f32_e32 v126, v126, v126
	v_max_f32_e32 v122, 0, v122
	v_mul_f32_e32 v127, v123, v123
	v_max_f32_e32 v123, v128, v128
	v_mul_f32_e32 v128, v124, v124
	v_max_f32_e32 v124, v129, v129
	v_max_f32_e32 v125, v125, v125
	v_lshl_add_u64 v[148:149], s[24:25], 0, v[148:149]
	v_lshlrev_b64 v[150:151], 1, v[140:141]
	v_max_f32_e32 v126, 0, v126
	v_mul_f32_e32 v122, v122, v122
	v_max_f32_e32 v123, 0, v123
	v_max_f32_e32 v124, 0, v124
	v_max_f32_e32 v125, 0, v125
	v_max_f32_e32 v114, v114, v114
	v_lshl_add_u64 v[140:141], v[148:149], 0, v[150:151]
	v_mul_f32_e32 v126, v126, v126
	v_mul_f32_e32 v123, v123, v123
	v_mul_f32_e32 v124, v124, v124
	v_mul_f32_e32 v125, v125, v125
	v_cvt_pk_bf16_f32 v122, v126, v122
	v_max_f32_e32 v114, 0, v114
	v_max_f32_e32 v115, v115, v115
	v_max_f32_e32 v116, v116, v116
	v_cvt_pk_bf16_f32 v123, v123, v124
	v_cvt_pk_bf16_f32 v124, v147, v127
	v_cvt_pk_bf16_f32 v125, v128, v125
	global_store_dwordx4 v[140:141], v[122:125], off nt
	v_max_f32_e32 v115, 0, v115
	v_max_f32_e32 v116, 0, v116
	v_mul_f32_e32 v122, v114, v114
	v_max_f32_e32 v114, v119, v119
	v_max_f32_e32 v118, v118, v118
	v_max_f32_e32 v114, 0, v114
	v_mul_f32_e32 v119, v115, v115
	v_max_f32_e32 v115, v120, v120
	v_mul_f32_e32 v120, v116, v116
	v_max_f32_e32 v116, v121, v121
	v_max_f32_e32 v117, v117, v117
	v_max_f32_e32 v118, 0, v118
	v_mul_f32_e32 v114, v114, v114
	v_max_f32_e32 v115, 0, v115
	v_max_f32_e32 v116, 0, v116
	v_max_f32_e32 v117, 0, v117
	v_mul_f32_e32 v118, v118, v118
	v_mul_f32_e32 v115, v115, v115
	v_mul_f32_e32 v116, v116, v116
	v_mul_f32_e32 v117, v117, v117
; __device__ __forceinline__ unsigned cvt_pk_bf16(float lo, float hi) { unsigned r; asm("v_cvt_pk_bf16_f32 %0, %1, %2" : "=v"(r) : "v"(lo), "v"(hi)); return r; }
;     __device__ __forceinline__ void operator()(const f32x4 (&acc)[2][2][4][2], const Unit& u, int wr, int wc, int fr, int fq) const {
;     ...
;             for (int m = 0; m < 4; ++m) { bf16_t* rowp = O + (size_t)(row0 + ai * HALF + m * 16) * ldc + col0;
; #pragma unroll
;                 for (int bj = 0; bj < 2; ++bj) { f32x4 v0 = acc[ai][bj][m][0], v1 = acc[ai][bj][m][1];
;                     if (ACT == 1) {
; #pragma unroll
;                         for (int j = 0; j < 4; ++j) { float a = fmaxf(v0[j], 0.f), b = fmaxf(v1[j], 0.f); v0[j] = a * a; v1[j] = b * b; } }
;                     u32x4 w; w.x = cvt_pk_bf16(v0[0], v0[1]); w.y = cvt_pk_bf16(v0[2], v0[3]); w.z = cvt_pk_bf16(v1[0], v1[1]); w.w = cvt_pk_bf16(v1[2], v1[3]);
;                     if (ACT == 1) __builtin_nontemporal_store(w, (u32x4*)(rowp + bj * HALF));
;                     else *(u32x4*)(rowp + bj * HALF) = w; } }
	v_cvt_pk_bf16_f32 v114, v118, v114
	v_max_f32_e32 v106, v106, v106
	v_cvt_pk_bf16_f32 v115, v115, v116
	v_cvt_pk_bf16_f32 v116, v122, v119
	v_cvt_pk_bf16_f32 v117, v120, v117
	global_store_dwordx4 v[140:141], v[114:117], off offset:256 nt
	v_max_f32_e32 v106, 0, v106
	v_max_f32_e32 v107, v107, v107
	v_or_b32_e32 v114, 16, v146
	v_max_f32_e32 v108, v108, v108
	v_ashrrev_i32_e32 v115, 31, v114
	v_mul_f32_e32 v116, v106, v106
	v_max_f32_e32 v106, v111, v111
	v_max_f32_e32 v107, 0, v107
	v_max_f32_e32 v108, 0, v108
	v_lshlrev_b64 v[114:115], 14, v[114:115]
	v_max_f32_e32 v110, v110, v110
	v_max_f32_e32 v106, 0, v106
	v_mul_f32_e32 v111, v107, v107
	v_max_f32_e32 v107, v112, v112
	v_mul_f32_e32 v112, v108, v108
	v_max_f32_e32 v108, v113, v113
	v_max_f32_e32 v109, v109, v109
	v_lshl_add_u64 v[114:115], s[24:25], 0, v[114:115]
	v_max_f32_e32 v110, 0, v110
	v_mul_f32_e32 v106, v106, v106
	v_max_f32_e32 v107, 0, v107
	v_max_f32_e32 v108, 0, v108
	v_max_f32_e32 v109, 0, v109
	v_max_f32_e32 v98, v98, v98
	v_lshl_add_u64 v[114:115], v[114:115], 0, v[150:151]
	v_mul_f32_e32 v110, v110, v110
	v_mul_f32_e32 v107, v107, v107
	v_mul_f32_e32 v108, v108, v108
	v_mul_f32_e32 v109, v109, v109
	v_cvt_pk_bf16_f32 v106, v110, v106
	v_max_f32_e32 v98, 0, v98
	v_max_f32_e32 v99, v99, v99
	v_max_f32_e32 v100, v100, v100
	v_cvt_pk_bf16_f32 v107, v107, v108
	v_cvt_pk_bf16_f32 v108, v116, v111
	v_cvt_pk_bf16_f32 v109, v112, v109
	global_store_dwordx4 v[114:115], v[106:109], off nt
	v_max_f32_e32 v99, 0, v99
	v_max_f32_e32 v100, 0, v100
	v_mul_f32_e32 v106, v98, v98
	v_max_f32_e32 v98, v103, v103
	v_max_f32_e32 v102, v102, v102
	v_max_f32_e32 v98, 0, v98
	v_mul_f32_e32 v103, v99, v99
	v_max_f32_e32 v99, v104, v104
	v_mul_f32_e32 v104, v100, v100
	v_max_f32_e32 v100, v105, v105
	v_max_f32_e32 v101, v101, v101
	v_max_f32_e32 v102, 0, v102
	v_mul_f32_e32 v98, v98, v98
	v_max_f32_e32 v99, 0, v99
	v_max_f32_e32 v100, 0, v100
	v_max_f32_e32 v101, 0, v101
	v_mul_f32_e32 v102, v102, v102
	v_mul_f32_e32 v99, v99, v99
	v_mul_f32_e32 v100, v100, v100
	v_mul_f32_e32 v101, v101, v101
	v_cvt_pk_bf16_f32 v98, v102, v98
	v_max_f32_e32 v90, v90, v90
	v_cvt_pk_bf16_f32 v99, v99, v100
	v_cvt_pk_bf16_f32 v100, v106, v103
	v_cvt_pk_bf16_f32 v101, v104, v101
	global_store_dwordx4 v[114:115], v[98:101], off offset:256 nt
	v_max_f32_e32 v90, 0, v90
	v_max_f32_e32 v91, v91, v91
	v_or_b32_e32 v98, 32, v146
	v_max_f32_e32 v92, v92, v92
	v_ashrrev_i32_e32 v99, 31, v98
	v_mul_f32_e32 v100, v90, v90
	v_max_f32_e32 v90, v95, v95
	v_max_f32_e32 v91, 0, v91
	v_max_f32_e32 v92, 0, v92
	v_lshlrev_b64 v[98:99], 14, v[98:99]
	v_max_f32_e32 v94, v94, v94
	v_max_f32_e32 v90, 0, v90
	v_mul_f32_e32 v95, v91, v91
	v_max_f32_e32 v91, v96, v96
	v_mul_f32_e32 v96, v92, v92
	v_max_f32_e32 v92, v97, v97
	v_max_f32_e32 v93, v93, v93
	v_lshl_add_u64 v[98:99], s[24:25], 0, v[98:99]
	v_max_f32_e32 v94, 0, v94
	v_mul_f32_e32 v90, v90, v90
	v_max_f32_e32 v91, 0, v91
	v_max_f32_e32 v92, 0, v92
	v_max_f32_e32 v93, 0, v93
	v_max_f32_e32 v82, v82, v82
	v_lshl_add_u64 v[98:99], v[98:99], 0, v[150:151]
	v_mul_f32_e32 v94, v94, v94
	v_mul_f32_e32 v91, v91, v91
	v_mul_f32_e32 v92, v92, v92
	v_mul_f32_e32 v93, v93, v93
	v_cvt_pk_bf16_f32 v90, v94, v90
	v_max_f32_e32 v82, 0, v82
	v_max_f32_e32 v83, v83, v83
	v_max_f32_e32 v84, v84, v84
	v_cvt_pk_bf16_f32 v91, v91, v92
	v_cvt_pk_bf16_f32 v92, v100, v95
	v_cvt_pk_bf16_f32 v93, v96, v93
	global_store_dwordx4 v[98:99], v[90:93], off nt
	v_max_f32_e32 v83, 0, v83
	v_max_f32_e32 v84, 0, v84
	v_mul_f32_e32 v90, v82, v82
	v_max_f32_e32 v82, v87, v87
	v_max_f32_e32 v86, v86, v86
	v_max_f32_e32 v82, 0, v82
	v_mul_f32_e32 v87, v83, v83
	v_max_f32_e32 v83, v88, v88
	v_mul_f32_e32 v88, v84, v84
	v_max_f32_e32 v84, v89, v89
	v_max_f32_e32 v85, v85, v85
	v_max_f32_e32 v86, 0, v86
	v_mul_f32_e32 v82, v82, v82
	v_max_f32_e32 v83, 0, v83
	v_max_f32_e32 v84, 0, v84
	v_max_f32_e32 v85, 0, v85
	v_mul_f32_e32 v86, v86, v86
	v_mul_f32_e32 v83, v83, v83
	v_mul_f32_e32 v84, v84, v84
	v_mul_f32_e32 v85, v85, v85
	v_cvt_pk_bf16_f32 v82, v86, v82
	v_max_f32_e32 v74, v74, v74
	v_cvt_pk_bf16_f32 v83, v83, v84
	v_cvt_pk_bf16_f32 v84, v90, v87
	v_cvt_pk_bf16_f32 v85, v88, v85
	global_store_dwordx4 v[98:99], v[82:85], off offset:256 nt
	v_max_f32_e32 v74, 0, v74
	v_max_f32_e32 v75, v75, v75
	v_or_b32_e32 v82, 48, v146
	v_max_f32_e32 v76, v76, v76
	v_ashrrev_i32_e32 v83, 31, v82
	v_mul_f32_e32 v84, v74, v74
	v_max_f32_e32 v74, v79, v79
	v_max_f32_e32 v75, 0, v75
	v_max_f32_e32 v76, 0, v76
	v_lshlrev_b64 v[82:83], 14, v[82:83]
	v_max_f32_e32 v78, v78, v78
	v_max_f32_e32 v74, 0, v74
	v_mul_f32_e32 v79, v75, v75
	v_max_f32_e32 v75, v80, v80
	v_mul_f32_e32 v80, v76, v76
	v_max_f32_e32 v76, v81, v81
	v_max_f32_e32 v77, v77, v77
	v_lshl_add_u64 v[82:83], s[24:25], 0, v[82:83]
	v_max_f32_e32 v78, 0, v78
	v_mul_f32_e32 v74, v74, v74
	v_max_f32_e32 v75, 0, v75
	v_max_f32_e32 v76, 0, v76
	v_max_f32_e32 v77, 0, v77
	v_max_f32_e32 v66, v66, v66
	v_max_f32_e32 v67, v67, v67
	v_max_f32_e32 v68, v68, v68
	v_lshl_add_u64 v[82:83], v[82:83], 0, v[150:151]
	v_mul_f32_e32 v78, v78, v78
	v_mul_f32_e32 v75, v75, v75
	v_mul_f32_e32 v76, v76, v76
	v_mul_f32_e32 v77, v77, v77
	v_cvt_pk_bf16_f32 v74, v78, v74
	v_max_f32_e32 v66, 0, v66
	v_max_f32_e32 v67, 0, v67
	v_max_f32_e32 v68, 0, v68
	v_cvt_pk_bf16_f32 v75, v75, v76
	v_cvt_pk_bf16_f32 v76, v84, v79
	v_cvt_pk_bf16_f32 v77, v80, v77
	global_store_dwordx4 v[82:83], v[74:77], off nt
	v_max_f32_e32 v69, v69, v69
	v_max_f32_e32 v70, v70, v70
	v_mul_f32_e32 v74, v66, v66
	v_max_f32_e32 v66, v71, v71
	v_mul_f32_e32 v71, v67, v67
	v_max_f32_e32 v67, v72, v72
	v_mul_f32_e32 v72, v68, v68
; __device__ __forceinline__ unsigned cvt_pk_bf16(float lo, float hi) { unsigned r; asm("v_cvt_pk_bf16_f32 %0, %1, %2" : "=v"(r) : "v"(lo), "v"(hi)); return r; }
;     __device__ __forceinline__ void operator()(const f32x4 (&acc)[2][2][4][2], const Unit& u, int wr, int wc, int fr, int fq) const {
;     ...
;             for (int m = 0; m < 4; ++m) { bf16_t* rowp = O + (size_t)(row0 + ai * HALF + m * 16) * ldc + col0;
; #pragma unroll
;                 for (int bj = 0; bj < 2; ++bj) { f32x4 v0 = acc[ai][bj][m][0], v1 = acc[ai][bj][m][1];
;                     if (ACT == 1) {
; #pragma unroll
;                         for (int j = 0; j < 4; ++j) { float a = fmaxf(v0[j], 0.f), b = fmaxf(v1[j], 0.f); v0[j] = a * a; v1[j] = b * b; } }
;                     u32x4 w; w.x = cvt_pk_bf16(v0[0], v0[1]); w.y = cvt_pk_bf16(v0[2], v0[3]); w.z = cvt_pk_bf16(v1[0], v1[1]); w.w = cvt_pk_bf16(v1[2], v1[3]);
;                     if (ACT == 1) __builtin_nontemporal_store(w, (u32x4*)(rowp + bj * HALF));
;                     else *(u32x4*)(rowp + bj * HALF) = w; } }
	v_max_f32_e32 v68, v73, v73
	v_max_f32_e32 v67, 0, v67
	v_max_f32_e32 v68, 0, v68
	v_max_f32_e32 v66, 0, v66
	v_mul_f32_e32 v67, v67, v67
	v_max_f32_e32 v69, 0, v69
	v_mul_f32_e32 v68, v68, v68
	v_max_f32_e32 v58, v58, v58
	v_max_f32_e32 v70, 0, v70
	v_mul_f32_e32 v66, v66, v66
	v_mul_f32_e32 v69, v69, v69
	v_cvt_pk_bf16_f32 v67, v67, v68
	v_cvt_pk_bf16_f32 v68, v74, v71
	v_max_f32_e32 v58, 0, v58
	v_max_f32_e32 v59, v59, v59
	v_max_f32_e32 v60, v60, v60
	v_mul_f32_e32 v70, v70, v70
	v_cvt_pk_bf16_f32 v66, v70, v66
	v_cvt_pk_bf16_f32 v69, v72, v69
	global_store_dwordx4 v[82:83], v[66:69], off offset:256 nt
	v_max_f32_e32 v62, v62, v62
	v_max_f32_e32 v59, 0, v59
	v_mul_f32_e32 v68, v58, v58
	v_max_f32_e32 v58, v63, v63
	v_max_f32_e32 v60, 0, v60
	v_max_f32_e32 v62, 0, v62
	v_max_f32_e32 v58, 0, v58
	v_mul_f32_e32 v63, v59, v59
	v_max_f32_e32 v59, v64, v64
	v_mul_f32_e32 v64, v60, v60
	v_max_f32_e32 v60, v65, v65
	v_mul_f32_e32 v62, v62, v62
	v_mul_f32_e32 v58, v58, v58
	v_max_f32_e32 v59, 0, v59
	v_max_f32_e32 v60, 0, v60
	v_max_f32_e32 v61, v61, v61
	s_mov_b32 s8, 0x200000
	v_mul_f32_e32 v59, v59, v59
	v_max_f32_e32 v61, 0, v61
	v_mul_f32_e32 v60, v60, v60
	v_cvt_pk_bf16_f32 v58, v62, v58
	v_add_co_u32_e32 v62, vcc, s8, v140
	v_max_f32_e32 v50, v50, v50
	v_max_f32_e32 v51, v51, v51
	v_max_f32_e32 v52, v52, v52
	v_mul_f32_e32 v61, v61, v61
	v_cvt_pk_bf16_f32 v59, v59, v60
	v_cvt_pk_bf16_f32 v60, v68, v63
	v_addc_co_u32_e32 v63, vcc, 0, v141, vcc
	v_max_f32_e32 v50, 0, v50
	v_max_f32_e32 v51, 0, v51
	v_max_f32_e32 v52, 0, v52
	v_cvt_pk_bf16_f32 v61, v64, v61
	global_store_dwordx4 v[62:63], v[58:61], off nt
	v_max_f32_e32 v53, v53, v53
	s_mov_b64 s[38:39], 0x200000
	v_mul_f32_e32 v58, v50, v50
	v_max_f32_e32 v50, v55, v55
	v_mul_f32_e32 v55, v51, v51
	v_max_f32_e32 v51, v56, v56
	v_mul_f32_e32 v56, v52, v52
	v_max_f32_e32 v52, v57, v57
	v_max_f32_e32 v51, 0, v51
	v_max_f32_e32 v52, 0, v52
	v_max_f32_e32 v54, v54, v54
	v_max_f32_e32 v50, 0, v50
	v_mul_f32_e32 v51, v51, v51
	v_max_f32_e32 v53, 0, v53
	v_mul_f32_e32 v52, v52, v52
	v_max_f32_e32 v42, v42, v42
	v_lshl_add_u64 v[66:67], v[140:141], 0, s[38:39]
	v_max_f32_e32 v54, 0, v54
	v_mul_f32_e32 v50, v50, v50
	v_mul_f32_e32 v53, v53, v53
	v_cvt_pk_bf16_f32 v51, v51, v52
	v_cvt_pk_bf16_f32 v52, v58, v55
	v_max_f32_e32 v42, 0, v42
	v_max_f32_e32 v43, v43, v43
	v_max_f32_e32 v44, v44, v44
	v_mul_f32_e32 v54, v54, v54
	v_cvt_pk_bf16_f32 v50, v54, v50
	v_cvt_pk_bf16_f32 v53, v56, v53
	global_store_dwordx4 v[66:67], v[50:53], off offset:256 nt
	v_max_f32_e32 v46, v46, v46
	v_max_f32_e32 v43, 0, v43
	v_mul_f32_e32 v52, v42, v42
	v_max_f32_e32 v42, v47, v47
	v_max_f32_e32 v44, 0, v44
	v_max_f32_e32 v46, 0, v46
	v_max_f32_e32 v42, 0, v42
	v_mul_f32_e32 v47, v43, v43
	v_max_f32_e32 v43, v48, v48
	v_mul_f32_e32 v48, v44, v44
	v_max_f32_e32 v44, v49, v49
	v_mul_f32_e32 v46, v46, v46
	v_mul_f32_e32 v42, v42, v42
	v_max_f32_e32 v43, 0, v43
	v_max_f32_e32 v44, 0, v44
	v_max_f32_e32 v45, v45, v45
	s_mov_b32 s8, 0x240000
	v_mul_f32_e32 v43, v43, v43
	v_max_f32_e32 v45, 0, v45
	v_mul_f32_e32 v44, v44, v44
	v_cvt_pk_bf16_f32 v42, v46, v42
	v_add_co_u32_e32 v46, vcc, s8, v140
	v_max_f32_e32 v34, v34, v34
	v_max_f32_e32 v35, v35, v35
	v_max_f32_e32 v36, v36, v36
	v_mul_f32_e32 v45, v45, v45
	v_cvt_pk_bf16_f32 v43, v43, v44
	v_cvt_pk_bf16_f32 v44, v52, v47
	v_addc_co_u32_e32 v47, vcc, 0, v141, vcc
	v_max_f32_e32 v34, 0, v34
	v_max_f32_e32 v35, 0, v35
	v_max_f32_e32 v36, 0, v36
	v_cvt_pk_bf16_f32 v45, v48, v45
	global_store_dwordx4 v[46:47], v[42:45], off nt
	v_max_f32_e32 v37, v37, v37
	s_mov_b64 s[38:39], 0x240000
	v_mul_f32_e32 v42, v34, v34
	v_max_f32_e32 v34, v39, v39
	v_mul_f32_e32 v39, v35, v35
	v_max_f32_e32 v35, v40, v40
	v_mul_f32_e32 v40, v36, v36
	v_max_f32_e32 v36, v41, v41
	v_max_f32_e32 v35, 0, v35
	v_max_f32_e32 v36, 0, v36
	v_max_f32_e32 v38, v38, v38
	v_max_f32_e32 v34, 0, v34
	v_mul_f32_e32 v35, v35, v35
	v_max_f32_e32 v37, 0, v37
	v_mul_f32_e32 v36, v36, v36
	v_max_f32_e32 v26, v26, v26
	v_lshl_add_u64 v[50:51], v[140:141], 0, s[38:39]
	v_max_f32_e32 v38, 0, v38
	v_mul_f32_e32 v34, v34, v34
	v_mul_f32_e32 v37, v37, v37
	v_cvt_pk_bf16_f32 v35, v35, v36
; __device__ __forceinline__ unsigned cvt_pk_bf16(float lo, float hi) { unsigned r; asm("v_cvt_pk_bf16_f32 %0, %1, %2" : "=v"(r) : "v"(lo), "v"(hi)); return r; }
;     __device__ __forceinline__ void operator()(const f32x4 (&acc)[2][2][4][2], const Unit& u, int wr, int wc, int fr, int fq) const {
;     ...
;             for (int m = 0; m < 4; ++m) { bf16_t* rowp = O + (size_t)(row0 + ai * HALF + m * 16) * ldc + col0;
; #pragma unroll
;                 for (int bj = 0; bj < 2; ++bj) { f32x4 v0 = acc[ai][bj][m][0], v1 = acc[ai][bj][m][1];
;                     if (ACT == 1) {
; #pragma unroll
;                         for (int j = 0; j < 4; ++j) { float a = fmaxf(v0[j], 0.f), b = fmaxf(v1[j], 0.f); v0[j] = a * a; v1[j] = b * b; } }
;                     u32x4 w; w.x = cvt_pk_bf16(v0[0], v0[1]); w.y = cvt_pk_bf16(v0[2], v0[3]); w.z = cvt_pk_bf16(v1[0], v1[1]); w.w = cvt_pk_bf16(v1[2], v1[3]);
;                     if (ACT == 1) __builtin_nontemporal_store(w, (u32x4*)(rowp + bj * HALF));
;                     else *(u32x4*)(rowp + bj * HALF) = w; } }
	v_cvt_pk_bf16_f32 v36, v42, v39
	v_max_f32_e32 v26, 0, v26
	v_max_f32_e32 v27, v27, v27
	v_max_f32_e32 v28, v28, v28
	v_mul_f32_e32 v38, v38, v38
	v_cvt_pk_bf16_f32 v34, v38, v34
	v_cvt_pk_bf16_f32 v37, v40, v37
	global_store_dwordx4 v[50:51], v[34:37], off offset:256 nt
	v_max_f32_e32 v30, v30, v30
	v_max_f32_e32 v27, 0, v27
	v_mul_f32_e32 v36, v26, v26
	v_max_f32_e32 v26, v31, v31
	v_max_f32_e32 v28, 0, v28
	v_max_f32_e32 v30, 0, v30
	v_max_f32_e32 v26, 0, v26
	v_mul_f32_e32 v31, v27, v27
	v_max_f32_e32 v27, v32, v32
	v_mul_f32_e32 v32, v28, v28
	v_max_f32_e32 v28, v33, v33
	v_mul_f32_e32 v30, v30, v30
	v_mul_f32_e32 v26, v26, v26
	v_max_f32_e32 v27, 0, v27
	v_max_f32_e32 v28, 0, v28
	v_max_f32_e32 v29, v29, v29
	s_mov_b32 s8, 0x280000
	v_mul_f32_e32 v27, v27, v27
	v_max_f32_e32 v29, 0, v29
	v_mul_f32_e32 v28, v28, v28
	v_cvt_pk_bf16_f32 v26, v30, v26
	v_add_co_u32_e32 v30, vcc, s8, v140
	v_max_f32_e32 v18, v18, v18
	v_max_f32_e32 v19, v19, v19
	v_max_f32_e32 v20, v20, v20
	v_mul_f32_e32 v29, v29, v29
	v_cvt_pk_bf16_f32 v27, v27, v28
	v_cvt_pk_bf16_f32 v28, v36, v31
	v_addc_co_u32_e32 v31, vcc, 0, v141, vcc
	v_max_f32_e32 v18, 0, v18
	v_max_f32_e32 v19, 0, v19
	v_max_f32_e32 v20, 0, v20
	v_cvt_pk_bf16_f32 v29, v32, v29
	global_store_dwordx4 v[30:31], v[26:29], off nt
	v_max_f32_e32 v21, v21, v21
	s_mov_b64 s[38:39], 0x280000
	v_mul_f32_e32 v26, v18, v18
	v_max_f32_e32 v18, v23, v23
	v_mul_f32_e32 v23, v19, v19
	v_max_f32_e32 v19, v24, v24
	v_mul_f32_e32 v24, v20, v20
	v_max_f32_e32 v20, v25, v25
	v_max_f32_e32 v19, 0, v19
	v_max_f32_e32 v20, 0, v20
	v_max_f32_e32 v22, v22, v22
	v_max_f32_e32 v18, 0, v18
	v_mul_f32_e32 v19, v19, v19
	v_max_f32_e32 v21, 0, v21
	v_mul_f32_e32 v20, v20, v20
	v_max_f32_e32 v10, v10, v10
	v_lshl_add_u64 v[34:35], v[140:141], 0, s[38:39]
	v_max_f32_e32 v22, 0, v22
	v_mul_f32_e32 v18, v18, v18
	v_mul_f32_e32 v21, v21, v21
	v_cvt_pk_bf16_f32 v19, v19, v20
	v_cvt_pk_bf16_f32 v20, v26, v23
	v_max_f32_e32 v10, 0, v10
	v_max_f32_e32 v11, v11, v11
	v_max_f32_e32 v12, v12, v12
	v_mul_f32_e32 v22, v22, v22
	v_cvt_pk_bf16_f32 v18, v22, v18
	v_cvt_pk_bf16_f32 v21, v24, v21
	global_store_dwordx4 v[34:35], v[18:21], off offset:256 nt
	v_max_f32_e32 v14, v14, v14
	v_max_f32_e32 v11, 0, v11
	v_mul_f32_e32 v20, v10, v10
	v_max_f32_e32 v10, v15, v15
	v_max_f32_e32 v12, 0, v12
	v_max_f32_e32 v14, 0, v14
	v_max_f32_e32 v10, 0, v10
	v_mul_f32_e32 v15, v11, v11
	v_max_f32_e32 v11, v16, v16
	v_mul_f32_e32 v16, v12, v12
	v_max_f32_e32 v12, v17, v17
	v_mul_f32_e32 v14, v14, v14
	v_mul_f32_e32 v10, v10, v10
	v_max_f32_e32 v11, 0, v11
	v_max_f32_e32 v12, 0, v12
	v_max_f32_e32 v13, v13, v13
	s_mov_b32 s8, 0x2c0000
	v_mul_f32_e32 v11, v11, v11
	v_max_f32_e32 v13, 0, v13
	v_mul_f32_e32 v12, v12, v12
	v_cvt_pk_bf16_f32 v10, v14, v10
	v_add_co_u32_e32 v14, vcc, s8, v140
	v_max_f32_e32 v2, v2, v2
	v_max_f32_e32 v3, v3, v3
	v_max_f32_e32 v4, v4, v4
	v_mul_f32_e32 v13, v13, v13
	v_cvt_pk_bf16_f32 v11, v11, v12
	v_cvt_pk_bf16_f32 v12, v20, v15
	v_addc_co_u32_e32 v15, vcc, 0, v141, vcc
	v_max_f32_e32 v2, 0, v2
	v_max_f32_e32 v3, 0, v3
	v_max_f32_e32 v4, 0, v4
	v_cvt_pk_bf16_f32 v13, v16, v13
	global_store_dwordx4 v[14:15], v[10:13], off nt
	v_max_f32_e32 v5, v5, v5
	s_mov_b64 s[38:39], 0x2c0000
	v_mul_f32_e32 v10, v2, v2
	v_max_f32_e32 v2, v7, v7
	v_mul_f32_e32 v7, v3, v3
	v_max_f32_e32 v3, v8, v8
	v_mul_f32_e32 v8, v4, v4
	v_max_f32_e32 v4, v9, v9
	v_max_f32_e32 v6, v6, v6
	v_max_f32_e32 v2, 0, v2
	v_max_f32_e32 v3, 0, v3
	v_max_f32_e32 v4, 0, v4
	v_max_f32_e32 v5, 0, v5
	v_lshl_add_u64 v[18:19], v[140:141], 0, s[38:39]
	v_max_f32_e32 v6, 0, v6
	v_mul_f32_e32 v2, v2, v2
	v_mul_f32_e32 v3, v3, v3
	v_mul_f32_e32 v4, v4, v4
	v_mul_f32_e32 v5, v5, v5
	s_and_b64 vcc, exec, s[40:41]
	s_mov_b32 s68, s26
	s_mov_b32 s8, s28
	s_mov_b64 s[46:47], s[44:45]
	s_mov_b64 s[48:49], s[42:43]
	v_mul_f32_e32 v6, v6, v6
	v_cvt_pk_bf16_f32 v2, v6, v2
	v_cvt_pk_bf16_f32 v3, v3, v4
	v_cvt_pk_bf16_f32 v4, v10, v7
	v_cvt_pk_bf16_f32 v5, v8, v5
	global_store_dwordx4 v[18:19], v[2:5], off offset:256 nt
	s_cbranch_vccz .LBB0_70
	s_waitcnt vmcnt(0)
	s_cmpk_gt_u32 s52, 0xff
	s_cbranch_scc1 .LBB0_77
	s_barrier

; #define PG8_STAGE(bufoff, gbase, voff) do { _Pragma("unroll") for (int _i = 0; _i < 2; ++_i) \
;         __builtin_amdgcn_global_load_lds((const unsigned*)((const char*)(gbase) + (voff)[_i]), (LAS unsigned*)(lds + (bufoff) + ldsw + _i * 8192), 16, 0, 0); } while (0)
; #define PG8_LDA(dst, b, h) do { _Pragma("unroll") for (int m = 0; m < 4; ++m) _Pragma("unroll") for (int k = 0; k < 2; ++k) dst[m][k] = *(const LAS bf16x8*)(lds + PG8_SA(b, h) + aoff + m * 2048 + k * 1024); } while (0)
; #define PG8_LDB(dst, b, h) do { _Pragma("unroll") for (int n = 0; n < 2; ++n) _Pragma("unroll") for (int k = 0; k < 2; ++k) dst[n][k] = *(const LAS bf16x8*)(lds + PG8_SB(b, h) + boff + n * 2048 + k * 1024); } while (0)
; #define PG8_MMA(ai, bj, At, Bt) do { __builtin_amdgcn_s_setprio(1); _Pragma("unroll") for (int m = 0; m < 4; ++m) _Pragma("unroll") for (int n = 0; n < 2; ++n) _Pragma("unroll") for (int k = 0; k < 2; ++k) \
;         acc[ai][bj][m][n] = __builtin_amdgcn_mfma_f32_16x16x32_bf16(Bt[n][k], At[m][k], acc[ai][bj][m][n], 0, 0, 0); __builtin_amdgcn_s_setprio(0); } while (0)
; #define PG8_WAIT_V(n) asm volatile("s_waitcnt vmcnt(" #n ")" ::: "memory")
; #define PG8_WAIT_L(n) asm volatile("s_waitcnt lgkmcnt(" #n ")" ::: "memory")
; #define PG8_BAR __builtin_amdgcn_s_barrier()
; template <class Epi, class Sched>
; __device__ __forceinline__ void gemm_phase(LAS unsigned char* lds, const Gemm g, const Sched& S, const Epi& E) {
;     ...
;             const bool last = (t == nt - 2);
;             const char* a1 = cA + (size_t)(t + 1) * kstep;
;             const char* a2 = last ? nA : cA + (size_t)(t + 2) * kstep; const char* b2 = last ? nB : cB + (size_t)(t + 2) * kstep;
;             const char* a3 = a2 + kstep; const char* b3 = b2 + kstep;
;             PG8_LDB(B0, 0, 0); PG8_SCHED; PG8_LDA(At, 0, 0); PG8_STAGE(PG8_SA(1, 1), a1 + hstep, voffA);
;             PG8_WAIT_L(8); PG8_BAR; PG8_WAIT_L(0); PG8_MMA(0, 0, At, B0); PG8_BAR; PG8_SCHED;
;             PG8_LDB(B1, 0, 1); PG8_STAGE(PG8_SB(0, 0), b2, voffB);
;             PG8_BAR; PG8_WAIT_L(0); PG8_MMA(0, 1, At, B1); PG8_BAR;
;             PG8_LDA(At, 0, 1); PG8_STAGE(PG8_SA(0, 0), a2, voffA);
;             PG8_BAR; PG8_WAIT_L(0); PG8_MMA(1, 0, At, B0); PG8_BAR; PG8_SCHED;
;             PG8_STAGE(PG8_SB(0, 1), b2 + hstep, voffB);
;             PG8_WAIT_V(6); PG8_BAR; PG8_MMA(1, 1, At, B1); PG8_BAR;
.LBB0_99:
	s_add_u32 s56, s28, 0x100
	s_addc_u32 s57, s29, 0
	s_cmp_eq_u32 s81, 28
	s_cselect_b32 s61, s51, s57
	s_cselect_b32 s60, s77, s56
	s_cselect_b32 s59, s49, s80
	s_cselect_b32 s58, s78, s79
	v_lshl_add_u64 v[156:157], s[28:29], 0, v[150:151]
	s_add_i32 m0, s9, 0xc000
	s_nop 0
	global_load_lds_dwordx4 v[156:157], off
	v_lshl_add_u64 v[156:157], s[28:29], 0, v[148:149]
	s_add_i32 m0, s9, 0xe000
	s_nop 0
	global_load_lds_dwordx4 v[156:157], off
	s_add_i32 s38, 0, 0x10000
	v_add_u32_e32 v110, s38, v169
	ds_read_b128 v[98:101], v110
	ds_read_b128 v[102:105], v110 offset:1024
	ds_read_b128 v[106:109], v110 offset:2048
	ds_read_b128 v[110:113], v110 offset:3072
	ds_read_b128 v[152:155], v171
	ds_read_b128 v[160:163], v171 offset:1024
	ds_read_b128 v[164:167], v171 offset:2048
	ds_read_b128 v[172:175], v171 offset:3072
	ds_read_b128 v[176:179], v171 offset:4096
	ds_read_b128 v[180:183], v171 offset:5120
	ds_read_b128 v[184:187], v171 offset:6144
	ds_read_b128 v[188:191], v171 offset:7168
	s_add_i32 s39, 0, 0x14000
	v_add_u32_e32 v156, s39, v169
	ds_read_b128 v[192:195], v156
	ds_read_b128 v[196:199], v156 offset:1024
	ds_read_b128 v[200:203], v156 offset:2048
	ds_read_b128 v[204:207], v156 offset:3072
	s_waitcnt vmcnt(8)
	s_waitcnt lgkmcnt(4)
	s_barrier
	s_waitcnt lgkmcnt(0)
	s_setprio 1
	v_mfma_f32_16x16x32_bf16 v[142:145], v[98:101], v[152:155], v[142:145]
	v_mfma_f32_16x16x32_bf16 v[138:141], v[106:109], v[152:155], v[138:141]
	v_mfma_f32_16x16x32_bf16 v[126:129], v[98:101], v[164:167], v[126:129]
	v_mfma_f32_16x16x32_bf16 v[122:125], v[106:109], v[164:167], v[122:125]
	v_mfma_f32_16x16x32_bf16 v[94:97], v[98:101], v[176:179], v[94:97]
	v_mfma_f32_16x16x32_bf16 v[90:93], v[106:109], v[176:179], v[90:93]
	v_mfma_f32_16x16x32_bf16 v[86:89], v[98:101], v[184:187], v[86:89]
	v_mfma_f32_16x16x32_bf16 v[82:85], v[106:109], v[184:187], v[82:85]
	v_mfma_f32_16x16x32_bf16 v[142:145], v[102:105], v[160:163], v[142:145]
	v_mfma_f32_16x16x32_bf16 v[138:141], v[110:113], v[160:163], v[138:141]
	v_mfma_f32_16x16x32_bf16 v[126:129], v[102:105], v[172:175], v[126:129]
	v_mfma_f32_16x16x32_bf16 v[122:125], v[110:113], v[172:175], v[122:125]
	v_mfma_f32_16x16x32_bf16 v[94:97], v[102:105], v[180:183], v[94:97]
	v_mfma_f32_16x16x32_bf16 v[90:93], v[110:113], v[180:183], v[90:93]
	v_mfma_f32_16x16x32_bf16 v[86:89], v[102:105], v[188:191], v[86:89]
	v_mfma_f32_16x16x32_bf16 v[82:85], v[110:113], v[188:191], v[82:85]
	v_mfma_f32_16x16x32_bf16 v[134:137], v[192:195], v[152:155], v[134:137]
	v_mfma_f32_16x16x32_bf16 v[130:133], v[200:203], v[152:155], v[130:133]
	v_mfma_f32_16x16x32_bf16 v[118:121], v[192:195], v[164:167], v[118:121]
	v_mfma_f32_16x16x32_bf16 v[114:117], v[200:203], v[164:167], v[114:117]
	v_mfma_f32_16x16x32_bf16 v[78:81], v[192:195], v[176:179], v[78:81]
	v_mfma_f32_16x16x32_bf16 v[74:77], v[200:203], v[176:179], v[74:77]
	v_mfma_f32_16x16x32_bf16 v[70:73], v[192:195], v[184:187], v[70:73]
	v_mfma_f32_16x16x32_bf16 v[66:69], v[200:203], v[184:187], v[66:69]
	v_mfma_f32_16x16x32_bf16 v[134:137], v[196:199], v[160:163], v[134:137]
	v_mfma_f32_16x16x32_bf16 v[130:133], v[204:207], v[160:163], v[130:133]
	v_mfma_f32_16x16x32_bf16 v[118:121], v[196:199], v[172:175], v[118:121]
	v_mfma_f32_16x16x32_bf16 v[114:117], v[204:207], v[172:175], v[114:117]
	v_mfma_f32_16x16x32_bf16 v[78:81], v[196:199], v[180:183], v[78:81]
	v_mfma_f32_16x16x32_bf16 v[74:77], v[204:207], v[180:183], v[74:77]
	v_mfma_f32_16x16x32_bf16 v[70:73], v[196:199], v[188:191], v[70:73]
	v_mfma_f32_16x16x32_bf16 v[66:69], v[204:207], v[188:191], v[66:69]
	s_setprio 0
	s_barrier
	s_add_i32 s28, s38, s67
	v_lshl_add_u64 v[156:157], s[58:59], 0, v[0:1]
	s_mov_b32 m0, s28
	v_lshl_add_u64 v[210:211], s[58:59], 0, v[146:147]
	global_load_lds_dwordx4 v[156:157], off
	s_add_i32 m0, s28, 0x2000
	s_nop 0
	global_load_lds_dwordx4 v[210:211], off
	s_mov_b32 m0, s9
	v_lshl_add_u64 v[212:213], s[60:61], 0, v[0:1]
	global_load_lds_dwordx4 v[212:213], off
	v_lshl_add_u64 v[214:215], s[60:61], 0, v[146:147]
	s_mov_b32 m0, s68
	s_nop 0
	global_load_lds_dwordx4 v[214:215], off
	ds_read_b128 v[152:155], v171 offset:16384
	ds_read_b128 v[160:163], v171 offset:17408
	ds_read_b128 v[164:167], v171 offset:18432
	ds_read_b128 v[172:175], v171 offset:19456
	ds_read_b128 v[176:179], v171 offset:20480
	ds_read_b128 v[180:183], v171 offset:21504
	ds_read_b128 v[184:187], v171 offset:22528
	ds_read_b128 v[188:191], v171 offset:23552
	s_waitcnt vmcnt(6)
	s_waitcnt lgkmcnt(0)
	s_barrier
; #define PG8_STAGE(bufoff, gbase, voff) do { _Pragma("unroll") for (int _i = 0; _i < 2; ++_i) \
;         __builtin_amdgcn_global_load_lds((const unsigned*)((const char*)(gbase) + (voff)[_i]), (LAS unsigned*)(lds + (bufoff) + ldsw + _i * 8192), 16, 0, 0); } while (0)
; #define PG8_LDA(dst, b, h) do { _Pragma("unroll") for (int m = 0; m < 4; ++m) _Pragma("unroll") for (int k = 0; k < 2; ++k) dst[m][k] = *(const LAS bf16x8*)(lds + PG8_SA(b, h) + aoff + m * 2048 + k * 1024); } while (0)
; #define PG8_LDB(dst, b, h) do { _Pragma("unroll") for (int n = 0; n < 2; ++n) _Pragma("unroll") for (int k = 0; k < 2; ++k) dst[n][k] = *(const LAS bf16x8*)(lds + PG8_SB(b, h) + boff + n * 2048 + k * 1024); } while (0)
; #define PG8_MMA(ai, bj, At, Bt) do { __builtin_amdgcn_s_setprio(1); _Pragma("unroll") for (int m = 0; m < 4; ++m) _Pragma("unroll") for (int n = 0; n < 2; ++n) _Pragma("unroll") for (int k = 0; k < 2; ++k) \
;         acc[ai][bj][m][n] = __builtin_amdgcn_mfma_f32_16x16x32_bf16(Bt[n][k], At[m][k], acc[ai][bj][m][n], 0, 0, 0); __builtin_amdgcn_s_setprio(0); } while (0)
; #define PG8_WAIT_V(n) asm volatile("s_waitcnt vmcnt(" #n ")" ::: "memory")
; #define PG8_WAIT_L(n) asm volatile("s_waitcnt lgkmcnt(" #n ")" ::: "memory")
; #define PG8_BAR __builtin_amdgcn_s_barrier()
; #define PG8_SCHED __builtin_amdgcn_sched_barrier(0)
; template <class Epi, class Sched>
; __device__ __forceinline__ void gemm_phase(LAS unsigned char* lds, const Gemm g, const Sched& S, const Epi& E) {
;     ...
;             PG8_BAR; PG8_WAIT_L(0); PG8_MMA(1, 0, At, B0); PG8_BAR; PG8_SCHED;
;             PG8_STAGE(PG8_SB(0, 1), b2 + hstep, voffB);
;             PG8_WAIT_V(6); PG8_BAR; PG8_MMA(1, 1, At, B1); PG8_BAR;
;             PG8_LDB(B0, 1, 0); PG8_SCHED; PG8_LDA(At, 1, 0); PG8_STAGE(PG8_SA(0, 1), a2 + hstep, voffA);
;             PG8_WAIT_L(8); PG8_BAR; PG8_WAIT_L(0); PG8_MMA(0, 0, At, B0); PG8_BAR; PG8_SCHED;
	s_setprio 1
	v_mfma_f32_16x16x32_bf16 v[62:65], v[98:101], v[152:155], v[62:65]
	v_mfma_f32_16x16x32_bf16 v[58:61], v[106:109], v[152:155], v[58:61]
	v_mfma_f32_16x16x32_bf16 v[46:49], v[98:101], v[164:167], v[46:49]
	v_mfma_f32_16x16x32_bf16 v[42:45], v[106:109], v[164:167], v[42:45]
	v_mfma_f32_16x16x32_bf16 v[30:33], v[98:101], v[176:179], v[30:33]
	v_mfma_f32_16x16x32_bf16 v[26:29], v[106:109], v[176:179], v[26:29]
	v_mfma_f32_16x16x32_bf16 v[22:25], v[98:101], v[184:187], v[22:25]
	v_mfma_f32_16x16x32_bf16 v[18:21], v[106:109], v[184:187], v[18:21]
	v_mfma_f32_16x16x32_bf16 v[62:65], v[102:105], v[160:163], v[62:65]
	v_mfma_f32_16x16x32_bf16 v[58:61], v[110:113], v[160:163], v[58:61]
	v_mfma_f32_16x16x32_bf16 v[46:49], v[102:105], v[172:175], v[46:49]
	v_mfma_f32_16x16x32_bf16 v[42:45], v[110:113], v[172:175], v[42:45]
	v_mfma_f32_16x16x32_bf16 v[30:33], v[102:105], v[180:183], v[30:33]
	v_mfma_f32_16x16x32_bf16 v[26:29], v[110:113], v[180:183], v[26:29]
	v_mfma_f32_16x16x32_bf16 v[22:25], v[102:105], v[188:191], v[22:25]
	v_mfma_f32_16x16x32_bf16 v[18:21], v[110:113], v[188:191], v[18:21]
	s_add_u32 s28, s58, 0x80000
	s_addc_u32 s29, s59, 0
	s_add_i32 s38, s39, s67
	v_lshl_add_u64 v[98:99], s[28:29], 0, v[0:1]
	s_mov_b32 m0, s38
	s_nop 0
	global_load_lds_dwordx4 v[98:99], off
	v_lshl_add_u64 v[98:99], s[28:29], 0, v[146:147]
	s_add_i32 m0, s38, 0x2000
	s_nop 0
	global_load_lds_dwordx4 v[98:99], off
	v_mfma_f32_16x16x32_bf16 v[54:57], v[192:195], v[152:155], v[54:57]
	v_mfma_f32_16x16x32_bf16 v[50:53], v[200:203], v[152:155], v[50:53]
	v_mfma_f32_16x16x32_bf16 v[38:41], v[192:195], v[164:167], v[38:41]
	v_mfma_f32_16x16x32_bf16 v[34:37], v[200:203], v[164:167], v[34:37]
	v_mfma_f32_16x16x32_bf16 v[14:17], v[192:195], v[176:179], v[14:17]
	v_mfma_f32_16x16x32_bf16 v[10:13], v[200:203], v[176:179], v[10:13]
	v_mfma_f32_16x16x32_bf16 v[6:9], v[192:195], v[184:187], v[6:9]
	v_mfma_f32_16x16x32_bf16 v[2:5], v[200:203], v[184:187], v[2:5]
	v_mfma_f32_16x16x32_bf16 v[54:57], v[196:199], v[160:163], v[54:57]
	v_mfma_f32_16x16x32_bf16 v[50:53], v[204:207], v[160:163], v[50:53]
	v_mfma_f32_16x16x32_bf16 v[38:41], v[196:199], v[172:175], v[38:41]
	v_mfma_f32_16x16x32_bf16 v[34:37], v[204:207], v[172:175], v[34:37]
	v_mfma_f32_16x16x32_bf16 v[14:17], v[196:199], v[180:183], v[14:17]
	v_mfma_f32_16x16x32_bf16 v[10:13], v[204:207], v[180:183], v[10:13]
	v_mfma_f32_16x16x32_bf16 v[6:9], v[196:199], v[188:191], v[6:9]
	v_mfma_f32_16x16x32_bf16 v[2:5], v[204:207], v[188:191], v[2:5]
	s_setprio 0
	s_barrier
	s_add_u32 s28, s60, 0x80000
	s_addc_u32 s29, s61, 0
	s_mov_b32 m0, s69
	v_lshl_add_u64 v[192:193], s[28:29], 0, v[0:1]
	global_load_lds_dwordx4 v[192:193], off
	v_lshl_add_u64 v[192:193], s[28:29], 0, v[146:147]
	s_mov_b32 m0, s70
	s_nop 0
	global_load_lds_dwordx4 v[192:193], off
	s_add_i32 s38, 0, 0x18000
	v_add_u32_e32 v110, s38, v169
	ds_read_b128 v[98:101], v110
	ds_read_b128 v[102:105], v110 offset:1024
	ds_read_b128 v[106:109], v110 offset:2048
	ds_read_b128 v[110:113], v110 offset:3072
	ds_read_b128 v[152:155], v171 offset:32768
	ds_read_b128 v[160:163], v171 offset:33792
	ds_read_b128 v[164:167], v171 offset:34816
	ds_read_b128 v[172:175], v171 offset:35840
	ds_read_b128 v[176:179], v171 offset:36864
	ds_read_b128 v[180:183], v171 offset:37888
	ds_read_b128 v[184:187], v171 offset:38912
	ds_read_b128 v[188:191], v171 offset:39936
	s_add_i32 s39, 0, 0x1c000
	v_add_u32_e32 v204, s39, v169
	ds_read_b128 v[192:195], v204
	ds_read_b128 v[196:199], v204 offset:1024
	ds_read_b128 v[200:203], v204 offset:2048
	ds_read_b128 v[204:207], v204 offset:3072
	s_waitcnt vmcnt(8)
	s_waitcnt lgkmcnt(4)
	s_barrier
	s_waitcnt lgkmcnt(0)
	s_setprio 1
	v_mfma_f32_16x16x32_bf16 v[142:145], v[98:101], v[152:155], v[142:145]
	v_mfma_f32_16x16x32_bf16 v[138:141], v[106:109], v[152:155], v[138:141]
	v_mfma_f32_16x16x32_bf16 v[126:129], v[98:101], v[164:167], v[126:129]
	v_mfma_f32_16x16x32_bf16 v[122:125], v[106:109], v[164:167], v[122:125]
	v_mfma_f32_16x16x32_bf16 v[94:97], v[98:101], v[176:179], v[94:97]
	v_mfma_f32_16x16x32_bf16 v[90:93], v[106:109], v[176:179], v[90:93]
	v_mfma_f32_16x16x32_bf16 v[86:89], v[98:101], v[184:187], v[86:89]
	v_mfma_f32_16x16x32_bf16 v[82:85], v[106:109], v[184:187], v[82:85]
	v_mfma_f32_16x16x32_bf16 v[142:145], v[102:105], v[160:163], v[142:145]
	v_mfma_f32_16x16x32_bf16 v[138:141], v[110:113], v[160:163], v[138:141]
	v_mfma_f32_16x16x32_bf16 v[126:129], v[102:105], v[172:175], v[126:129]
	v_mfma_f32_16x16x32_bf16 v[122:125], v[110:113], v[172:175], v[122:125]
	v_mfma_f32_16x16x32_bf16 v[94:97], v[102:105], v[180:183], v[94:97]
	v_mfma_f32_16x16x32_bf16 v[90:93], v[110:113], v[180:183], v[90:93]
	v_mfma_f32_16x16x32_bf16 v[86:89], v[102:105], v[188:191], v[86:89]
	v_mfma_f32_16x16x32_bf16 v[82:85], v[110:113], v[188:191], v[82:85]
	v_mfma_f32_16x16x32_bf16 v[134:137], v[192:195], v[152:155], v[134:137]
	v_mfma_f32_16x16x32_bf16 v[130:133], v[200:203], v[152:155], v[130:133]
	v_mfma_f32_16x16x32_bf16 v[118:121], v[192:195], v[164:167], v[118:121]
	v_mfma_f32_16x16x32_bf16 v[114:117], v[200:203], v[164:167], v[114:117]
	v_mfma_f32_16x16x32_bf16 v[78:81], v[192:195], v[176:179], v[78:81]
	v_mfma_f32_16x16x32_bf16 v[74:77], v[200:203], v[176:179], v[74:77]
	v_mfma_f32_16x16x32_bf16 v[70:73], v[192:195], v[184:187], v[70:73]
	v_mfma_f32_16x16x32_bf16 v[66:69], v[200:203], v[184:187], v[66:69]
	v_mfma_f32_16x16x32_bf16 v[134:137], v[196:199], v[160:163], v[134:137]
	v_mfma_f32_16x16x32_bf16 v[130:133], v[204:207], v[160:163], v[130:133]
	v_mfma_f32_16x16x32_bf16 v[118:121], v[196:199], v[172:175], v[118:121]
	v_mfma_f32_16x16x32_bf16 v[114:117], v[204:207], v[172:175], v[114:117]
	v_mfma_f32_16x16x32_bf16 v[78:81], v[196:199], v[180:183], v[78:81]
	v_mfma_f32_16x16x32_bf16 v[74:77], v[204:207], v[180:183], v[74:77]
	v_mfma_f32_16x16x32_bf16 v[70:73], v[196:199], v[188:191], v[70:73]
	v_mfma_f32_16x16x32_bf16 v[66:69], v[204:207], v[188:191], v[66:69]
	s_setprio 0
	s_barrier
; #define PG8_STAGE(bufoff, gbase, voff) do { _Pragma("unroll") for (int _i = 0; _i < 2; ++_i) \
;         __builtin_amdgcn_global_load_lds((const unsigned*)((const char*)(gbase) + (voff)[_i]), (LAS unsigned*)(lds + (bufoff) + ldsw + _i * 8192), 16, 0, 0); } while (0)
; #define PG8_LDA(dst, b, h) do { _Pragma("unroll") for (int m = 0; m < 4; ++m) _Pragma("unroll") for (int k = 0; k < 2; ++k) dst[m][k] = *(const LAS bf16x8*)(lds + PG8_SA(b, h) + aoff + m * 2048 + k * 1024); } while (0)
; #define PG8_LDB(dst, b, h) do { _Pragma("unroll") for (int n = 0; n < 2; ++n) _Pragma("unroll") for (int k = 0; k < 2; ++k) dst[n][k] = *(const LAS bf16x8*)(lds + PG8_SB(b, h) + boff + n * 2048 + k * 1024); } while (0)
; #define PG8_MMA(ai, bj, At, Bt) do { __builtin_amdgcn_s_setprio(1); _Pragma("unroll") for (int m = 0; m < 4; ++m) _Pragma("unroll") for (int n = 0; n < 2; ++n) _Pragma("unroll") for (int k = 0; k < 2; ++k) \
;         acc[ai][bj][m][n] = __builtin_amdgcn_mfma_f32_16x16x32_bf16(Bt[n][k], At[m][k], acc[ai][bj][m][n], 0, 0, 0); __builtin_amdgcn_s_setprio(0); } while (0)
; #define PG8_WAIT_V(n) asm volatile("s_waitcnt vmcnt(" #n ")" ::: "memory")
; #define PG8_WAIT_L(n) asm volatile("s_waitcnt lgkmcnt(" #n ")" ::: "memory")
; #define PG8_BAR __builtin_amdgcn_s_barrier()
; #define PG8_SCHED __builtin_amdgcn_sched_barrier(0)
; template <class Epi, class Sched>
; __device__ __forceinline__ void gemm_phase(LAS unsigned char* lds, const Gemm g, const Sched& S, const Epi& E) {
;     ...
;         const bool has_next = S.next(ui + 1, nxt);
;         const char* nA = has_next ? (const char*)g.A + (size_t)nxt.pm * tstep + (size_t)nxt.ks * sstep : cA; const char* nB = has_next ? (const char*)g.Bt + (size_t)nxt.pn * tstep + (size_t)nxt.ks * sstep : cB;
;     ...
;             PG8_LDB(B1, 1, 1); PG8_STAGE(PG8_SB(1, 0), b3, voffB);
;             PG8_BAR; PG8_WAIT_L(0); PG8_MMA(0, 1, At, B1); PG8_BAR;
;             PG8_LDA(At, 1, 1); PG8_STAGE(PG8_SA(1, 0), a3, voffA);
;             PG8_BAR; PG8_WAIT_L(0); PG8_MMA(1, 0, At, B0); PG8_BAR; PG8_SCHED;
;             PG8_STAGE(PG8_SB(1, 1), b3 + hstep, voffB);
;             PG8_WAIT_V(6); PG8_BAR; PG8_MMA(1, 1, At, B1); PG8_BAR;
	s_add_i32 s28, s38, s67
	v_lshl_add_u64 v[156:157], v[156:157], 0, s[36:37]
	s_mov_b32 m0, s28
	s_nop 0
	global_load_lds_dwordx4 v[156:157], off
	v_lshl_add_u64 v[156:157], v[210:211], 0, s[36:37]
	s_add_i32 m0, s28, 0x2000
	s_nop 0
	global_load_lds_dwordx4 v[156:157], off
	s_mov_b32 m0, s72
	v_lshl_add_u64 v[156:157], v[212:213], 0, s[36:37]
	global_load_lds_dwordx4 v[156:157], off
	v_lshl_add_u64 v[156:157], v[214:215], 0, s[36:37]
	s_mov_b32 m0, s73
	s_nop 0
	global_load_lds_dwordx4 v[156:157], off
	ds_read_b128 v[152:155], v171 offset:49152
	ds_read_b128 v[160:163], v171 offset:50176
	ds_read_b128 v[164:167], v171 offset:51200
	ds_read_b128 v[172:175], v171 offset:52224
	ds_read_b128 v[176:179], v171 offset:53248
	ds_read_b128 v[180:183], v171 offset:54272
	ds_read_b128 v[184:187], v171 offset:55296
	ds_read_b128 v[188:191], v171 offset:56320
	s_waitcnt vmcnt(6)
	s_waitcnt lgkmcnt(0)
	s_barrier
	s_setprio 1
	v_mfma_f32_16x16x32_bf16 v[62:65], v[98:101], v[152:155], v[62:65]
	v_mfma_f32_16x16x32_bf16 v[58:61], v[106:109], v[152:155], v[58:61]
	v_mfma_f32_16x16x32_bf16 v[46:49], v[98:101], v[164:167], v[46:49]
	v_mfma_f32_16x16x32_bf16 v[42:45], v[106:109], v[164:167], v[42:45]
	v_mfma_f32_16x16x32_bf16 v[30:33], v[98:101], v[176:179], v[30:33]
	v_mfma_f32_16x16x32_bf16 v[26:29], v[106:109], v[176:179], v[26:29]
	v_mfma_f32_16x16x32_bf16 v[22:25], v[98:101], v[184:187], v[22:25]
	v_mfma_f32_16x16x32_bf16 v[18:21], v[106:109], v[184:187], v[18:21]
	v_mfma_f32_16x16x32_bf16 v[62:65], v[102:105], v[160:163], v[62:65]
	v_mfma_f32_16x16x32_bf16 v[58:61], v[110:113], v[160:163], v[58:61]
	v_mfma_f32_16x16x32_bf16 v[46:49], v[102:105], v[172:175], v[46:49]
	v_mfma_f32_16x16x32_bf16 v[42:45], v[110:113], v[172:175], v[42:45]
	v_mfma_f32_16x16x32_bf16 v[30:33], v[102:105], v[180:183], v[30:33]
	v_mfma_f32_16x16x32_bf16 v[26:29], v[110:113], v[180:183], v[26:29]
	v_mfma_f32_16x16x32_bf16 v[22:25], v[102:105], v[188:191], v[22:25]
	v_mfma_f32_16x16x32_bf16 v[18:21], v[110:113], v[188:191], v[18:21]
	s_add_u32 s28, s58, 0x80080
	s_addc_u32 s29, s59, 0
	s_add_i32 s38, s39, s67
	v_lshl_add_u64 v[98:99], s[28:29], 0, v[0:1]
	s_mov_b32 m0, s38
	s_nop 0
	global_load_lds_dwordx4 v[98:99], off
	v_lshl_add_u64 v[98:99], s[28:29], 0, v[146:147]
	s_add_i32 m0, s38, 0x2000
	s_nop 0
	global_load_lds_dwordx4 v[98:99], off
	v_mfma_f32_16x16x32_bf16 v[54:57], v[192:195], v[152:155], v[54:57]
	v_mfma_f32_16x16x32_bf16 v[50:53], v[200:203], v[152:155], v[50:53]
	v_mfma_f32_16x16x32_bf16 v[38:41], v[192:195], v[164:167], v[38:41]
	v_mfma_f32_16x16x32_bf16 v[34:37], v[200:203], v[164:167], v[34:37]
	v_mfma_f32_16x16x32_bf16 v[14:17], v[192:195], v[176:179], v[14:17]
	v_mfma_f32_16x16x32_bf16 v[10:13], v[200:203], v[176:179], v[10:13]
	v_mfma_f32_16x16x32_bf16 v[6:9], v[192:195], v[184:187], v[6:9]
	v_mfma_f32_16x16x32_bf16 v[2:5], v[200:203], v[184:187], v[2:5]
	v_mfma_f32_16x16x32_bf16 v[54:57], v[196:199], v[160:163], v[54:57]
	v_mfma_f32_16x16x32_bf16 v[50:53], v[204:207], v[160:163], v[50:53]
	v_mfma_f32_16x16x32_bf16 v[38:41], v[196:199], v[172:175], v[38:41]
	v_mfma_f32_16x16x32_bf16 v[34:37], v[204:207], v[172:175], v[34:37]
	v_mfma_f32_16x16x32_bf16 v[14:17], v[196:199], v[180:183], v[14:17]
	v_mfma_f32_16x16x32_bf16 v[10:13], v[204:207], v[180:183], v[10:13]
	v_mfma_f32_16x16x32_bf16 v[6:9], v[196:199], v[188:191], v[6:9]
	v_mfma_f32_16x16x32_bf16 v[2:5], v[204:207], v[188:191], v[2:5]
	s_setprio 0
	s_add_i32 s81, s81, 2
	s_add_u32 s79, s79, 0x100
	s_addc_u32 s80, s80, 0
	s_cmp_gt_u32 s81, 29
	s_mov_b64 s[28:29], s[56:57]
	s_barrier
	s_cbranch_scc0 .LBB0_99
	s_cmp_lt_i32 s8, 64
	s_cselect_b64 s[58:59], -1, 0
	s_cmp_gt_i32 s8, 63
	s_cbranch_scc0 .LBB0_90
	s_mov_b64 s[60:61], 0x18000
	s_mov_b64 s[28:29], s[46:47]
	s_mov_b64 s[56:57], s[24:25]
	s_branch .LBB0_91

; #define PG8_STAGE(bufoff, gbase, voff) do { _Pragma("unroll") for (int _i = 0; _i < 2; ++_i) \
;         __builtin_amdgcn_global_load_lds((const unsigned*)((const char*)(gbase) + (voff)[_i]), (LAS unsigned*)(lds + (bufoff) + ldsw + _i * 8192), 16, 0, 0); } while (0)
; #define PG8_LDA(dst, b, h) do { _Pragma("unroll") for (int m = 0; m < 4; ++m) _Pragma("unroll") for (int k = 0; k < 2; ++k) dst[m][k] = *(const LAS bf16x8*)(lds + PG8_SA(b, h) + aoff + m * 2048 + k * 1024); } while (0)
; #define PG8_LDB(dst, b, h) do { _Pragma("unroll") for (int n = 0; n < 2; ++n) _Pragma("unroll") for (int k = 0; k < 2; ++k) dst[n][k] = *(const LAS bf16x8*)(lds + PG8_SB(b, h) + boff + n * 2048 + k * 1024); } while (0)
; #define PG8_MMA(ai, bj, At, Bt) do { __builtin_amdgcn_s_setprio(1); _Pragma("unroll") for (int m = 0; m < 4; ++m) _Pragma("unroll") for (int n = 0; n < 2; ++n) _Pragma("unroll") for (int k = 0; k < 2; ++k) \
;         acc[ai][bj][m][n] = __builtin_amdgcn_mfma_f32_16x16x32_bf16(Bt[n][k], At[m][k], acc[ai][bj][m][n], 0, 0, 0); __builtin_amdgcn_s_setprio(0); } while (0)
; #define PG8_WAIT_L(n) asm volatile("s_waitcnt lgkmcnt(" #n ")" ::: "memory")
; #define PG8_BAR __builtin_amdgcn_s_barrier()
; #define PG8_SCHED __builtin_amdgcn_sched_barrier(0)
; template <class Epi, class Sched>
; __device__ __forceinline__ void gemm_phase(LAS unsigned char* lds, const Gemm g, const Sched& S, const Epi& E) {
;     ...
;             const bool last = (t == nt - 2);
;             const char* a1 = cA + (size_t)(t + 1) * kstep;
;             const char* a2 = last ? nA : cA + (size_t)(t + 2) * kstep; const char* b2 = last ? nB : cB + (size_t)(t + 2) * kstep;
;             const char* a3 = a2 + kstep; const char* b3 = b2 + kstep;
;             PG8_LDB(B0, 0, 0); PG8_SCHED; PG8_LDA(At, 0, 0); PG8_STAGE(PG8_SA(1, 1), a1 + hstep, voffA);
;             PG8_WAIT_L(8); PG8_BAR; PG8_WAIT_L(0); PG8_MMA(0, 0, At, B0); PG8_BAR; PG8_SCHED;
;             PG8_LDB(B1, 0, 1); PG8_STAGE(PG8_SB(0, 0), b2, voffB);
;             PG8_BAR; PG8_WAIT_L(0); PG8_MMA(0, 1, At, B1); PG8_BAR;
;             PG8_LDA(At, 0, 1); PG8_STAGE(PG8_SA(0, 0), a2, voffA);
;             PG8_BAR; PG8_WAIT_L(0); PG8_MMA(1, 0, At, B0); PG8_BAR; PG8_SCHED;
.LBB0_113:
	s_add_u32 s54, s52, 0x100
	s_addc_u32 s55, s53, 0
	s_cmp_eq_u32 s73, 4
	s_cselect_b32 s59, s11, s55
	s_cselect_b32 s58, s29, s54
	s_cselect_b32 s57, s41, s72
	s_cselect_b32 s56, s45, s71
	v_lshl_add_u64 v[156:157], s[52:53], 0, v[134:135]
	s_add_i32 m0, s25, 0xc000
	s_nop 0
	global_load_lds_dwordx4 v[156:157], off
	v_lshl_add_u64 v[156:157], s[52:53], 0, v[132:133]
	s_add_i32 m0, s25, 0xe000
	s_nop 0
	global_load_lds_dwordx4 v[156:157], off
	s_add_i32 s38, 0, 0x10000
	v_add_u32_e32 v152, s38, v137
	ds_read_b128 v[140:143], v152
	ds_read_b128 v[144:147], v152 offset:1024
	ds_read_b128 v[148:151], v152 offset:2048
	ds_read_b128 v[152:155], v152 offset:3072
	ds_read_b128 v[160:163], v139
	ds_read_b128 v[164:167], v139 offset:1024
	ds_read_b128 v[168:171], v139 offset:2048
	ds_read_b128 v[172:175], v139 offset:3072
	ds_read_b128 v[176:179], v139 offset:4096
	ds_read_b128 v[180:183], v139 offset:5120
	ds_read_b128 v[184:187], v139 offset:6144
	ds_read_b128 v[188:191], v139 offset:7168
	s_add_i32 s52, 0, 0x14000
	v_add_u32_e32 v156, s52, v137
	ds_read_b128 v[192:195], v156
	ds_read_b128 v[196:199], v156 offset:1024
	ds_read_b128 v[200:203], v156 offset:2048
	ds_read_b128 v[204:207], v156 offset:3072
	s_waitcnt vmcnt(8)
	s_waitcnt lgkmcnt(4)
	s_barrier
	s_waitcnt lgkmcnt(0)
	s_setprio 1
	v_mfma_f32_16x16x32_bf16 v[126:129], v[140:143], v[160:163], v[126:129]
	v_mfma_f32_16x16x32_bf16 v[122:125], v[148:151], v[160:163], v[122:125]
	v_mfma_f32_16x16x32_bf16 v[118:121], v[140:143], v[168:171], v[118:121]
	v_mfma_f32_16x16x32_bf16 v[114:117], v[148:151], v[168:171], v[114:117]
	v_mfma_f32_16x16x32_bf16 v[106:109], v[140:143], v[176:179], v[106:109]
	v_mfma_f32_16x16x32_bf16 v[98:101], v[148:151], v[176:179], v[98:101]
	v_mfma_f32_16x16x32_bf16 v[90:93], v[140:143], v[184:187], v[90:93]
	v_mfma_f32_16x16x32_bf16 v[82:85], v[148:151], v[184:187], v[82:85]
	v_mfma_f32_16x16x32_bf16 v[126:129], v[144:147], v[164:167], v[126:129]
	v_mfma_f32_16x16x32_bf16 v[122:125], v[152:155], v[164:167], v[122:125]
	v_mfma_f32_16x16x32_bf16 v[118:121], v[144:147], v[172:175], v[118:121]
	v_mfma_f32_16x16x32_bf16 v[114:117], v[152:155], v[172:175], v[114:117]
	v_mfma_f32_16x16x32_bf16 v[106:109], v[144:147], v[180:183], v[106:109]
	v_mfma_f32_16x16x32_bf16 v[98:101], v[152:155], v[180:183], v[98:101]
	v_mfma_f32_16x16x32_bf16 v[90:93], v[144:147], v[188:191], v[90:93]
	v_mfma_f32_16x16x32_bf16 v[82:85], v[152:155], v[188:191], v[82:85]
	v_mfma_f32_16x16x32_bf16 v[110:113], v[192:195], v[160:163], v[110:113]
	v_mfma_f32_16x16x32_bf16 v[102:105], v[200:203], v[160:163], v[102:105]
	v_mfma_f32_16x16x32_bf16 v[94:97], v[192:195], v[168:171], v[94:97]
	v_mfma_f32_16x16x32_bf16 v[86:89], v[200:203], v[168:171], v[86:89]
	v_mfma_f32_16x16x32_bf16 v[78:81], v[192:195], v[176:179], v[78:81]
	v_mfma_f32_16x16x32_bf16 v[74:77], v[200:203], v[176:179], v[74:77]
	v_mfma_f32_16x16x32_bf16 v[70:73], v[192:195], v[184:187], v[70:73]
	v_mfma_f32_16x16x32_bf16 v[66:69], v[200:203], v[184:187], v[66:69]
	v_mfma_f32_16x16x32_bf16 v[110:113], v[196:199], v[164:167], v[110:113]
	v_mfma_f32_16x16x32_bf16 v[102:105], v[204:207], v[164:167], v[102:105]
	v_mfma_f32_16x16x32_bf16 v[94:97], v[196:199], v[172:175], v[94:97]
	v_mfma_f32_16x16x32_bf16 v[86:89], v[204:207], v[172:175], v[86:89]
	v_mfma_f32_16x16x32_bf16 v[78:81], v[196:199], v[180:183], v[78:81]
	v_mfma_f32_16x16x32_bf16 v[74:77], v[204:207], v[180:183], v[74:77]
	v_mfma_f32_16x16x32_bf16 v[70:73], v[196:199], v[188:191], v[70:73]
	v_mfma_f32_16x16x32_bf16 v[66:69], v[204:207], v[188:191], v[66:69]
	s_setprio 0
	s_barrier
	s_add_i32 s38, s38, s65
	v_lshl_add_u64 v[156:157], s[56:57], 0, v[0:1]
	s_mov_b32 m0, s38
	v_lshl_add_u64 v[210:211], s[56:57], 0, v[130:131]
	global_load_lds_dwordx4 v[156:157], off
	s_add_i32 m0, s38, 0x2000
	s_nop 0
	global_load_lds_dwordx4 v[210:211], off
	s_mov_b32 m0, s25
	v_lshl_add_u64 v[212:213], s[58:59], 0, v[0:1]
	global_load_lds_dwordx4 v[212:213], off
	v_lshl_add_u64 v[214:215], s[58:59], 0, v[130:131]
	s_mov_b32 m0, s27
	s_nop 0
	global_load_lds_dwordx4 v[214:215], off
	ds_read_b128 v[160:163], v139 offset:16384
	ds_read_b128 v[164:167], v139 offset:17408
	ds_read_b128 v[168:171], v139 offset:18432
	ds_read_b128 v[172:175], v139 offset:19456
	ds_read_b128 v[176:179], v139 offset:20480
	ds_read_b128 v[180:183], v139 offset:21504
	ds_read_b128 v[184:187], v139 offset:22528
	ds_read_b128 v[188:191], v139 offset:23552
	s_waitcnt vmcnt(6)
	s_waitcnt lgkmcnt(0)
	s_barrier
; #define PG8_STAGE(bufoff, gbase, voff) do { _Pragma("unroll") for (int _i = 0; _i < 2; ++_i) \
;         __builtin_amdgcn_global_load_lds((const unsigned*)((const char*)(gbase) + (voff)[_i]), (LAS unsigned*)(lds + (bufoff) + ldsw + _i * 8192), 16, 0, 0); } while (0)
; #define PG8_LDA(dst, b, h) do { _Pragma("unroll") for (int m = 0; m < 4; ++m) _Pragma("unroll") for (int k = 0; k < 2; ++k) dst[m][k] = *(const LAS bf16x8*)(lds + PG8_SA(b, h) + aoff + m * 2048 + k * 1024); } while (0)
; #define PG8_LDB(dst, b, h) do { _Pragma("unroll") for (int n = 0; n < 2; ++n) _Pragma("unroll") for (int k = 0; k < 2; ++k) dst[n][k] = *(const LAS bf16x8*)(lds + PG8_SB(b, h) + boff + n * 2048 + k * 1024); } while (0)
; #define PG8_MMA(ai, bj, At, Bt) do { __builtin_amdgcn_s_setprio(1); _Pragma("unroll") for (int m = 0; m < 4; ++m) _Pragma("unroll") for (int n = 0; n < 2; ++n) _Pragma("unroll") for (int k = 0; k < 2; ++k) \
;         acc[ai][bj][m][n] = __builtin_amdgcn_mfma_f32_16x16x32_bf16(Bt[n][k], At[m][k], acc[ai][bj][m][n], 0, 0, 0); __builtin_amdgcn_s_setprio(0); } while (0)
; #define PG8_WAIT_V(n) asm volatile("s_waitcnt vmcnt(" #n ")" ::: "memory")
; #define PG8_WAIT_L(n) asm volatile("s_waitcnt lgkmcnt(" #n ")" ::: "memory")
; #define PG8_BAR __builtin_amdgcn_s_barrier()
; #define PG8_SCHED __builtin_amdgcn_sched_barrier(0)
; template <class Epi, class Sched>
; __device__ __forceinline__ void gemm_phase(LAS unsigned char* lds, const Gemm g, const Sched& S, const Epi& E) {
;     ...
;             PG8_BAR; PG8_WAIT_L(0); PG8_MMA(1, 0, At, B0); PG8_BAR; PG8_SCHED;
;             PG8_STAGE(PG8_SB(0, 1), b2 + hstep, voffB);
;             PG8_WAIT_V(6); PG8_BAR; PG8_MMA(1, 1, At, B1); PG8_BAR;
;             PG8_LDB(B0, 1, 0); PG8_SCHED; PG8_LDA(At, 1, 0); PG8_STAGE(PG8_SA(0, 1), a2 + hstep, voffA);
;             PG8_WAIT_L(8); PG8_BAR; PG8_WAIT_L(0); PG8_MMA(0, 0, At, B0); PG8_BAR; PG8_SCHED;
	s_setprio 1
	v_mfma_f32_16x16x32_bf16 v[62:65], v[140:143], v[160:163], v[62:65]
	v_mfma_f32_16x16x32_bf16 v[58:61], v[148:151], v[160:163], v[58:61]
	v_mfma_f32_16x16x32_bf16 v[54:57], v[140:143], v[168:171], v[54:57]
	v_mfma_f32_16x16x32_bf16 v[50:53], v[148:151], v[168:171], v[50:53]
	v_mfma_f32_16x16x32_bf16 v[38:41], v[140:143], v[176:179], v[38:41]
	v_mfma_f32_16x16x32_bf16 v[34:37], v[148:151], v[176:179], v[34:37]
	v_mfma_f32_16x16x32_bf16 v[22:25], v[140:143], v[184:187], v[22:25]
	v_mfma_f32_16x16x32_bf16 v[18:21], v[148:151], v[184:187], v[18:21]
	v_mfma_f32_16x16x32_bf16 v[62:65], v[144:147], v[164:167], v[62:65]
	v_mfma_f32_16x16x32_bf16 v[58:61], v[152:155], v[164:167], v[58:61]
	v_mfma_f32_16x16x32_bf16 v[54:57], v[144:147], v[172:175], v[54:57]
	v_mfma_f32_16x16x32_bf16 v[50:53], v[152:155], v[172:175], v[50:53]
	v_mfma_f32_16x16x32_bf16 v[38:41], v[144:147], v[180:183], v[38:41]
	v_mfma_f32_16x16x32_bf16 v[34:37], v[152:155], v[180:183], v[34:37]
	v_mfma_f32_16x16x32_bf16 v[22:25], v[144:147], v[188:191], v[22:25]
	v_mfma_f32_16x16x32_bf16 v[18:21], v[152:155], v[188:191], v[18:21]
	s_add_u32 s38, s56, 0x80000
	s_addc_u32 s39, s57, 0
	s_add_i32 s52, s52, s65
	v_lshl_add_u64 v[140:141], s[38:39], 0, v[0:1]
	s_mov_b32 m0, s52
	s_nop 0
	global_load_lds_dwordx4 v[140:141], off
	v_lshl_add_u64 v[140:141], s[38:39], 0, v[130:131]
	s_add_i32 m0, s52, 0x2000
	s_nop 0
	global_load_lds_dwordx4 v[140:141], off
	v_mfma_f32_16x16x32_bf16 v[46:49], v[192:195], v[160:163], v[46:49]
	v_mfma_f32_16x16x32_bf16 v[42:45], v[200:203], v[160:163], v[42:45]
	v_mfma_f32_16x16x32_bf16 v[30:33], v[192:195], v[168:171], v[30:33]
	v_mfma_f32_16x16x32_bf16 v[26:29], v[200:203], v[168:171], v[26:29]
	v_mfma_f32_16x16x32_bf16 v[14:17], v[192:195], v[176:179], v[14:17]
	v_mfma_f32_16x16x32_bf16 v[10:13], v[200:203], v[176:179], v[10:13]
	v_mfma_f32_16x16x32_bf16 v[6:9], v[192:195], v[184:187], v[6:9]
	v_mfma_f32_16x16x32_bf16 v[2:5], v[200:203], v[184:187], v[2:5]
	v_mfma_f32_16x16x32_bf16 v[46:49], v[196:199], v[164:167], v[46:49]
	v_mfma_f32_16x16x32_bf16 v[42:45], v[204:207], v[164:167], v[42:45]
	v_mfma_f32_16x16x32_bf16 v[30:33], v[196:199], v[172:175], v[30:33]
	v_mfma_f32_16x16x32_bf16 v[26:29], v[204:207], v[172:175], v[26:29]
	v_mfma_f32_16x16x32_bf16 v[14:17], v[196:199], v[180:183], v[14:17]
	v_mfma_f32_16x16x32_bf16 v[10:13], v[204:207], v[180:183], v[10:13]
	v_mfma_f32_16x16x32_bf16 v[6:9], v[196:199], v[188:191], v[6:9]
	v_mfma_f32_16x16x32_bf16 v[2:5], v[204:207], v[188:191], v[2:5]
	s_setprio 0
	s_barrier
	s_add_u32 s38, s58, 0x80000
	s_addc_u32 s39, s59, 0
	s_mov_b32 m0, s66
	v_lshl_add_u64 v[192:193], s[38:39], 0, v[0:1]
	global_load_lds_dwordx4 v[192:193], off
	v_lshl_add_u64 v[192:193], s[38:39], 0, v[130:131]
	s_mov_b32 m0, s67
	s_nop 0
	global_load_lds_dwordx4 v[192:193], off
	s_add_i32 s52, 0, 0x18000
	v_add_u32_e32 v152, s52, v137
	ds_read_b128 v[140:143], v152
	ds_read_b128 v[144:147], v152 offset:1024
	ds_read_b128 v[148:151], v152 offset:2048
	ds_read_b128 v[152:155], v152 offset:3072
	ds_read_b128 v[160:163], v139 offset:32768
	ds_read_b128 v[164:167], v139 offset:33792
	ds_read_b128 v[168:171], v139 offset:34816
	ds_read_b128 v[172:175], v139 offset:35840
	ds_read_b128 v[176:179], v139 offset:36864
	ds_read_b128 v[180:183], v139 offset:37888
	ds_read_b128 v[184:187], v139 offset:38912
	ds_read_b128 v[188:191], v139 offset:39936
	s_add_i32 s53, 0, 0x1c000
	v_add_u32_e32 v204, s53, v137
	ds_read_b128 v[192:195], v204
	ds_read_b128 v[196:199], v204 offset:1024
	ds_read_b128 v[200:203], v204 offset:2048
	ds_read_b128 v[204:207], v204 offset:3072
	s_waitcnt vmcnt(8)
	s_waitcnt lgkmcnt(4)
	s_barrier
	s_waitcnt lgkmcnt(0)
	s_setprio 1
	v_mfma_f32_16x16x32_bf16 v[126:129], v[140:143], v[160:163], v[126:129]
	v_mfma_f32_16x16x32_bf16 v[122:125], v[148:151], v[160:163], v[122:125]
	v_mfma_f32_16x16x32_bf16 v[118:121], v[140:143], v[168:171], v[118:121]
	v_mfma_f32_16x16x32_bf16 v[114:117], v[148:151], v[168:171], v[114:117]
	v_mfma_f32_16x16x32_bf16 v[106:109], v[140:143], v[176:179], v[106:109]
	v_mfma_f32_16x16x32_bf16 v[98:101], v[148:151], v[176:179], v[98:101]
	v_mfma_f32_16x16x32_bf16 v[90:93], v[140:143], v[184:187], v[90:93]
	v_mfma_f32_16x16x32_bf16 v[82:85], v[148:151], v[184:187], v[82:85]
	v_mfma_f32_16x16x32_bf16 v[126:129], v[144:147], v[164:167], v[126:129]
	v_mfma_f32_16x16x32_bf16 v[122:125], v[152:155], v[164:167], v[122:125]
	v_mfma_f32_16x16x32_bf16 v[118:121], v[144:147], v[172:175], v[118:121]
	v_mfma_f32_16x16x32_bf16 v[114:117], v[152:155], v[172:175], v[114:117]
	v_mfma_f32_16x16x32_bf16 v[106:109], v[144:147], v[180:183], v[106:109]
	v_mfma_f32_16x16x32_bf16 v[98:101], v[152:155], v[180:183], v[98:101]
	v_mfma_f32_16x16x32_bf16 v[90:93], v[144:147], v[188:191], v[90:93]
	v_mfma_f32_16x16x32_bf16 v[82:85], v[152:155], v[188:191], v[82:85]
	v_mfma_f32_16x16x32_bf16 v[110:113], v[192:195], v[160:163], v[110:113]
	v_mfma_f32_16x16x32_bf16 v[102:105], v[200:203], v[160:163], v[102:105]
	v_mfma_f32_16x16x32_bf16 v[94:97], v[192:195], v[168:171], v[94:97]
	v_mfma_f32_16x16x32_bf16 v[86:89], v[200:203], v[168:171], v[86:89]
	v_mfma_f32_16x16x32_bf16 v[78:81], v[192:195], v[176:179], v[78:81]
	v_mfma_f32_16x16x32_bf16 v[74:77], v[200:203], v[176:179], v[74:77]
	v_mfma_f32_16x16x32_bf16 v[70:73], v[192:195], v[184:187], v[70:73]
	v_mfma_f32_16x16x32_bf16 v[66:69], v[200:203], v[184:187], v[66:69]
	v_mfma_f32_16x16x32_bf16 v[110:113], v[196:199], v[164:167], v[110:113]
	v_mfma_f32_16x16x32_bf16 v[102:105], v[204:207], v[164:167], v[102:105]
	v_mfma_f32_16x16x32_bf16 v[94:97], v[196:199], v[172:175], v[94:97]
	v_mfma_f32_16x16x32_bf16 v[86:89], v[204:207], v[172:175], v[86:89]
	v_mfma_f32_16x16x32_bf16 v[78:81], v[196:199], v[180:183], v[78:81]
	v_mfma_f32_16x16x32_bf16 v[74:77], v[204:207], v[180:183], v[74:77]
	v_mfma_f32_16x16x32_bf16 v[70:73], v[196:199], v[188:191], v[70:73]
	v_mfma_f32_16x16x32_bf16 v[66:69], v[204:207], v[188:191], v[66:69]
	s_setprio 0
	s_barrier
; #define PG8_STAGE(bufoff, gbase, voff) do { _Pragma("unroll") for (int _i = 0; _i < 2; ++_i) \
;         __builtin_amdgcn_global_load_lds((const unsigned*)((const char*)(gbase) + (voff)[_i]), (LAS unsigned*)(lds + (bufoff) + ldsw + _i * 8192), 16, 0, 0); } while (0)
; #define PG8_LDA(dst, b, h) do { _Pragma("unroll") for (int m = 0; m < 4; ++m) _Pragma("unroll") for (int k = 0; k < 2; ++k) dst[m][k] = *(const LAS bf16x8*)(lds + PG8_SA(b, h) + aoff + m * 2048 + k * 1024); } while (0)
; #define PG8_LDB(dst, b, h) do { _Pragma("unroll") for (int n = 0; n < 2; ++n) _Pragma("unroll") for (int k = 0; k < 2; ++k) dst[n][k] = *(const LAS bf16x8*)(lds + PG8_SB(b, h) + boff + n * 2048 + k * 1024); } while (0)
; #define PG8_MMA(ai, bj, At, Bt) do { __builtin_amdgcn_s_setprio(1); _Pragma("unroll") for (int m = 0; m < 4; ++m) _Pragma("unroll") for (int n = 0; n < 2; ++n) _Pragma("unroll") for (int k = 0; k < 2; ++k) \
;         acc[ai][bj][m][n] = __builtin_amdgcn_mfma_f32_16x16x32_bf16(Bt[n][k], At[m][k], acc[ai][bj][m][n], 0, 0, 0); __builtin_amdgcn_s_setprio(0); } while (0)
; #define PG8_WAIT_V(n) asm volatile("s_waitcnt vmcnt(" #n ")" ::: "memory")
; #define PG8_WAIT_L(n) asm volatile("s_waitcnt lgkmcnt(" #n ")" ::: "memory")
; #define PG8_BAR __builtin_amdgcn_s_barrier()
; #define PG8_SCHED __builtin_amdgcn_sched_barrier(0)
; template <class Epi, class Sched>
; __device__ __forceinline__ void gemm_phase(LAS unsigned char* lds, const Gemm g, const Sched& S, const Epi& E) {
;     ...
;             PG8_LDB(B1, 1, 1); PG8_STAGE(PG8_SB(1, 0), b3, voffB);
;             PG8_BAR; PG8_WAIT_L(0); PG8_MMA(0, 1, At, B1); PG8_BAR;
;             PG8_LDA(At, 1, 1); PG8_STAGE(PG8_SA(1, 0), a3, voffA);
;             PG8_BAR; PG8_WAIT_L(0); PG8_MMA(1, 0, At, B0); PG8_BAR; PG8_SCHED;
;             PG8_STAGE(PG8_SB(1, 1), b3 + hstep, voffB);
;             PG8_WAIT_V(6); PG8_BAR; PG8_MMA(1, 1, At, B1); PG8_BAR;
	s_add_i32 s38, s52, s65
	v_lshl_add_u64 v[156:157], v[156:157], 0, s[36:37]
	s_mov_b32 m0, s38
	s_nop 0
	global_load_lds_dwordx4 v[156:157], off
	v_lshl_add_u64 v[156:157], v[210:211], 0, s[36:37]
	s_add_i32 m0, s38, 0x2000
	s_nop 0
	global_load_lds_dwordx4 v[156:157], off
	s_mov_b32 m0, s68
	v_lshl_add_u64 v[156:157], v[212:213], 0, s[36:37]
	global_load_lds_dwordx4 v[156:157], off
	v_lshl_add_u64 v[156:157], v[214:215], 0, s[36:37]
	s_mov_b32 m0, s69
	s_nop 0
	global_load_lds_dwordx4 v[156:157], off
	ds_read_b128 v[160:163], v139 offset:49152
	ds_read_b128 v[164:167], v139 offset:50176
	ds_read_b128 v[168:171], v139 offset:51200
	ds_read_b128 v[172:175], v139 offset:52224
	ds_read_b128 v[176:179], v139 offset:53248
	ds_read_b128 v[180:183], v139 offset:54272
	ds_read_b128 v[184:187], v139 offset:55296
	ds_read_b128 v[188:191], v139 offset:56320
	s_waitcnt vmcnt(6)
	s_waitcnt lgkmcnt(0)
	s_barrier
	s_setprio 1
	v_mfma_f32_16x16x32_bf16 v[62:65], v[140:143], v[160:163], v[62:65]
	v_mfma_f32_16x16x32_bf16 v[58:61], v[148:151], v[160:163], v[58:61]
	v_mfma_f32_16x16x32_bf16 v[54:57], v[140:143], v[168:171], v[54:57]
	v_mfma_f32_16x16x32_bf16 v[50:53], v[148:151], v[168:171], v[50:53]
	v_mfma_f32_16x16x32_bf16 v[38:41], v[140:143], v[176:179], v[38:41]
	v_mfma_f32_16x16x32_bf16 v[34:37], v[148:151], v[176:179], v[34:37]
	v_mfma_f32_16x16x32_bf16 v[22:25], v[140:143], v[184:187], v[22:25]
	v_mfma_f32_16x16x32_bf16 v[18:21], v[148:151], v[184:187], v[18:21]
	v_mfma_f32_16x16x32_bf16 v[62:65], v[144:147], v[164:167], v[62:65]
	v_mfma_f32_16x16x32_bf16 v[58:61], v[152:155], v[164:167], v[58:61]
	v_mfma_f32_16x16x32_bf16 v[54:57], v[144:147], v[172:175], v[54:57]
	v_mfma_f32_16x16x32_bf16 v[50:53], v[152:155], v[172:175], v[50:53]
	v_mfma_f32_16x16x32_bf16 v[38:41], v[144:147], v[180:183], v[38:41]
	v_mfma_f32_16x16x32_bf16 v[34:37], v[152:155], v[180:183], v[34:37]
	v_mfma_f32_16x16x32_bf16 v[22:25], v[144:147], v[188:191], v[22:25]
	v_mfma_f32_16x16x32_bf16 v[18:21], v[152:155], v[188:191], v[18:21]
	s_add_u32 s38, s56, 0x80080
	s_addc_u32 s39, s57, 0
	s_add_i32 s52, s53, s65
	v_lshl_add_u64 v[140:141], s[38:39], 0, v[0:1]
	s_mov_b32 m0, s52
	s_nop 0
	global_load_lds_dwordx4 v[140:141], off
	v_lshl_add_u64 v[140:141], s[38:39], 0, v[130:131]
	s_add_i32 m0, s52, 0x2000
	s_nop 0
	global_load_lds_dwordx4 v[140:141], off
	v_mfma_f32_16x16x32_bf16 v[46:49], v[192:195], v[160:163], v[46:49]
	v_mfma_f32_16x16x32_bf16 v[42:45], v[200:203], v[160:163], v[42:45]
	v_mfma_f32_16x16x32_bf16 v[30:33], v[192:195], v[168:171], v[30:33]
	v_mfma_f32_16x16x32_bf16 v[26:29], v[200:203], v[168:171], v[26:29]
	v_mfma_f32_16x16x32_bf16 v[14:17], v[192:195], v[176:179], v[14:17]
	v_mfma_f32_16x16x32_bf16 v[10:13], v[200:203], v[176:179], v[10:13]
	v_mfma_f32_16x16x32_bf16 v[6:9], v[192:195], v[184:187], v[6:9]
	v_mfma_f32_16x16x32_bf16 v[2:5], v[200:203], v[184:187], v[2:5]
	v_mfma_f32_16x16x32_bf16 v[46:49], v[196:199], v[164:167], v[46:49]
	v_mfma_f32_16x16x32_bf16 v[42:45], v[204:207], v[164:167], v[42:45]
	v_mfma_f32_16x16x32_bf16 v[30:33], v[196:199], v[172:175], v[30:33]
	v_mfma_f32_16x16x32_bf16 v[26:29], v[204:207], v[172:175], v[26:29]
	v_mfma_f32_16x16x32_bf16 v[14:17], v[196:199], v[180:183], v[14:17]
	v_mfma_f32_16x16x32_bf16 v[10:13], v[204:207], v[180:183], v[10:13]
	v_mfma_f32_16x16x32_bf16 v[6:9], v[196:199], v[188:191], v[6:9]
	v_mfma_f32_16x16x32_bf16 v[2:5], v[204:207], v[188:191], v[2:5]
	s_setprio 0
	s_add_i32 s73, s73, 2
	s_add_u32 s71, s71, 0x100
	s_addc_u32 s72, s72, 0
	s_cmp_gt_u32 s73, 5
	s_mov_b64 s[52:53], s[54:55]
	s_barrier
	s_cbranch_scc0 .LBB0_113
; #define PG8_WAIT_V(n) asm volatile("s_waitcnt vmcnt(" #n ")" ::: "memory")
; #define PG8_BAR __builtin_amdgcn_s_barrier()
;     __device__ __forceinline__ void operator()(const f32x4 (&acc)[2][2][4][2], const Unit& u, int wr, int wc, int fr, int fq) const {
;         const int row0 = u.pm * BM + wr * 64 + fr, col0 = u.pn * BM + wc * 32 + 4 * fq;
;         float* base = part + (size_t)u.ks * Mp * ldc;
; #pragma unroll
;         for (int ai = 0; ai < 2; ++ai)
; #pragma unroll
;             for (int m = 0; m < 4; ++m) { float* rowp = base + (size_t)(row0 + ai * HALF + m * 16) * ldc + col0;
; #pragma unroll
;                 for (int bj = 0; bj < 2; ++bj)
; #pragma unroll
;                     for (int n = 0; n < 2; ++n) *(f32x4*)(rowp + bj * HALF + n * 16) = acc[ai][bj][m][n]; }
;     }
; template <class Epi, class Sched>
; __device__ __forceinline__ void gemm_phase(LAS unsigned char* lds, const Gemm g, const Sched& S, const Epi& E) {
;     ...
;         cur = nxt; cA = nA; cB = nB; ++ui;
;     }
;     PG8_WAIT_V(0);
;     if (wr == 0) PG8_BAR;
;     PG8_BAR;
	s_ashr_i32 s11, s10, 31
	s_lshl_b64 s[10:11], s[10:11], 24
	v_lshl_or_b32 v140, s26, 8, v138
	s_add_u32 s10, s8, s10
	v_lshl_add_u32 v142, s24, 8, v136
	s_addc_u32 s11, s9, s11
	v_ashrrev_i32_e32 v141, 31, v140
	v_ashrrev_i32_e32 v143, 31, v142
	v_lshl_add_u64 v[140:141], v[140:141], 2, s[10:11]
	v_lshlrev_b64 v[144:145], 13, v[142:143]
	v_lshl_add_u64 v[144:145], v[140:141], 0, v[144:145]
	global_store_dwordx4 v[144:145], v[126:129], off
	global_store_dwordx4 v[144:145], v[122:125], off offset:64
	global_store_dwordx4 v[144:145], v[110:113], off offset:512
	global_store_dwordx4 v[144:145], v[102:105], off offset:576
	s_mov_b64 s[10:11], 0x100000
	s_mov_b32 s26, s40
	v_or_b32_e32 v102, 16, v142
	v_ashrrev_i32_e32 v103, 31, v102
	v_lshlrev_b64 v[102:103], 13, v[102:103]
	v_lshl_add_u64 v[102:103], v[140:141], 0, v[102:103]
	global_store_dwordx4 v[102:103], v[118:121], off
	global_store_dwordx4 v[102:103], v[114:117], off offset:64
	global_store_dwordx4 v[102:103], v[94:97], off offset:512
	global_store_dwordx4 v[102:103], v[86:89], off offset:576
	s_mov_b32 s24, s44
	s_mov_b64 s[54:55], s[50:51]
	v_or_b32_e32 v86, 32, v142
	v_ashrrev_i32_e32 v87, 31, v86
	v_lshlrev_b64 v[86:87], 13, v[86:87]
	v_lshl_add_u64 v[86:87], v[140:141], 0, v[86:87]
	global_store_dwordx4 v[86:87], v[106:109], off
	global_store_dwordx4 v[86:87], v[98:101], off offset:64
	global_store_dwordx4 v[86:87], v[78:81], off offset:512
	global_store_dwordx4 v[86:87], v[74:77], off offset:576
	s_mov_b64 s[52:53], s[48:49]
	s_nop 0
	v_or_b32_e32 v74, 48, v142
	v_ashrrev_i32_e32 v75, 31, v74
	v_lshlrev_b64 v[74:75], 13, v[74:75]
	v_lshl_add_u64 v[74:75], v[140:141], 0, v[74:75]
	global_store_dwordx4 v[74:75], v[90:93], off
	global_store_dwordx4 v[74:75], v[82:85], off offset:64
	global_store_dwordx4 v[74:75], v[70:73], off offset:512
	global_store_dwordx4 v[74:75], v[66:69], off offset:576
	s_nop 1
	v_add_co_u32_e32 v68, vcc, s93, v144
	v_lshl_add_u64 v[66:67], v[144:145], 0, s[10:11]
	s_nop 0
	v_addc_co_u32_e32 v69, vcc, 0, v145, vcc
	s_mov_b64 s[10:11], 0x120000
	global_store_dwordx4 v[68:69], v[62:65], off
	global_store_dwordx4 v[66:67], v[58:61], off offset:64
	global_store_dwordx4 v[66:67], v[46:49], off offset:512
	global_store_dwordx4 v[66:67], v[42:45], off offset:576
	s_nop 1
	v_lshl_add_u64 v[42:43], v[144:145], 0, s[10:11]
	s_mov_b32 s10, 0x120000
	v_add_co_u32_e32 v44, vcc, s10, v144
	s_mov_b64 s[10:11], 0x140000
	s_nop 0
	v_addc_co_u32_e32 v45, vcc, 0, v145, vcc
	global_store_dwordx4 v[44:45], v[54:57], off
	global_store_dwordx4 v[42:43], v[50:53], off offset:64
	global_store_dwordx4 v[42:43], v[30:33], off offset:512
	global_store_dwordx4 v[42:43], v[26:29], off offset:576
	s_nop 1
	v_lshl_add_u64 v[26:27], v[144:145], 0, s[10:11]
	s_mov_b32 s10, 0x140000
	v_add_co_u32_e32 v28, vcc, s10, v144
	s_mov_b64 s[10:11], 0x160000
	s_nop 0
	v_addc_co_u32_e32 v29, vcc, 0, v145, vcc
	global_store_dwordx4 v[28:29], v[38:41], off
	global_store_dwordx4 v[26:27], v[34:37], off offset:64
	global_store_dwordx4 v[26:27], v[14:17], off offset:512
	global_store_dwordx4 v[26:27], v[10:13], off offset:576
	s_nop 1
	v_add_co_u32_e32 v12, vcc, 0x160000, v144
	v_lshl_add_u64 v[10:11], v[144:145], 0, s[10:11]
	s_nop 0
	v_addc_co_u32_e32 v13, vcc, 0, v145, vcc
	s_and_b64 vcc, exec, s[46:47]
	s_mov_b32 s10, s28
	global_store_dwordx4 v[12:13], v[22:25], off
	global_store_dwordx4 v[10:11], v[18:21], off offset:64
	global_store_dwordx4 v[10:11], v[6:9], off offset:512
	global_store_dwordx4 v[10:11], v[2:5], off offset:576
	s_cbranch_vccz .LBB0_110
	s_waitcnt vmcnt(0)
	s_cmpk_gt_u32 s60, 0xff
	s_cbranch_scc1 .LBB0_117
	s_barrier

; #define PG8_STAGE(bufoff, gbase, voff) do { _Pragma("unroll") for (int _i = 0; _i < 2; ++_i) \
;         __builtin_amdgcn_global_load_lds((const unsigned*)((const char*)(gbase) + (voff)[_i]), (LAS unsigned*)(lds + (bufoff) + ldsw + _i * 8192), 16, 0, 0); } while (0)
; #define PG8_LDA(dst, b, h) do { _Pragma("unroll") for (int m = 0; m < 4; ++m) _Pragma("unroll") for (int k = 0; k < 2; ++k) dst[m][k] = *(const LAS bf16x8*)(lds + PG8_SA(b, h) + aoff + m * 2048 + k * 1024); } while (0)
; #define PG8_LDB(dst, b, h) do { _Pragma("unroll") for (int n = 0; n < 2; ++n) _Pragma("unroll") for (int k = 0; k < 2; ++k) dst[n][k] = *(const LAS bf16x8*)(lds + PG8_SB(b, h) + boff + n * 2048 + k * 1024); } while (0)
; #define PG8_MMA(ai, bj, At, Bt) do { __builtin_amdgcn_s_setprio(1); _Pragma("unroll") for (int m = 0; m < 4; ++m) _Pragma("unroll") for (int n = 0; n < 2; ++n) _Pragma("unroll") for (int k = 0; k < 2; ++k) \
;         acc[ai][bj][m][n] = __builtin_amdgcn_mfma_f32_16x16x32_bf16(Bt[n][k], At[m][k], acc[ai][bj][m][n], 0, 0, 0); __builtin_amdgcn_s_setprio(0); } while (0)
; #define PG8_WAIT_L(n) asm volatile("s_waitcnt lgkmcnt(" #n ")" ::: "memory")
; #define PG8_BAR __builtin_amdgcn_s_barrier()
; #define PG8_SCHED __builtin_amdgcn_sched_barrier(0)
; template <class Epi, class Sched>
; __device__ __forceinline__ void gemm_phase(LAS unsigned char* lds, const Gemm g, const Sched& S, const Epi& E) {
;     ...
;             const bool last = (t == nt - 2);
;             const char* a1 = cA + (size_t)(t + 1) * kstep;
;             const char* a2 = last ? nA : cA + (size_t)(t + 2) * kstep; const char* b2 = last ? nB : cB + (size_t)(t + 2) * kstep;
;             const char* a3 = a2 + kstep; const char* b3 = b2 + kstep;
;             PG8_LDB(B0, 0, 0); PG8_SCHED; PG8_LDA(At, 0, 0); PG8_STAGE(PG8_SA(1, 1), a1 + hstep, voffA);
;             PG8_WAIT_L(8); PG8_BAR; PG8_WAIT_L(0); PG8_MMA(0, 0, At, B0); PG8_BAR; PG8_SCHED;
;             PG8_LDB(B1, 0, 1); PG8_STAGE(PG8_SB(0, 0), b2, voffB);
;             PG8_BAR; PG8_WAIT_L(0); PG8_MMA(0, 1, At, B1); PG8_BAR;
;             PG8_LDA(At, 0, 1); PG8_STAGE(PG8_SA(0, 0), a2, voffA);
;             PG8_BAR; PG8_WAIT_L(0); PG8_MMA(1, 0, At, B0); PG8_BAR; PG8_SCHED;
.LBB0_354:
	s_add_u32 s38, s50, 0xfff80080
	s_addc_u32 s39, s51, -1
	s_cmp_eq_u32 s70, 28
	s_cselect_b32 s55, s9, s39
	s_cselect_b32 s54, s66, s38
	s_cselect_b32 s53, s43, s69
	s_cselect_b32 s52, s67, s68
	v_lshl_add_u64 v[156:157], s[50:51], 0, v[138:139]
	s_add_i32 m0, s29, 0xc000
	s_nop 0
	global_load_lds_dwordx4 v[156:157], off
	v_lshl_add_u64 v[156:157], s[50:51], 0, v[136:137]
	s_add_i32 m0, s29, 0xe000
	s_nop 0
	global_load_lds_dwordx4 v[156:157], off
	s_add_i32 s71, 0, 0x10000
	v_add_u32_e32 v156, s71, v145
	ds_read_b128 v[140:143], v156
	ds_read_b128 v[148:151], v156 offset:1024
	ds_read_b128 v[152:155], v156 offset:2048
	ds_read_b128 v[160:163], v156 offset:3072
	ds_read_b128 v[164:167], v147
	ds_read_b128 v[168:171], v147 offset:1024
	ds_read_b128 v[172:175], v147 offset:2048
	ds_read_b128 v[176:179], v147 offset:3072
	ds_read_b128 v[180:183], v147 offset:4096
	ds_read_b128 v[184:187], v147 offset:5120
	ds_read_b128 v[188:191], v147 offset:6144
	ds_read_b128 v[192:195], v147 offset:7168
	s_add_i32 s38, 0, 0x14000
	v_add_u32_e32 v156, s38, v145
	ds_read_b128 v[196:199], v156
	ds_read_b128 v[200:203], v156 offset:1024
	ds_read_b128 v[204:207], v156 offset:2048
	ds_read_b128 v[210:213], v156 offset:3072
	s_waitcnt vmcnt(8)
	s_waitcnt lgkmcnt(4)
	s_barrier
	s_waitcnt lgkmcnt(0)
	s_setprio 1
	v_mfma_f32_16x16x32_bf16 v[126:129], v[140:143], v[164:167], v[126:129]
	v_mfma_f32_16x16x32_bf16 v[122:125], v[152:155], v[164:167], v[122:125]
	v_mfma_f32_16x16x32_bf16 v[118:121], v[140:143], v[172:175], v[118:121]
	v_mfma_f32_16x16x32_bf16 v[110:113], v[152:155], v[172:175], v[110:113]
	v_mfma_f32_16x16x32_bf16 v[102:105], v[140:143], v[180:183], v[102:105]
	v_mfma_f32_16x16x32_bf16 v[94:97], v[152:155], v[180:183], v[94:97]
	v_mfma_f32_16x16x32_bf16 v[86:89], v[140:143], v[188:191], v[86:89]
	v_mfma_f32_16x16x32_bf16 v[78:81], v[152:155], v[188:191], v[78:81]
	v_mfma_f32_16x16x32_bf16 v[126:129], v[148:151], v[168:171], v[126:129]
	v_mfma_f32_16x16x32_bf16 v[122:125], v[160:163], v[168:171], v[122:125]
	v_mfma_f32_16x16x32_bf16 v[118:121], v[148:151], v[176:179], v[118:121]
	v_mfma_f32_16x16x32_bf16 v[110:113], v[160:163], v[176:179], v[110:113]
	v_mfma_f32_16x16x32_bf16 v[102:105], v[148:151], v[184:187], v[102:105]
	v_mfma_f32_16x16x32_bf16 v[94:97], v[160:163], v[184:187], v[94:97]
	v_mfma_f32_16x16x32_bf16 v[86:89], v[148:151], v[192:195], v[86:89]
	v_mfma_f32_16x16x32_bf16 v[78:81], v[160:163], v[192:195], v[78:81]
	v_mfma_f32_16x16x32_bf16 v[114:117], v[196:199], v[164:167], v[114:117]
	v_mfma_f32_16x16x32_bf16 v[106:109], v[204:207], v[164:167], v[106:109]
	v_mfma_f32_16x16x32_bf16 v[98:101], v[196:199], v[172:175], v[98:101]
	v_mfma_f32_16x16x32_bf16 v[90:93], v[204:207], v[172:175], v[90:93]
	v_mfma_f32_16x16x32_bf16 v[82:85], v[196:199], v[180:183], v[82:85]
	v_mfma_f32_16x16x32_bf16 v[74:77], v[204:207], v[180:183], v[74:77]
	v_mfma_f32_16x16x32_bf16 v[70:73], v[196:199], v[188:191], v[70:73]
	v_mfma_f32_16x16x32_bf16 v[66:69], v[204:207], v[188:191], v[66:69]
	v_mfma_f32_16x16x32_bf16 v[114:117], v[200:203], v[168:171], v[114:117]
	v_mfma_f32_16x16x32_bf16 v[106:109], v[210:213], v[168:171], v[106:109]
	v_mfma_f32_16x16x32_bf16 v[98:101], v[200:203], v[176:179], v[98:101]
	v_mfma_f32_16x16x32_bf16 v[90:93], v[210:213], v[176:179], v[90:93]
	v_mfma_f32_16x16x32_bf16 v[82:85], v[200:203], v[184:187], v[82:85]
	v_mfma_f32_16x16x32_bf16 v[74:77], v[210:213], v[184:187], v[74:77]
	v_mfma_f32_16x16x32_bf16 v[70:73], v[200:203], v[192:195], v[70:73]
	v_mfma_f32_16x16x32_bf16 v[66:69], v[210:213], v[192:195], v[66:69]
	s_setprio 0
	s_barrier
	s_add_i32 s39, s71, s56
	v_lshl_add_u64 v[156:157], s[52:53], 0, v[0:1]
	s_mov_b32 m0, s39
	v_lshl_add_u64 v[214:215], s[52:53], 0, v[134:135]
	global_load_lds_dwordx4 v[156:157], off
	s_add_i32 m0, s39, 0x2000
	s_nop 0
	global_load_lds_dwordx4 v[214:215], off
	s_mov_b32 m0, s29
	v_lshl_add_u64 v[216:217], s[54:55], 0, v[130:131]
	global_load_lds_dwordx4 v[216:217], off
	v_lshl_add_u64 v[224:225], s[54:55], 0, v[132:133]
	s_mov_b32 m0, s41
	s_nop 0
	global_load_lds_dwordx4 v[224:225], off
	ds_read_b128 v[164:167], v147 offset:16384
	ds_read_b128 v[168:171], v147 offset:17408
	ds_read_b128 v[172:175], v147 offset:18432
	ds_read_b128 v[176:179], v147 offset:19456
	ds_read_b128 v[180:183], v147 offset:20480
	ds_read_b128 v[184:187], v147 offset:21504
	ds_read_b128 v[188:191], v147 offset:22528
	ds_read_b128 v[192:195], v147 offset:23552
	s_waitcnt vmcnt(6)
	s_waitcnt lgkmcnt(0)
	s_barrier
; #define PG8_STAGE(bufoff, gbase, voff) do { _Pragma("unroll") for (int _i = 0; _i < 2; ++_i) \
;         __builtin_amdgcn_global_load_lds((const unsigned*)((const char*)(gbase) + (voff)[_i]), (LAS unsigned*)(lds + (bufoff) + ldsw + _i * 8192), 16, 0, 0); } while (0)
; #define PG8_LDA(dst, b, h) do { _Pragma("unroll") for (int m = 0; m < 4; ++m) _Pragma("unroll") for (int k = 0; k < 2; ++k) dst[m][k] = *(const LAS bf16x8*)(lds + PG8_SA(b, h) + aoff + m * 2048 + k * 1024); } while (0)
; #define PG8_LDB(dst, b, h) do { _Pragma("unroll") for (int n = 0; n < 2; ++n) _Pragma("unroll") for (int k = 0; k < 2; ++k) dst[n][k] = *(const LAS bf16x8*)(lds + PG8_SB(b, h) + boff + n * 2048 + k * 1024); } while (0)
; #define PG8_MMA(ai, bj, At, Bt) do { __builtin_amdgcn_s_setprio(1); _Pragma("unroll") for (int m = 0; m < 4; ++m) _Pragma("unroll") for (int n = 0; n < 2; ++n) _Pragma("unroll") for (int k = 0; k < 2; ++k) \
;         acc[ai][bj][m][n] = __builtin_amdgcn_mfma_f32_16x16x32_bf16(Bt[n][k], At[m][k], acc[ai][bj][m][n], 0, 0, 0); __builtin_amdgcn_s_setprio(0); } while (0)
; #define PG8_WAIT_V(n) asm volatile("s_waitcnt vmcnt(" #n ")" ::: "memory")
; #define PG8_WAIT_L(n) asm volatile("s_waitcnt lgkmcnt(" #n ")" ::: "memory")
; #define PG8_BAR __builtin_amdgcn_s_barrier()
; #define PG8_SCHED __builtin_amdgcn_sched_barrier(0)
; template <class Epi, class Sched>
; __device__ __forceinline__ void gemm_phase(LAS unsigned char* lds, const Gemm g, const Sched& S, const Epi& E) {
;     ...
;             PG8_BAR; PG8_WAIT_L(0); PG8_MMA(1, 0, At, B0); PG8_BAR; PG8_SCHED;
;             PG8_STAGE(PG8_SB(0, 1), b2 + hstep, voffB);
;             PG8_WAIT_V(6); PG8_BAR; PG8_MMA(1, 1, At, B1); PG8_BAR;
;             PG8_LDB(B0, 1, 0); PG8_SCHED; PG8_LDA(At, 1, 0); PG8_STAGE(PG8_SA(0, 1), a2 + hstep, voffA);
;             PG8_WAIT_L(8); PG8_BAR; PG8_WAIT_L(0); PG8_MMA(0, 0, At, B0); PG8_BAR; PG8_SCHED;
	s_setprio 1
	v_mfma_f32_16x16x32_bf16 v[62:65], v[140:143], v[164:167], v[62:65]
	v_mfma_f32_16x16x32_bf16 v[58:61], v[152:155], v[164:167], v[58:61]
	v_mfma_f32_16x16x32_bf16 v[54:57], v[140:143], v[172:175], v[54:57]
	v_mfma_f32_16x16x32_bf16 v[46:49], v[152:155], v[172:175], v[46:49]
	v_mfma_f32_16x16x32_bf16 v[38:41], v[140:143], v[180:183], v[38:41]
	v_mfma_f32_16x16x32_bf16 v[30:33], v[152:155], v[180:183], v[30:33]
	v_mfma_f32_16x16x32_bf16 v[22:25], v[140:143], v[188:191], v[22:25]
	v_mfma_f32_16x16x32_bf16 v[14:17], v[152:155], v[188:191], v[14:17]
	v_mfma_f32_16x16x32_bf16 v[62:65], v[148:151], v[168:171], v[62:65]
	v_mfma_f32_16x16x32_bf16 v[58:61], v[160:163], v[168:171], v[58:61]
	v_mfma_f32_16x16x32_bf16 v[54:57], v[148:151], v[176:179], v[54:57]
	v_mfma_f32_16x16x32_bf16 v[46:49], v[160:163], v[176:179], v[46:49]
	v_mfma_f32_16x16x32_bf16 v[38:41], v[148:151], v[184:187], v[38:41]
	v_mfma_f32_16x16x32_bf16 v[30:33], v[160:163], v[184:187], v[30:33]
	v_mfma_f32_16x16x32_bf16 v[22:25], v[148:151], v[192:195], v[22:25]
	v_mfma_f32_16x16x32_bf16 v[14:17], v[160:163], v[192:195], v[14:17]
	s_add_u32 s72, s52, 0x80000
	s_addc_u32 s73, s53, 0
	s_add_i32 s38, s38, s56
	v_lshl_add_u64 v[140:141], s[72:73], 0, v[0:1]
	s_mov_b32 m0, s38
	s_nop 0
	global_load_lds_dwordx4 v[140:141], off
	v_lshl_add_u64 v[140:141], s[72:73], 0, v[134:135]
	s_add_i32 m0, s38, 0x2000
	s_nop 0
	global_load_lds_dwordx4 v[140:141], off
	v_mfma_f32_16x16x32_bf16 v[50:53], v[196:199], v[164:167], v[50:53]
	v_mfma_f32_16x16x32_bf16 v[42:45], v[204:207], v[164:167], v[42:45]
	v_mfma_f32_16x16x32_bf16 v[34:37], v[196:199], v[172:175], v[34:37]
	v_mfma_f32_16x16x32_bf16 v[26:29], v[204:207], v[172:175], v[26:29]
	v_mfma_f32_16x16x32_bf16 v[18:21], v[196:199], v[180:183], v[18:21]
	v_mfma_f32_16x16x32_bf16 v[10:13], v[204:207], v[180:183], v[10:13]
	v_mfma_f32_16x16x32_bf16 v[6:9], v[196:199], v[188:191], v[6:9]
	v_mfma_f32_16x16x32_bf16 v[2:5], v[204:207], v[188:191], v[2:5]
	v_mfma_f32_16x16x32_bf16 v[50:53], v[200:203], v[168:171], v[50:53]
	v_mfma_f32_16x16x32_bf16 v[42:45], v[210:213], v[168:171], v[42:45]
	v_mfma_f32_16x16x32_bf16 v[34:37], v[200:203], v[176:179], v[34:37]
	v_mfma_f32_16x16x32_bf16 v[26:29], v[210:213], v[176:179], v[26:29]
	v_mfma_f32_16x16x32_bf16 v[18:21], v[200:203], v[184:187], v[18:21]
	v_mfma_f32_16x16x32_bf16 v[10:13], v[210:213], v[184:187], v[10:13]
	v_mfma_f32_16x16x32_bf16 v[6:9], v[200:203], v[192:195], v[6:9]
	v_mfma_f32_16x16x32_bf16 v[2:5], v[210:213], v[192:195], v[2:5]
	s_setprio 0
	s_barrier
	s_add_u32 s54, s54, 0x80000
	s_addc_u32 s55, s55, 0
	s_mov_b32 m0, s57
	v_lshl_add_u64 v[196:197], s[54:55], 0, v[130:131]
	global_load_lds_dwordx4 v[196:197], off
	v_lshl_add_u64 v[196:197], s[54:55], 0, v[132:133]
	s_mov_b32 m0, s58
	s_nop 0
	global_load_lds_dwordx4 v[196:197], off
	s_add_i32 s38, 0, 0x18000
	v_add_u32_e32 v160, s38, v145
	ds_read_b128 v[140:143], v160
	ds_read_b128 v[148:151], v160 offset:1024
	ds_read_b128 v[152:155], v160 offset:2048
	ds_read_b128 v[160:163], v160 offset:3072
	ds_read_b128 v[164:167], v147 offset:32768
	ds_read_b128 v[168:171], v147 offset:33792
	ds_read_b128 v[172:175], v147 offset:34816
	ds_read_b128 v[176:179], v147 offset:35840
	ds_read_b128 v[180:183], v147 offset:36864
	ds_read_b128 v[184:187], v147 offset:37888
	ds_read_b128 v[188:191], v147 offset:38912
	ds_read_b128 v[192:195], v147 offset:39936
	s_add_i32 s39, 0, 0x1c000
	v_add_u32_e32 v210, s39, v145
	ds_read_b128 v[196:199], v210
	ds_read_b128 v[200:203], v210 offset:1024
	ds_read_b128 v[204:207], v210 offset:2048
	ds_read_b128 v[210:213], v210 offset:3072
	s_waitcnt vmcnt(8)
	s_waitcnt lgkmcnt(4)
	s_barrier
	s_waitcnt lgkmcnt(0)
	s_setprio 1
	v_mfma_f32_16x16x32_bf16 v[126:129], v[140:143], v[164:167], v[126:129]
	v_mfma_f32_16x16x32_bf16 v[122:125], v[152:155], v[164:167], v[122:125]
	v_mfma_f32_16x16x32_bf16 v[118:121], v[140:143], v[172:175], v[118:121]
	v_mfma_f32_16x16x32_bf16 v[110:113], v[152:155], v[172:175], v[110:113]
	v_mfma_f32_16x16x32_bf16 v[102:105], v[140:143], v[180:183], v[102:105]
	v_mfma_f32_16x16x32_bf16 v[94:97], v[152:155], v[180:183], v[94:97]
	v_mfma_f32_16x16x32_bf16 v[86:89], v[140:143], v[188:191], v[86:89]
	v_mfma_f32_16x16x32_bf16 v[78:81], v[152:155], v[188:191], v[78:81]
	v_mfma_f32_16x16x32_bf16 v[126:129], v[148:151], v[168:171], v[126:129]
	v_mfma_f32_16x16x32_bf16 v[122:125], v[160:163], v[168:171], v[122:125]
	v_mfma_f32_16x16x32_bf16 v[118:121], v[148:151], v[176:179], v[118:121]
	v_mfma_f32_16x16x32_bf16 v[110:113], v[160:163], v[176:179], v[110:113]
	v_mfma_f32_16x16x32_bf16 v[102:105], v[148:151], v[184:187], v[102:105]
	v_mfma_f32_16x16x32_bf16 v[94:97], v[160:163], v[184:187], v[94:97]
	v_mfma_f32_16x16x32_bf16 v[86:89], v[148:151], v[192:195], v[86:89]
	v_mfma_f32_16x16x32_bf16 v[78:81], v[160:163], v[192:195], v[78:81]
	v_mfma_f32_16x16x32_bf16 v[114:117], v[196:199], v[164:167], v[114:117]
	v_mfma_f32_16x16x32_bf16 v[106:109], v[204:207], v[164:167], v[106:109]
	v_mfma_f32_16x16x32_bf16 v[98:101], v[196:199], v[172:175], v[98:101]
	v_mfma_f32_16x16x32_bf16 v[90:93], v[204:207], v[172:175], v[90:93]
	v_mfma_f32_16x16x32_bf16 v[82:85], v[196:199], v[180:183], v[82:85]
	v_mfma_f32_16x16x32_bf16 v[74:77], v[204:207], v[180:183], v[74:77]
	v_mfma_f32_16x16x32_bf16 v[70:73], v[196:199], v[188:191], v[70:73]
	v_mfma_f32_16x16x32_bf16 v[66:69], v[204:207], v[188:191], v[66:69]
	v_mfma_f32_16x16x32_bf16 v[114:117], v[200:203], v[168:171], v[114:117]
	v_mfma_f32_16x16x32_bf16 v[106:109], v[210:213], v[168:171], v[106:109]
	v_mfma_f32_16x16x32_bf16 v[98:101], v[200:203], v[176:179], v[98:101]
	v_mfma_f32_16x16x32_bf16 v[90:93], v[210:213], v[176:179], v[90:93]
	v_mfma_f32_16x16x32_bf16 v[82:85], v[200:203], v[184:187], v[82:85]
	v_mfma_f32_16x16x32_bf16 v[74:77], v[210:213], v[184:187], v[74:77]
	v_mfma_f32_16x16x32_bf16 v[70:73], v[200:203], v[192:195], v[70:73]
	v_mfma_f32_16x16x32_bf16 v[66:69], v[210:213], v[192:195], v[66:69]
	s_setprio 0
	s_barrier
; #define PG8_STAGE(bufoff, gbase, voff) do { _Pragma("unroll") for (int _i = 0; _i < 2; ++_i) \
;         __builtin_amdgcn_global_load_lds((const unsigned*)((const char*)(gbase) + (voff)[_i]), (LAS unsigned*)(lds + (bufoff) + ldsw + _i * 8192), 16, 0, 0); } while (0)
; #define PG8_LDA(dst, b, h) do { _Pragma("unroll") for (int m = 0; m < 4; ++m) _Pragma("unroll") for (int k = 0; k < 2; ++k) dst[m][k] = *(const LAS bf16x8*)(lds + PG8_SA(b, h) + aoff + m * 2048 + k * 1024); } while (0)
; #define PG8_LDB(dst, b, h) do { _Pragma("unroll") for (int n = 0; n < 2; ++n) _Pragma("unroll") for (int k = 0; k < 2; ++k) dst[n][k] = *(const LAS bf16x8*)(lds + PG8_SB(b, h) + boff + n * 2048 + k * 1024); } while (0)
; #define PG8_MMA(ai, bj, At, Bt) do { __builtin_amdgcn_s_setprio(1); _Pragma("unroll") for (int m = 0; m < 4; ++m) _Pragma("unroll") for (int n = 0; n < 2; ++n) _Pragma("unroll") for (int k = 0; k < 2; ++k) \
;         acc[ai][bj][m][n] = __builtin_amdgcn_mfma_f32_16x16x32_bf16(Bt[n][k], At[m][k], acc[ai][bj][m][n], 0, 0, 0); __builtin_amdgcn_s_setprio(0); } while (0)
; #define PG8_WAIT_V(n) asm volatile("s_waitcnt vmcnt(" #n ")" ::: "memory")
; #define PG8_WAIT_L(n) asm volatile("s_waitcnt lgkmcnt(" #n ")" ::: "memory")
; #define PG8_BAR __builtin_amdgcn_s_barrier()
; #define PG8_SCHED __builtin_amdgcn_sched_barrier(0)
; template <class Epi, class Sched>
; __device__ __forceinline__ void gemm_phase(LAS unsigned char* lds, const Gemm g, const Sched& S, const Epi& E) {
;     ...
;             PG8_LDB(B1, 1, 1); PG8_STAGE(PG8_SB(1, 0), b3, voffB);
;             PG8_BAR; PG8_WAIT_L(0); PG8_MMA(0, 1, At, B1); PG8_BAR;
;             PG8_LDA(At, 1, 1); PG8_STAGE(PG8_SA(1, 0), a3, voffA);
;             PG8_BAR; PG8_WAIT_L(0); PG8_MMA(1, 0, At, B0); PG8_BAR; PG8_SCHED;
;             PG8_STAGE(PG8_SB(1, 1), b3 + hstep, voffB);
;             PG8_WAIT_V(6); PG8_BAR; PG8_MMA(1, 1, At, B1); PG8_BAR;
	s_add_i32 s38, s38, s56
	v_lshl_add_u64 v[156:157], v[156:157], 0, s[36:37]
	s_mov_b32 m0, s38
	s_nop 0
	global_load_lds_dwordx4 v[156:157], off
	v_lshl_add_u64 v[156:157], v[214:215], 0, s[36:37]
	s_add_i32 m0, s38, 0x2000
	s_nop 0
	global_load_lds_dwordx4 v[156:157], off
	s_mov_b32 m0, s59
	v_lshl_add_u64 v[156:157], v[216:217], 0, s[36:37]
	global_load_lds_dwordx4 v[156:157], off
	v_lshl_add_u64 v[156:157], v[224:225], 0, s[36:37]
	s_mov_b32 m0, s60
	s_nop 0
	global_load_lds_dwordx4 v[156:157], off
	ds_read_b128 v[164:167], v147 offset:49152
	ds_read_b128 v[168:171], v147 offset:50176
	ds_read_b128 v[172:175], v147 offset:51200
	ds_read_b128 v[176:179], v147 offset:52224
	ds_read_b128 v[180:183], v147 offset:53248
	ds_read_b128 v[184:187], v147 offset:54272
	ds_read_b128 v[188:191], v147 offset:55296
	ds_read_b128 v[192:195], v147 offset:56320
	s_waitcnt vmcnt(6)
	s_waitcnt lgkmcnt(0)
	s_barrier
	s_setprio 1
	v_mfma_f32_16x16x32_bf16 v[62:65], v[140:143], v[164:167], v[62:65]
	v_mfma_f32_16x16x32_bf16 v[58:61], v[152:155], v[164:167], v[58:61]
	v_mfma_f32_16x16x32_bf16 v[54:57], v[140:143], v[172:175], v[54:57]
	v_mfma_f32_16x16x32_bf16 v[46:49], v[152:155], v[172:175], v[46:49]
	v_mfma_f32_16x16x32_bf16 v[38:41], v[140:143], v[180:183], v[38:41]
	v_mfma_f32_16x16x32_bf16 v[30:33], v[152:155], v[180:183], v[30:33]
	v_mfma_f32_16x16x32_bf16 v[22:25], v[140:143], v[188:191], v[22:25]
	v_mfma_f32_16x16x32_bf16 v[14:17], v[152:155], v[188:191], v[14:17]
	v_mfma_f32_16x16x32_bf16 v[62:65], v[148:151], v[168:171], v[62:65]
	v_mfma_f32_16x16x32_bf16 v[58:61], v[160:163], v[168:171], v[58:61]
	v_mfma_f32_16x16x32_bf16 v[54:57], v[148:151], v[176:179], v[54:57]
	v_mfma_f32_16x16x32_bf16 v[46:49], v[160:163], v[176:179], v[46:49]
	v_mfma_f32_16x16x32_bf16 v[38:41], v[148:151], v[184:187], v[38:41]
	v_mfma_f32_16x16x32_bf16 v[30:33], v[160:163], v[184:187], v[30:33]
	v_mfma_f32_16x16x32_bf16 v[22:25], v[148:151], v[192:195], v[22:25]
	v_mfma_f32_16x16x32_bf16 v[14:17], v[160:163], v[192:195], v[14:17]
	s_add_u32 s52, s52, 0x80080
	s_addc_u32 s53, s53, 0
	s_add_i32 s38, s39, s56
	v_lshl_add_u64 v[140:141], s[52:53], 0, v[0:1]
	s_mov_b32 m0, s38
	s_nop 0
	global_load_lds_dwordx4 v[140:141], off
	v_lshl_add_u64 v[140:141], s[52:53], 0, v[134:135]
	s_add_i32 m0, s38, 0x2000
	s_nop 0
	global_load_lds_dwordx4 v[140:141], off
	v_mfma_f32_16x16x32_bf16 v[50:53], v[196:199], v[164:167], v[50:53]
	v_mfma_f32_16x16x32_bf16 v[42:45], v[204:207], v[164:167], v[42:45]
	v_mfma_f32_16x16x32_bf16 v[34:37], v[196:199], v[172:175], v[34:37]
	v_mfma_f32_16x16x32_bf16 v[26:29], v[204:207], v[172:175], v[26:29]
	v_mfma_f32_16x16x32_bf16 v[18:21], v[196:199], v[180:183], v[18:21]
	v_mfma_f32_16x16x32_bf16 v[10:13], v[204:207], v[180:183], v[10:13]
	v_mfma_f32_16x16x32_bf16 v[6:9], v[196:199], v[188:191], v[6:9]
	v_mfma_f32_16x16x32_bf16 v[2:5], v[204:207], v[188:191], v[2:5]
	v_mfma_f32_16x16x32_bf16 v[50:53], v[200:203], v[168:171], v[50:53]
	v_mfma_f32_16x16x32_bf16 v[42:45], v[210:213], v[168:171], v[42:45]
	v_mfma_f32_16x16x32_bf16 v[34:37], v[200:203], v[176:179], v[34:37]
	v_mfma_f32_16x16x32_bf16 v[26:29], v[210:213], v[176:179], v[26:29]
	v_mfma_f32_16x16x32_bf16 v[18:21], v[200:203], v[184:187], v[18:21]
	v_mfma_f32_16x16x32_bf16 v[10:13], v[210:213], v[184:187], v[10:13]
	v_mfma_f32_16x16x32_bf16 v[6:9], v[200:203], v[192:195], v[6:9]
	v_mfma_f32_16x16x32_bf16 v[2:5], v[210:213], v[192:195], v[2:5]
	s_setprio 0
	s_add_i32 s70, s70, 2
	s_add_u32 s68, s68, 0x100
	s_addc_u32 s69, s69, 0
	s_add_u32 s50, s50, 0x100
	s_addc_u32 s51, s51, 0
	s_cmp_gt_u32 s70, 29
	s_barrier
	s_cbranch_scc0 .LBB0_354
; __device__ __forceinline__ unsigned cvt_pk_bf16(float lo, float hi) { unsigned r; asm("v_cvt_pk_bf16_f32 %0, %1, %2" : "=v"(r) : "v"(lo), "v"(hi)); return r; }
; #define PG8_WAIT_V(n) asm volatile("s_waitcnt vmcnt(" #n ")" ::: "memory")
; #define PG8_BAR __builtin_amdgcn_s_barrier()
;     __device__ __forceinline__ void operator()(const f32x4 (&acc)[2][2][4][2], const Unit& u, int wr, int wc, int fr, int fq) const {
;         const int row0 = u.pm * BM + wr * 64 + fr, col0 = u.pn * BM + wc * 32 + 8 * fq;
; #pragma unroll
;         for (int ai = 0; ai < 2; ++ai)
; #pragma unroll
;             for (int m = 0; m < 4; ++m) { bf16_t* rowp = O + (size_t)(row0 + ai * HALF + m * 16) * ldc + col0;
; #pragma unroll
;                 for (int bj = 0; bj < 2; ++bj) { f32x4 v0 = acc[ai][bj][m][0], v1 = acc[ai][bj][m][1];
;                     if (ACT == 1) {
; #pragma unroll
;                         for (int j = 0; j < 4; ++j) { float a = fmaxf(v0[j], 0.f), b = fmaxf(v1[j], 0.f); v0[j] = a * a; v1[j] = b * b; } }
;                     u32x4 w; w.x = cvt_pk_bf16(v0[0], v0[1]); w.y = cvt_pk_bf16(v0[2], v0[3]); w.z = cvt_pk_bf16(v1[0], v1[1]); w.w = cvt_pk_bf16(v1[2], v1[3]);
;                     if (ACT == 1) __builtin_nontemporal_store(w, (u32x4*)(rowp + bj * HALF));
;                     else *(u32x4*)(rowp + bj * HALF) = w; } }
; template <class Epi, class Sched>
; __device__ __forceinline__ void gemm_phase(LAS unsigned char* lds, const Gemm g, const Sched& S, const Epi& E) {
;     ...
;         cur = nxt; cA = nA; cB = nB; ++ui;
;     }
;     PG8_WAIT_V(0);
;     if (wr == 0) PG8_BAR;
;     PG8_BAR;
	s_load_dwordx2 s[50:51], s[0:1], 0xc0
	v_lshl_add_u32 v150, s28, 8, v144
	v_lshl_or_b32 v142, s40, 8, v146
	v_ashrrev_i32_e32 v143, 31, v142
	v_cvt_pk_bf16_f32 v70, v70, v71
	s_waitcnt lgkmcnt(0)
	v_mov_b64_e32 v[140:141], s[50:51]
	v_cvt_pk_bf16_f32 v71, v72, v73
	v_cvt_pk_bf16_f32 v72, v66, v67
	v_add_u32_e32 v66, 0x80, v150
	v_mad_i64_i32 v[148:149], s[50:51], v150, s17, v[140:141]
	v_lshlrev_b64 v[142:143], 1, v[142:143]
	v_cvt_pk_bf16_f32 v114, v114, v115
	v_cvt_pk_bf16_f32 v115, v116, v117
	v_cvt_pk_bf16_f32 v116, v106, v107
	v_or_b32_e32 v106, 16, v150
	v_mad_i64_i32 v[66:67], s[50:51], v66, s17, v[140:141]
	v_cvt_pk_bf16_f32 v50, v50, v51
	v_cvt_pk_bf16_f32 v51, v52, v53
	v_cvt_pk_bf16_f32 v52, v42, v43
	v_add_u32_e32 v42, 0x90, v150
	v_lshl_add_u64 v[148:149], v[148:149], 0, v[142:143]
	v_mad_i64_i32 v[106:107], s[50:51], v106, s17, v[140:141]
	v_cvt_pk_bf16_f32 v98, v98, v99
	v_cvt_pk_bf16_f32 v99, v100, v101
	v_cvt_pk_bf16_f32 v100, v90, v91
	v_or_b32_e32 v90, 32, v150
	v_lshl_add_u64 v[66:67], v[66:67], 0, v[142:143]
	v_mad_i64_i32 v[42:43], s[50:51], v42, s17, v[140:141]
	v_cvt_pk_bf16_f32 v34, v34, v35
	v_cvt_pk_bf16_f32 v35, v36, v37
	v_cvt_pk_bf16_f32 v36, v26, v27
	v_add_u32_e32 v26, 0xa0, v150
	v_cvt_pk_bf16_f32 v117, v108, v109
	global_store_dwordx4 v[148:149], v[114:117], off offset:256
	v_mad_i64_i32 v[90:91], s[50:51], v90, s17, v[140:141]
	s_nop 0
	v_lshl_add_u64 v[114:115], v[106:107], 0, v[142:143]
	v_cvt_pk_bf16_f32 v82, v82, v83
	v_cvt_pk_bf16_f32 v83, v84, v85
	v_cvt_pk_bf16_f32 v84, v74, v75
	v_or_b32_e32 v74, 48, v150
	v_cvt_pk_bf16_f32 v53, v44, v45
	global_store_dwordx4 v[66:67], v[50:53], off offset:256
	v_mad_i64_i32 v[26:27], s[50:51], v26, s17, v[140:141]
	s_nop 0
	v_lshl_add_u64 v[50:51], v[42:43], 0, v[142:143]
	v_cvt_pk_bf16_f32 v18, v18, v19
	v_cvt_pk_bf16_f32 v19, v20, v21
	v_cvt_pk_bf16_f32 v20, v10, v11
	v_add_u32_e32 v10, 0xb0, v150
	v_cvt_pk_bf16_f32 v101, v92, v93
	global_store_dwordx4 v[114:115], v[98:101], off offset:256
	v_mad_i64_i32 v[74:75], s[50:51], v74, s17, v[140:141]
	s_nop 0
	v_lshl_add_u64 v[98:99], v[90:91], 0, v[142:143]
	v_cvt_pk_bf16_f32 v37, v28, v29
	global_store_dwordx4 v[50:51], v[34:37], off offset:256
	v_mad_i64_i32 v[10:11], s[50:51], v10, s17, v[140:141]
	s_nop 0
	v_lshl_add_u64 v[34:35], v[26:27], 0, v[142:143]
	v_cvt_pk_bf16_f32 v85, v76, v77
	global_store_dwordx4 v[98:99], v[82:85], off offset:256
	v_cvt_pk_bf16_f32 v21, v12, v13
	global_store_dwordx4 v[34:35], v[18:21], off offset:256
	s_and_b64 vcc, exec, s[46:47]
	v_lshl_add_u64 v[82:83], v[74:75], 0, v[142:143]
	v_lshl_add_u64 v[18:19], v[10:11], 0, v[142:143]
	s_mov_b32 s40, s42
	s_mov_b32 s28, s8
	s_mov_b32 s43, s42
	s_mov_b32 s46, s8
	s_mov_b64 s[50:51], s[48:49]
	s_mov_b64 s[52:53], s[44:45]
	v_cvt_pk_bf16_f32 v126, v126, v127
	v_cvt_pk_bf16_f32 v127, v128, v129
	v_cvt_pk_bf16_f32 v128, v122, v123
	v_cvt_pk_bf16_f32 v129, v124, v125
	global_store_dwordx4 v[148:149], v[126:129], off
	v_cvt_pk_bf16_f32 v106, v118, v119
	v_cvt_pk_bf16_f32 v107, v120, v121
	v_cvt_pk_bf16_f32 v108, v110, v111
	v_cvt_pk_bf16_f32 v109, v112, v113
	global_store_dwordx4 v[114:115], v[106:109], off
	v_cvt_pk_bf16_f32 v90, v102, v103
	v_cvt_pk_bf16_f32 v91, v104, v105
	v_cvt_pk_bf16_f32 v92, v94, v95
	v_cvt_pk_bf16_f32 v93, v96, v97
	global_store_dwordx4 v[98:99], v[90:93], off
	v_cvt_pk_bf16_f32 v74, v86, v87
	v_cvt_pk_bf16_f32 v75, v88, v89
	v_cvt_pk_bf16_f32 v76, v78, v79
	v_cvt_pk_bf16_f32 v77, v80, v81
	global_store_dwordx4 v[82:83], v[74:77], off
	v_cvt_pk_bf16_f32 v73, v68, v69
	global_store_dwordx4 v[82:83], v[70:73], off offset:256
	v_cvt_pk_bf16_f32 v62, v62, v63
	v_cvt_pk_bf16_f32 v63, v64, v65
	v_cvt_pk_bf16_f32 v64, v58, v59
	v_cvt_pk_bf16_f32 v65, v60, v61
	global_store_dwordx4 v[66:67], v[62:65], off
	v_cvt_pk_bf16_f32 v42, v54, v55
	v_cvt_pk_bf16_f32 v43, v56, v57
	v_cvt_pk_bf16_f32 v44, v46, v47
	v_cvt_pk_bf16_f32 v45, v48, v49
	global_store_dwordx4 v[50:51], v[42:45], off
	v_cvt_pk_bf16_f32 v26, v38, v39
	v_cvt_pk_bf16_f32 v27, v40, v41
	v_cvt_pk_bf16_f32 v28, v30, v31
	v_cvt_pk_bf16_f32 v29, v32, v33
	global_store_dwordx4 v[34:35], v[26:29], off
	v_cvt_pk_bf16_f32 v10, v22, v23
	v_cvt_pk_bf16_f32 v11, v24, v25
	v_cvt_pk_bf16_f32 v12, v14, v15
	v_cvt_pk_bf16_f32 v13, v16, v17
	global_store_dwordx4 v[18:19], v[10:13], off
	v_cvt_pk_bf16_f32 v6, v6, v7
	v_cvt_pk_bf16_f32 v7, v8, v9
	v_cvt_pk_bf16_f32 v8, v2, v3
	v_cvt_pk_bf16_f32 v9, v4, v5
	global_store_dwordx4 v[18:19], v[6:9], off offset:256
	s_cbranch_vccz .LBB0_346
	s_waitcnt vmcnt(0)
	s_cmpk_gt_u32 s25, 0xff
	s_cbranch_scc1 .LBB0_358
	s_barrier
